# c5 + redundant post-barrier s_waitcnt lgkmcnt(0) removed from the 7 GEMM main loops (waitcnt placement lever)
# speedup vs baseline: 1.0025x; 1.0025x over previous
; #define PG8_STAGE(bufoff, gbase, voff) do { _Pragma("unroll") for (int _i = 0; _i < 2; ++_i) \
;         __builtin_amdgcn_global_load_lds((const unsigned*)((const char*)(gbase) + (voff)[_i]), (LAS unsigned*)(lds + (bufoff) + ldsw + _i * 8192), 16, 0, 0); } while (0)
; #define PG8_LDA(dst, b, h) do { _Pragma("unroll") for (int m = 0; m < 4; ++m) _Pragma("unroll") for (int k = 0; k < 2; ++k) dst[m][k] = *(const LAS bf16x8*)(lds + PG8_SA(b, h) + aoff + m * 2048 + k * 1024); } while (0)
; #define PG8_LDB(dst, b, h) do { _Pragma("unroll") for (int n = 0; n < 2; ++n) _Pragma("unroll") for (int k = 0; k < 2; ++k) dst[n][k] = *(const LAS bf16x8*)(lds + PG8_SB(b, h) + boff + n * 2048 + k * 1024); } while (0)
; #define PG8_MMA(ai, bj, At, Bt) do { __builtin_amdgcn_s_setprio(1); _Pragma("unroll") for (int m = 0; m < 4; ++m) _Pragma("unroll") for (int n = 0; n < 2; ++n) _Pragma("unroll") for (int k = 0; k < 2; ++k) \
;         acc[ai][bj][m][n] = __builtin_amdgcn_mfma_f32_16x16x32_bf16(Bt[n][k], At[m][k], acc[ai][bj][m][n], 0, 0, 0); __builtin_amdgcn_s_setprio(0); } while (0)
; #define PG8_WAIT_V(n) asm volatile("s_waitcnt vmcnt(" #n ")" ::: "memory")
; #define PG8_WAIT_L(n) asm volatile("s_waitcnt lgkmcnt(" #n ")" ::: "memory")
; #define PG8_BAR __builtin_amdgcn_s_barrier()
; #define PG8_SCHED __builtin_amdgcn_sched_barrier(0)
; template <class Epi, class Sched>
; __device__ __forceinline__ void gemm_phase(LAS unsigned char* lds, const Gemm g, const Sched& S, const Epi& E, const int tid) {
;     ...
;         for (int t = 0; t < nt; t += 2) {
;             const bool last = (t == nt - 2);
;             const char* a1 = cA + (size_t)(t + 1) * kstep;
;             const char* a2 = last ? nA : cA + (size_t)(t + 2) * kstep; const char* b2 = last ? nB : cB + (size_t)(t + 2) * kstep;
;             const char* a3 = a2 + kstep; const char* b3 = b2 + kstep;
;             PG8_LDB(B0, 0, 0); PG8_LDB(B1, 0, 1); PG8_SCHED; PG8_LDA(At, 0, 0); PG8_STAGE(PG8_SA(1, 1), a1 + hstepA, voffA);
;             PG8_WAIT_V(8); PG8_WAIT_L(0); PG8_BAR; PG8_MMA(0, 0, At, B0); PG8_MMA(0, 1, At, B1); PG8_BAR; PG8_SCHED;
;             PG8_LDA(At, 0, 1); PG8_STAGE(PG8_SB(0, 0), b2, voffB); PG8_STAGE(PG8_SB(0, 1), b2 + hstepB, voffB); PG8_STAGE(PG8_SA(0, 0), a2, voffA);
;             PG8_WAIT_V(8); PG8_WAIT_L(0); PG8_BAR; PG8_MMA(1, 0, At, B0); PG8_MMA(1, 1, At, B1); PG8_BAR; PG8_SCHED;
.LBB0_182:
	s_add_u32 s86, s54, 0x100
	s_addc_u32 s87, s55, 0
	s_add_i32 s13, 0, 0x10000
	s_cmpk_eq_i32 s12, 0x5c
	s_cselect_b32 s91, s9, s87
	s_cselect_b32 s90, s8, s86
	s_cselect_b32 s89, s47, s17
	s_cselect_b32 s88, s46, s16
	s_add_i32 s74, 0, 0x14000
	v_add_u32_e32 v150, s13, v204
	v_add_u32_e32 v162, s74, v204
	ds_read_b128 v[138:141], v150
	ds_read_b128 v[142:145], v150 offset:1024
	ds_read_b128 v[146:149], v150 offset:2048
	ds_read_b128 v[150:153], v150 offset:3072
	ds_read_b128 v[154:157], v162
	ds_read_b128 v[158:161], v162 offset:1024
	ds_read_b128 v[174:177], v162 offset:2048
	ds_read_b128 v[178:181], v162 offset:3072
	v_lshl_add_u64 v[162:163], s[54:55], 0, v[134:135]
	s_add_i32 m0, s84, 0xc000
	ds_read_b128 v[182:185], v206
	ds_read_b128 v[186:189], v206 offset:1024
	ds_read_b128 v[190:193], v206 offset:2048
	ds_read_b128 v[194:197], v206 offset:3072
	ds_read_b128 v[198:201], v206 offset:4096
	ds_read_b128 v[210:213], v206 offset:5120
	ds_read_b128 v[220:223], v206 offset:6144
	ds_read_b128 v[234:237], v206 offset:7168
	global_load_lds_dwordx4 v[162:163], off
	v_lshl_add_u64 v[162:163], s[54:55], 0, v[136:137]
	s_add_i32 m0, s84, 0xe000
	s_nop 0
	global_load_lds_dwordx4 v[162:163], off
	s_waitcnt vmcnt(8)
	s_waitcnt lgkmcnt(0)
	s_barrier
	v_mfma_f32_16x16x32_bf16 v[128:131], v[138:141], v[182:185], v[128:131]
	v_mfma_f32_16x16x32_bf16 v[96:99], v[146:149], v[182:185], v[96:99]
	v_mfma_f32_16x16x32_bf16 v[124:127], v[138:141], v[190:193], v[124:127]
	v_mfma_f32_16x16x32_bf16 v[92:95], v[146:149], v[190:193], v[92:95]
	v_mfma_f32_16x16x32_bf16 v[120:123], v[138:141], v[198:201], v[120:123]
	v_mfma_f32_16x16x32_bf16 v[88:91], v[146:149], v[198:201], v[88:91]
	v_mfma_f32_16x16x32_bf16 v[116:119], v[138:141], v[220:223], v[116:119]
	v_mfma_f32_16x16x32_bf16 v[84:87], v[146:149], v[220:223], v[84:87]
	v_mfma_f32_16x16x32_bf16 v[128:131], v[142:145], v[186:189], v[128:131]
	v_mfma_f32_16x16x32_bf16 v[96:99], v[150:153], v[186:189], v[96:99]
	v_mfma_f32_16x16x32_bf16 v[124:127], v[142:145], v[194:197], v[124:127]
	v_mfma_f32_16x16x32_bf16 v[92:95], v[150:153], v[194:197], v[92:95]
	v_mfma_f32_16x16x32_bf16 v[120:123], v[142:145], v[210:213], v[120:123]
	v_mfma_f32_16x16x32_bf16 v[88:91], v[150:153], v[210:213], v[88:91]
	v_mfma_f32_16x16x32_bf16 v[116:119], v[142:145], v[234:237], v[116:119]
	v_mfma_f32_16x16x32_bf16 v[84:87], v[150:153], v[234:237], v[84:87]
	v_mfma_f32_16x16x32_bf16 v[64:67], v[154:157], v[182:185], v[64:67]
	v_mfma_f32_16x16x32_bf16 v[32:35], v[174:177], v[182:185], v[32:35]
	v_mfma_f32_16x16x32_bf16 v[60:63], v[154:157], v[190:193], v[60:63]
	v_mfma_f32_16x16x32_bf16 v[28:31], v[174:177], v[190:193], v[28:31]
	v_mfma_f32_16x16x32_bf16 v[56:59], v[154:157], v[198:201], v[56:59]
	v_mfma_f32_16x16x32_bf16 v[24:27], v[174:177], v[198:201], v[24:27]
	v_mfma_f32_16x16x32_bf16 v[52:55], v[154:157], v[220:223], v[52:55]
	v_mfma_f32_16x16x32_bf16 v[20:23], v[174:177], v[220:223], v[20:23]
	v_mfma_f32_16x16x32_bf16 v[64:67], v[158:161], v[186:189], v[64:67]
	v_mfma_f32_16x16x32_bf16 v[32:35], v[178:181], v[186:189], v[32:35]
	v_mfma_f32_16x16x32_bf16 v[60:63], v[158:161], v[194:197], v[60:63]
	v_mfma_f32_16x16x32_bf16 v[28:31], v[178:181], v[194:197], v[28:31]
	v_mfma_f32_16x16x32_bf16 v[56:59], v[158:161], v[210:213], v[56:59]
	v_mfma_f32_16x16x32_bf16 v[24:27], v[178:181], v[210:213], v[24:27]
	v_mfma_f32_16x16x32_bf16 v[52:55], v[158:161], v[234:237], v[52:55]
	v_mfma_f32_16x16x32_bf16 v[20:23], v[178:181], v[234:237], v[20:23]
	s_barrier
	s_add_i32 s13, s13, s79
	v_lshl_add_u64 v[162:163], s[88:89], 0, v[164:165]
	s_mov_b32 m0, s13
	ds_read_b128 v[182:185], v206 offset:16384
	ds_read_b128 v[186:189], v206 offset:17408
	ds_read_b128 v[190:193], v206 offset:18432
	ds_read_b128 v[194:197], v206 offset:19456
	ds_read_b128 v[198:201], v206 offset:20480
	ds_read_b128 v[210:213], v206 offset:21504
	ds_read_b128 v[220:223], v206 offset:22528
	ds_read_b128 v[234:237], v206 offset:23552
	global_load_lds_dwordx4 v[162:163], off
	s_add_i32 m0, s13, 0x2000
	s_add_u32 s54, s88, 0x180000
	v_lshl_add_u64 v[202:203], s[88:89], 0, v[132:133]
	s_addc_u32 s55, s89, 0
	s_add_i32 s13, s74, s79
	global_load_lds_dwordx4 v[202:203], off
	v_lshl_add_u64 v[224:225], s[54:55], 0, v[164:165]
	s_mov_b32 m0, s13
	v_lshl_add_u64 v[226:227], s[90:91], 0, v[132:133]
	global_load_lds_dwordx4 v[224:225], off
	v_lshl_add_u64 v[224:225], s[54:55], 0, v[132:133]
	s_add_i32 m0, s13, 0x2000
	s_nop 0
	global_load_lds_dwordx4 v[224:225], off
	v_lshl_add_u64 v[224:225], s[90:91], 0, v[164:165]
	s_mov_b32 m0, s84
	s_nop 0
	global_load_lds_dwordx4 v[224:225], off
	s_mov_b32 m0, s85
	s_nop 0
	global_load_lds_dwordx4 v[226:227], off
	s_waitcnt vmcnt(8)
	s_waitcnt lgkmcnt(0)
	s_barrier
; #define PG8_STAGE(bufoff, gbase, voff) do { _Pragma("unroll") for (int _i = 0; _i < 2; ++_i) \
;         __builtin_amdgcn_global_load_lds((const unsigned*)((const char*)(gbase) + (voff)[_i]), (LAS unsigned*)(lds + (bufoff) + ldsw + _i * 8192), 16, 0, 0); } while (0)
; #define PG8_LDA(dst, b, h) do { _Pragma("unroll") for (int m = 0; m < 4; ++m) _Pragma("unroll") for (int k = 0; k < 2; ++k) dst[m][k] = *(const LAS bf16x8*)(lds + PG8_SA(b, h) + aoff + m * 2048 + k * 1024); } while (0)
; #define PG8_LDB(dst, b, h) do { _Pragma("unroll") for (int n = 0; n < 2; ++n) _Pragma("unroll") for (int k = 0; k < 2; ++k) dst[n][k] = *(const LAS bf16x8*)(lds + PG8_SB(b, h) + boff + n * 2048 + k * 1024); } while (0)
; #define PG8_MMA(ai, bj, At, Bt) do { __builtin_amdgcn_s_setprio(1); _Pragma("unroll") for (int m = 0; m < 4; ++m) _Pragma("unroll") for (int n = 0; n < 2; ++n) _Pragma("unroll") for (int k = 0; k < 2; ++k) \
;         acc[ai][bj][m][n] = __builtin_amdgcn_mfma_f32_16x16x32_bf16(Bt[n][k], At[m][k], acc[ai][bj][m][n], 0, 0, 0); __builtin_amdgcn_s_setprio(0); } while (0)
; #define PG8_WAIT_V(n) asm volatile("s_waitcnt vmcnt(" #n ")" ::: "memory")
; #define PG8_WAIT_L(n) asm volatile("s_waitcnt lgkmcnt(" #n ")" ::: "memory")
; #define PG8_BAR __builtin_amdgcn_s_barrier()
; #define PG8_SCHED __builtin_amdgcn_sched_barrier(0)
; template <class Epi, class Sched>
; __device__ __forceinline__ void gemm_phase(LAS unsigned char* lds, const Gemm g, const Sched& S, const Epi& E, const int tid) {
;     ...
;             PG8_WAIT_V(8); PG8_WAIT_L(0); PG8_BAR; PG8_MMA(1, 0, At, B0); PG8_MMA(1, 1, At, B1); PG8_BAR; PG8_SCHED;
;             PG8_LDB(B0, 1, 0); PG8_LDB(B1, 1, 1); PG8_SCHED; PG8_LDA(At, 1, 0); PG8_STAGE(PG8_SA(0, 1), a2 + hstepA, voffA);
;             PG8_WAIT_V(8); PG8_WAIT_L(0); PG8_BAR; PG8_MMA(0, 0, At, B0); PG8_MMA(0, 1, At, B1); PG8_BAR; PG8_SCHED;
	v_mfma_f32_16x16x32_bf16 v[112:115], v[138:141], v[182:185], v[112:115]
	v_mfma_f32_16x16x32_bf16 v[80:83], v[146:149], v[182:185], v[80:83]
	v_mfma_f32_16x16x32_bf16 v[108:111], v[138:141], v[190:193], v[108:111]
	v_mfma_f32_16x16x32_bf16 v[76:79], v[146:149], v[190:193], v[76:79]
	v_mfma_f32_16x16x32_bf16 v[104:107], v[138:141], v[198:201], v[104:107]
	v_mfma_f32_16x16x32_bf16 v[72:75], v[146:149], v[198:201], v[72:75]
	v_mfma_f32_16x16x32_bf16 v[100:103], v[138:141], v[220:223], v[100:103]
	v_mfma_f32_16x16x32_bf16 v[68:71], v[146:149], v[220:223], v[68:71]
	v_mfma_f32_16x16x32_bf16 v[112:115], v[142:145], v[186:189], v[112:115]
	v_mfma_f32_16x16x32_bf16 v[80:83], v[150:153], v[186:189], v[80:83]
	v_mfma_f32_16x16x32_bf16 v[108:111], v[142:145], v[194:197], v[108:111]
	v_mfma_f32_16x16x32_bf16 v[76:79], v[150:153], v[194:197], v[76:79]
	v_mfma_f32_16x16x32_bf16 v[104:107], v[142:145], v[210:213], v[104:107]
	v_mfma_f32_16x16x32_bf16 v[72:75], v[150:153], v[210:213], v[72:75]
	v_mfma_f32_16x16x32_bf16 v[100:103], v[142:145], v[234:237], v[100:103]
	v_mfma_f32_16x16x32_bf16 v[68:71], v[150:153], v[234:237], v[68:71]
	v_mfma_f32_16x16x32_bf16 v[48:51], v[154:157], v[182:185], v[48:51]
	v_mfma_f32_16x16x32_bf16 v[16:19], v[174:177], v[182:185], v[16:19]
	v_mfma_f32_16x16x32_bf16 v[44:47], v[154:157], v[190:193], v[44:47]
	v_mfma_f32_16x16x32_bf16 v[12:15], v[174:177], v[190:193], v[12:15]
	v_mfma_f32_16x16x32_bf16 v[40:43], v[154:157], v[198:201], v[40:43]
	v_mfma_f32_16x16x32_bf16 v[8:11], v[174:177], v[198:201], v[8:11]
	v_mfma_f32_16x16x32_bf16 v[36:39], v[154:157], v[220:223], v[36:39]
	v_mfma_f32_16x16x32_bf16 v[4:7], v[174:177], v[220:223], v[4:7]
	v_mfma_f32_16x16x32_bf16 v[48:51], v[158:161], v[186:189], v[48:51]
	v_mfma_f32_16x16x32_bf16 v[16:19], v[178:181], v[186:189], v[16:19]
	v_mfma_f32_16x16x32_bf16 v[44:47], v[158:161], v[194:197], v[44:47]
	v_mfma_f32_16x16x32_bf16 v[12:15], v[178:181], v[194:197], v[12:15]
	v_mfma_f32_16x16x32_bf16 v[40:43], v[158:161], v[210:213], v[40:43]
	v_mfma_f32_16x16x32_bf16 v[8:11], v[178:181], v[210:213], v[8:11]
	v_mfma_f32_16x16x32_bf16 v[36:39], v[158:161], v[234:237], v[36:39]
	v_mfma_f32_16x16x32_bf16 v[4:7], v[178:181], v[234:237], v[4:7]
	s_barrier
	s_add_i32 s13, 0, 0x18000
	s_add_i32 s74, 0, 0x1c000
	v_add_u32_e32 v150, s13, v204
	v_add_u32_e32 v178, s74, v204
	ds_read_b128 v[138:141], v150
	ds_read_b128 v[142:145], v150 offset:1024
	ds_read_b128 v[146:149], v150 offset:2048
	ds_read_b128 v[150:153], v150 offset:3072
	ds_read_b128 v[154:157], v178
	ds_read_b128 v[158:161], v178 offset:1024
	ds_read_b128 v[174:177], v178 offset:2048
	ds_read_b128 v[178:181], v178 offset:3072
	s_add_u32 s54, s90, 0x180000
	s_addc_u32 s55, s91, 0
	s_mov_b32 m0, s92
	v_lshl_add_u64 v[238:239], s[54:55], 0, v[164:165]
	ds_read_b128 v[182:185], v206 offset:32768
	ds_read_b128 v[186:189], v206 offset:33792
	ds_read_b128 v[190:193], v206 offset:34816
	ds_read_b128 v[194:197], v206 offset:35840
	ds_read_b128 v[198:201], v206 offset:36864
	ds_read_b128 v[210:213], v206 offset:37888
	ds_read_b128 v[220:223], v206 offset:38912
	ds_read_b128 v[234:237], v206 offset:39936
	global_load_lds_dwordx4 v[238:239], off
	v_lshl_add_u64 v[238:239], s[54:55], 0, v[132:133]
	s_mov_b32 m0, s93
	s_nop 0
	global_load_lds_dwordx4 v[238:239], off
	s_waitcnt vmcnt(8)
	s_waitcnt lgkmcnt(0)
	s_barrier
	v_mfma_f32_16x16x32_bf16 v[128:131], v[138:141], v[182:185], v[128:131]
	v_mfma_f32_16x16x32_bf16 v[96:99], v[146:149], v[182:185], v[96:99]
	v_mfma_f32_16x16x32_bf16 v[124:127], v[138:141], v[190:193], v[124:127]
	v_mfma_f32_16x16x32_bf16 v[92:95], v[146:149], v[190:193], v[92:95]
	v_mfma_f32_16x16x32_bf16 v[120:123], v[138:141], v[198:201], v[120:123]
	v_mfma_f32_16x16x32_bf16 v[88:91], v[146:149], v[198:201], v[88:91]
	v_mfma_f32_16x16x32_bf16 v[116:119], v[138:141], v[220:223], v[116:119]
	v_mfma_f32_16x16x32_bf16 v[84:87], v[146:149], v[220:223], v[84:87]
	v_mfma_f32_16x16x32_bf16 v[128:131], v[142:145], v[186:189], v[128:131]
	v_mfma_f32_16x16x32_bf16 v[96:99], v[150:153], v[186:189], v[96:99]
	v_mfma_f32_16x16x32_bf16 v[124:127], v[142:145], v[194:197], v[124:127]
	v_mfma_f32_16x16x32_bf16 v[92:95], v[150:153], v[194:197], v[92:95]
	v_mfma_f32_16x16x32_bf16 v[120:123], v[142:145], v[210:213], v[120:123]
	v_mfma_f32_16x16x32_bf16 v[88:91], v[150:153], v[210:213], v[88:91]
	v_mfma_f32_16x16x32_bf16 v[116:119], v[142:145], v[234:237], v[116:119]
	v_mfma_f32_16x16x32_bf16 v[84:87], v[150:153], v[234:237], v[84:87]
	v_mfma_f32_16x16x32_bf16 v[64:67], v[154:157], v[182:185], v[64:67]
	v_mfma_f32_16x16x32_bf16 v[32:35], v[174:177], v[182:185], v[32:35]
	v_mfma_f32_16x16x32_bf16 v[60:63], v[154:157], v[190:193], v[60:63]
	v_mfma_f32_16x16x32_bf16 v[28:31], v[174:177], v[190:193], v[28:31]
	v_mfma_f32_16x16x32_bf16 v[56:59], v[154:157], v[198:201], v[56:59]
	v_mfma_f32_16x16x32_bf16 v[24:27], v[174:177], v[198:201], v[24:27]
	v_mfma_f32_16x16x32_bf16 v[52:55], v[154:157], v[220:223], v[52:55]
	v_mfma_f32_16x16x32_bf16 v[20:23], v[174:177], v[220:223], v[20:23]
	v_mfma_f32_16x16x32_bf16 v[64:67], v[158:161], v[186:189], v[64:67]
	v_mfma_f32_16x16x32_bf16 v[32:35], v[178:181], v[186:189], v[32:35]
	v_mfma_f32_16x16x32_bf16 v[60:63], v[158:161], v[194:197], v[60:63]
	v_mfma_f32_16x16x32_bf16 v[28:31], v[178:181], v[194:197], v[28:31]
	v_mfma_f32_16x16x32_bf16 v[56:59], v[158:161], v[210:213], v[56:59]
	v_mfma_f32_16x16x32_bf16 v[24:27], v[178:181], v[210:213], v[24:27]
	v_mfma_f32_16x16x32_bf16 v[52:55], v[158:161], v[234:237], v[52:55]
	v_mfma_f32_16x16x32_bf16 v[20:23], v[178:181], v[234:237], v[20:23]
	s_barrier
; #define PG8_STAGE(bufoff, gbase, voff) do { _Pragma("unroll") for (int _i = 0; _i < 2; ++_i) \
;         __builtin_amdgcn_global_load_lds((const unsigned*)((const char*)(gbase) + (voff)[_i]), (LAS unsigned*)(lds + (bufoff) + ldsw + _i * 8192), 16, 0, 0); } while (0)
; #define PG8_LDA(dst, b, h) do { _Pragma("unroll") for (int m = 0; m < 4; ++m) _Pragma("unroll") for (int k = 0; k < 2; ++k) dst[m][k] = *(const LAS bf16x8*)(lds + PG8_SA(b, h) + aoff + m * 2048 + k * 1024); } while (0)
; #define PG8_MMA(ai, bj, At, Bt) do { __builtin_amdgcn_s_setprio(1); _Pragma("unroll") for (int m = 0; m < 4; ++m) _Pragma("unroll") for (int n = 0; n < 2; ++n) _Pragma("unroll") for (int k = 0; k < 2; ++k) \
;         acc[ai][bj][m][n] = __builtin_amdgcn_mfma_f32_16x16x32_bf16(Bt[n][k], At[m][k], acc[ai][bj][m][n], 0, 0, 0); __builtin_amdgcn_s_setprio(0); } while (0)
; #define PG8_WAIT_V(n) asm volatile("s_waitcnt vmcnt(" #n ")" ::: "memory")
; #define PG8_WAIT_L(n) asm volatile("s_waitcnt lgkmcnt(" #n ")" ::: "memory")
; #define PG8_BAR __builtin_amdgcn_s_barrier()
; #define PG8_SCHED __builtin_amdgcn_sched_barrier(0)
; template <class Epi, class Sched>
; __device__ __forceinline__ void gemm_phase(LAS unsigned char* lds, const Gemm g, const Sched& S, const Epi& E, const int tid) {
;     ...
;             PG8_LDA(At, 1, 1); PG8_STAGE(PG8_SB(1, 0), b3, voffB); PG8_STAGE(PG8_SB(1, 1), b3 + hstepB, voffB); PG8_STAGE(PG8_SA(1, 0), a3, voffA);
;             PG8_WAIT_V(8); PG8_WAIT_L(0); PG8_BAR; PG8_MMA(1, 0, At, B0); PG8_MMA(1, 1, At, B1); PG8_BAR; PG8_SCHED;
;         }
;         if (wr == 0) PG8_BAR;
	s_add_i32 s13, s13, s79
	v_lshl_add_u64 v[162:163], v[162:163], 0, s[28:29]
	s_mov_b32 m0, s13
	ds_read_b128 v[182:185], v206 offset:49152
	ds_read_b128 v[186:189], v206 offset:50176
	ds_read_b128 v[190:193], v206 offset:51200
	ds_read_b128 v[194:197], v206 offset:52224
	ds_read_b128 v[198:201], v206 offset:53248
	ds_read_b128 v[210:213], v206 offset:54272
	ds_read_b128 v[220:223], v206 offset:55296
	ds_read_b128 v[234:237], v206 offset:56320
	global_load_lds_dwordx4 v[162:163], off
	s_add_i32 m0, s13, 0x2000
	s_add_u32 s54, s88, 0x180080
	v_lshl_add_u64 v[162:163], v[202:203], 0, s[28:29]
	s_addc_u32 s55, s89, 0
	s_add_i32 s13, s74, s79
	global_load_lds_dwordx4 v[162:163], off
	v_lshl_add_u64 v[162:163], s[54:55], 0, v[164:165]
	s_mov_b32 m0, s13
	s_nop 0
	global_load_lds_dwordx4 v[162:163], off
	v_lshl_add_u64 v[162:163], s[54:55], 0, v[132:133]
	s_add_i32 m0, s13, 0x2000
	s_nop 0
	global_load_lds_dwordx4 v[162:163], off
	v_lshl_add_u64 v[162:163], v[224:225], 0, s[28:29]
	s_mov_b32 m0, s94
	s_nop 0
	global_load_lds_dwordx4 v[162:163], off
	v_lshl_add_u64 v[162:163], v[226:227], 0, s[28:29]
	s_mov_b32 m0, s95
	s_nop 0
	global_load_lds_dwordx4 v[162:163], off
	s_waitcnt vmcnt(8)
	s_waitcnt lgkmcnt(0)
	s_barrier
	v_mfma_f32_16x16x32_bf16 v[112:115], v[138:141], v[182:185], v[112:115]
	v_mfma_f32_16x16x32_bf16 v[80:83], v[146:149], v[182:185], v[80:83]
	v_mfma_f32_16x16x32_bf16 v[108:111], v[138:141], v[190:193], v[108:111]
	v_mfma_f32_16x16x32_bf16 v[76:79], v[146:149], v[190:193], v[76:79]
	v_mfma_f32_16x16x32_bf16 v[104:107], v[138:141], v[198:201], v[104:107]
	v_mfma_f32_16x16x32_bf16 v[72:75], v[146:149], v[198:201], v[72:75]
	v_mfma_f32_16x16x32_bf16 v[100:103], v[138:141], v[220:223], v[100:103]
	v_mfma_f32_16x16x32_bf16 v[68:71], v[146:149], v[220:223], v[68:71]
	v_mfma_f32_16x16x32_bf16 v[112:115], v[142:145], v[186:189], v[112:115]
	v_mfma_f32_16x16x32_bf16 v[80:83], v[150:153], v[186:189], v[80:83]
	v_mfma_f32_16x16x32_bf16 v[108:111], v[142:145], v[194:197], v[108:111]
	v_mfma_f32_16x16x32_bf16 v[76:79], v[150:153], v[194:197], v[76:79]
	v_mfma_f32_16x16x32_bf16 v[104:107], v[142:145], v[210:213], v[104:107]
	v_mfma_f32_16x16x32_bf16 v[72:75], v[150:153], v[210:213], v[72:75]
	v_mfma_f32_16x16x32_bf16 v[100:103], v[142:145], v[234:237], v[100:103]
	v_mfma_f32_16x16x32_bf16 v[68:71], v[150:153], v[234:237], v[68:71]
	v_mfma_f32_16x16x32_bf16 v[48:51], v[154:157], v[182:185], v[48:51]
	v_mfma_f32_16x16x32_bf16 v[16:19], v[174:177], v[182:185], v[16:19]
	v_mfma_f32_16x16x32_bf16 v[44:47], v[154:157], v[190:193], v[44:47]
	v_mfma_f32_16x16x32_bf16 v[12:15], v[174:177], v[190:193], v[12:15]
	v_mfma_f32_16x16x32_bf16 v[40:43], v[154:157], v[198:201], v[40:43]
	v_mfma_f32_16x16x32_bf16 v[8:11], v[174:177], v[198:201], v[8:11]
	v_mfma_f32_16x16x32_bf16 v[36:39], v[154:157], v[220:223], v[36:39]
	v_mfma_f32_16x16x32_bf16 v[4:7], v[174:177], v[220:223], v[4:7]
	v_mfma_f32_16x16x32_bf16 v[48:51], v[158:161], v[186:189], v[48:51]
	v_mfma_f32_16x16x32_bf16 v[16:19], v[178:181], v[186:189], v[16:19]
	v_mfma_f32_16x16x32_bf16 v[44:47], v[158:161], v[194:197], v[44:47]
	v_mfma_f32_16x16x32_bf16 v[12:15], v[178:181], v[194:197], v[12:15]
	v_mfma_f32_16x16x32_bf16 v[40:43], v[158:161], v[210:213], v[40:43]
	v_mfma_f32_16x16x32_bf16 v[8:11], v[178:181], v[210:213], v[8:11]
	v_mfma_f32_16x16x32_bf16 v[36:39], v[158:161], v[234:237], v[36:39]
	v_mfma_f32_16x16x32_bf16 v[4:7], v[178:181], v[234:237], v[4:7]
	s_barrier
	s_add_i32 s12, s12, 2
	s_add_u32 s16, s16, 0x100
	s_addc_u32 s17, s17, 0
	s_cmpk_gt_u32 s12, 0x5d
	s_mov_b64 s[54:55], s[86:87]
	s_cbranch_scc0 .LBB0_182
	s_and_b64 vcc, exec, s[44:45]
	s_cbranch_vccz .LBB0_185
	s_barrier

; #define PG8_STAGE(bufoff, gbase, voff) do { _Pragma("unroll") for (int _i = 0; _i < 2; ++_i) \
;         __builtin_amdgcn_global_load_lds((const unsigned*)((const char*)(gbase) + (voff)[_i]), (LAS unsigned*)(lds + (bufoff) + ldsw + _i * 8192), 16, 0, 0); } while (0)
; #define PG8_LDA(dst, b, h) do { _Pragma("unroll") for (int m = 0; m < 4; ++m) _Pragma("unroll") for (int k = 0; k < 2; ++k) dst[m][k] = *(const LAS bf16x8*)(lds + PG8_SA(b, h) + aoff + m * 2048 + k * 1024); } while (0)
; #define PG8_LDB(dst, b, h) do { _Pragma("unroll") for (int n = 0; n < 2; ++n) _Pragma("unroll") for (int k = 0; k < 2; ++k) dst[n][k] = *(const LAS bf16x8*)(lds + PG8_SB(b, h) + boff + n * 2048 + k * 1024); } while (0)
; #define PG8_MMA(ai, bj, At, Bt) do { __builtin_amdgcn_s_setprio(1); _Pragma("unroll") for (int m = 0; m < 4; ++m) _Pragma("unroll") for (int n = 0; n < 2; ++n) _Pragma("unroll") for (int k = 0; k < 2; ++k) \
;         acc[ai][bj][m][n] = __builtin_amdgcn_mfma_f32_16x16x32_bf16(Bt[n][k], At[m][k], acc[ai][bj][m][n], 0, 0, 0); __builtin_amdgcn_s_setprio(0); } while (0)
; #define PG8_WAIT_V(n) asm volatile("s_waitcnt vmcnt(" #n ")" ::: "memory")
; #define PG8_WAIT_L(n) asm volatile("s_waitcnt lgkmcnt(" #n ")" ::: "memory")
; #define PG8_BAR __builtin_amdgcn_s_barrier()
; #define PG8_SCHED __builtin_amdgcn_sched_barrier(0)
; template <class Epi, class Sched>
; __device__ __forceinline__ void gemm_phase(LAS unsigned char* lds, const Gemm g, const Sched& S, const Epi& E, const int tid) {
;     ...
;         for (int t = 0; t < nt; t += 2) {
;             const bool last = (t == nt - 2);
;             const char* a1 = cA + (size_t)(t + 1) * kstep;
;             const char* a2 = last ? nA : cA + (size_t)(t + 2) * kstep; const char* b2 = last ? nB : cB + (size_t)(t + 2) * kstep;
;             const char* a3 = a2 + kstep; const char* b3 = b2 + kstep;
;             PG8_LDB(B0, 0, 0); PG8_LDB(B1, 0, 1); PG8_SCHED; PG8_LDA(At, 0, 0); PG8_STAGE(PG8_SA(1, 1), a1 + hstepA, voffA);
;             PG8_WAIT_V(8); PG8_WAIT_L(0); PG8_BAR; PG8_MMA(0, 0, At, B0); PG8_MMA(0, 1, At, B1); PG8_BAR; PG8_SCHED;
;             PG8_LDA(At, 0, 1); PG8_STAGE(PG8_SB(0, 0), b2, voffB); PG8_STAGE(PG8_SB(0, 1), b2 + hstepB, voffB); PG8_STAGE(PG8_SA(0, 0), a2, voffA);
;             PG8_WAIT_V(8); PG8_WAIT_L(0); PG8_BAR; PG8_MMA(1, 0, At, B0); PG8_MMA(1, 1, At, B1); PG8_BAR; PG8_SCHED;
.LBB0_208:
	s_add_u32 s12, s54, 0xfff80080
	s_addc_u32 s13, s55, -1
	s_add_i32 s74, 0, 0x10000
	s_cmp_eq_u32 s95, 28
	s_cselect_b32 s89, s16, s13
	s_cselect_b32 s88, s17, s12
	s_cselect_b32 s87, s39, s94
	s_cselect_b32 s86, s43, s93
	s_add_i32 s96, 0, 0x14000
	v_add_u32_e32 v158, s74, v143
	v_add_u32_e32 v162, s96, v143
	ds_read_b128 v[146:149], v158
	ds_read_b128 v[150:153], v158 offset:1024
	ds_read_b128 v[154:157], v158 offset:2048
	ds_read_b128 v[158:161], v158 offset:3072
	ds_read_b128 v[174:177], v162
	ds_read_b128 v[178:181], v162 offset:1024
	ds_read_b128 v[182:185], v162 offset:2048
	ds_read_b128 v[186:189], v162 offset:3072
	v_lshl_add_u64 v[162:163], s[54:55], 0, v[138:139]
	s_add_i32 m0, s11, 0xc000
	ds_read_b128 v[190:193], v145
	ds_read_b128 v[194:197], v145 offset:1024
	ds_read_b128 v[198:201], v145 offset:2048
	ds_read_b128 v[202:205], v145 offset:3072
	ds_read_b128 v[210:213], v145 offset:4096
	ds_read_b128 v[220:223], v145 offset:5120
	ds_read_b128 v[234:237], v145 offset:6144
	ds_read_b128 v[238:241], v145 offset:7168
	global_load_lds_dwordx4 v[162:163], off
	v_lshl_add_u64 v[162:163], s[54:55], 0, v[140:141]
	s_add_i32 m0, s11, 0xe000
	s_nop 0
	global_load_lds_dwordx4 v[162:163], off
	s_waitcnt vmcnt(8)
	s_waitcnt lgkmcnt(0)
	s_barrier
	v_mfma_f32_16x16x32_bf16 v[128:131], v[146:149], v[190:193], v[128:131]
	v_mfma_f32_16x16x32_bf16 v[124:127], v[154:157], v[190:193], v[124:127]
	v_mfma_f32_16x16x32_bf16 v[120:123], v[146:149], v[198:201], v[120:123]
	v_mfma_f32_16x16x32_bf16 v[116:119], v[154:157], v[198:201], v[116:119]
	v_mfma_f32_16x16x32_bf16 v[104:107], v[146:149], v[210:213], v[104:107]
	v_mfma_f32_16x16x32_bf16 v[100:103], v[154:157], v[210:213], v[100:103]
	v_mfma_f32_16x16x32_bf16 v[88:91], v[146:149], v[234:237], v[88:91]
	v_mfma_f32_16x16x32_bf16 v[84:87], v[154:157], v[234:237], v[84:87]
	v_mfma_f32_16x16x32_bf16 v[128:131], v[150:153], v[194:197], v[128:131]
	v_mfma_f32_16x16x32_bf16 v[124:127], v[158:161], v[194:197], v[124:127]
	v_mfma_f32_16x16x32_bf16 v[120:123], v[150:153], v[202:205], v[120:123]
	v_mfma_f32_16x16x32_bf16 v[116:119], v[158:161], v[202:205], v[116:119]
	v_mfma_f32_16x16x32_bf16 v[104:107], v[150:153], v[220:223], v[104:107]
	v_mfma_f32_16x16x32_bf16 v[100:103], v[158:161], v[220:223], v[100:103]
	v_mfma_f32_16x16x32_bf16 v[88:91], v[150:153], v[238:241], v[88:91]
	v_mfma_f32_16x16x32_bf16 v[84:87], v[158:161], v[238:241], v[84:87]
	v_mfma_f32_16x16x32_bf16 v[112:115], v[174:177], v[190:193], v[112:115]
	v_mfma_f32_16x16x32_bf16 v[108:111], v[182:185], v[190:193], v[108:111]
	v_mfma_f32_16x16x32_bf16 v[96:99], v[174:177], v[198:201], v[96:99]
	v_mfma_f32_16x16x32_bf16 v[92:95], v[182:185], v[198:201], v[92:95]
	v_mfma_f32_16x16x32_bf16 v[80:83], v[174:177], v[210:213], v[80:83]
	v_mfma_f32_16x16x32_bf16 v[76:79], v[182:185], v[210:213], v[76:79]
	v_mfma_f32_16x16x32_bf16 v[72:75], v[174:177], v[234:237], v[72:75]
	v_mfma_f32_16x16x32_bf16 v[68:71], v[182:185], v[234:237], v[68:71]
	v_mfma_f32_16x16x32_bf16 v[112:115], v[178:181], v[194:197], v[112:115]
	v_mfma_f32_16x16x32_bf16 v[108:111], v[186:189], v[194:197], v[108:111]
	v_mfma_f32_16x16x32_bf16 v[96:99], v[178:181], v[202:205], v[96:99]
	v_mfma_f32_16x16x32_bf16 v[92:95], v[186:189], v[202:205], v[92:95]
	v_mfma_f32_16x16x32_bf16 v[80:83], v[178:181], v[220:223], v[80:83]
	v_mfma_f32_16x16x32_bf16 v[76:79], v[186:189], v[220:223], v[76:79]
	v_mfma_f32_16x16x32_bf16 v[72:75], v[178:181], v[238:241], v[72:75]
	v_mfma_f32_16x16x32_bf16 v[68:71], v[186:189], v[238:241], v[68:71]
	s_barrier
	s_add_i32 s12, s74, s57
	v_lshl_add_u64 v[162:163], s[86:87], 0, v[164:165]
	s_mov_b32 m0, s12
	ds_read_b128 v[190:193], v145 offset:16384
	ds_read_b128 v[194:197], v145 offset:17408
	ds_read_b128 v[198:201], v145 offset:18432
	ds_read_b128 v[202:205], v145 offset:19456
	ds_read_b128 v[210:213], v145 offset:20480
	ds_read_b128 v[220:223], v145 offset:21504
	ds_read_b128 v[234:237], v145 offset:22528
	ds_read_b128 v[238:241], v145 offset:23552
	global_load_lds_dwordx4 v[162:163], off
	s_add_i32 m0, s12, 0x2000
	s_add_u32 s12, s86, 0x80000
	v_lshl_add_u64 v[206:207], s[86:87], 0, v[132:133]
	s_addc_u32 s13, s87, 0
	s_add_i32 s74, s96, s57
	global_load_lds_dwordx4 v[206:207], off
	v_lshl_add_u64 v[224:225], s[12:13], 0, v[164:165]
	s_mov_b32 m0, s74
	v_lshl_add_u64 v[226:227], s[88:89], 0, v[134:135]
	global_load_lds_dwordx4 v[224:225], off
	v_lshl_add_u64 v[224:225], s[12:13], 0, v[132:133]
	s_add_i32 m0, s74, 0x2000
	s_nop 0
	global_load_lds_dwordx4 v[224:225], off
	v_lshl_add_u64 v[224:225], s[88:89], 0, v[136:137]
	s_mov_b32 m0, s11
	s_nop 0
	global_load_lds_dwordx4 v[224:225], off
	s_mov_b32 m0, s59
	s_nop 0
	global_load_lds_dwordx4 v[226:227], off
	s_waitcnt vmcnt(8)
	s_waitcnt lgkmcnt(0)
	s_barrier
; #define PG8_STAGE(bufoff, gbase, voff) do { _Pragma("unroll") for (int _i = 0; _i < 2; ++_i) \
;         __builtin_amdgcn_global_load_lds((const unsigned*)((const char*)(gbase) + (voff)[_i]), (LAS unsigned*)(lds + (bufoff) + ldsw + _i * 8192), 16, 0, 0); } while (0)
; #define PG8_LDA(dst, b, h) do { _Pragma("unroll") for (int m = 0; m < 4; ++m) _Pragma("unroll") for (int k = 0; k < 2; ++k) dst[m][k] = *(const LAS bf16x8*)(lds + PG8_SA(b, h) + aoff + m * 2048 + k * 1024); } while (0)
; #define PG8_LDB(dst, b, h) do { _Pragma("unroll") for (int n = 0; n < 2; ++n) _Pragma("unroll") for (int k = 0; k < 2; ++k) dst[n][k] = *(const LAS bf16x8*)(lds + PG8_SB(b, h) + boff + n * 2048 + k * 1024); } while (0)
; #define PG8_MMA(ai, bj, At, Bt) do { __builtin_amdgcn_s_setprio(1); _Pragma("unroll") for (int m = 0; m < 4; ++m) _Pragma("unroll") for (int n = 0; n < 2; ++n) _Pragma("unroll") for (int k = 0; k < 2; ++k) \
;         acc[ai][bj][m][n] = __builtin_amdgcn_mfma_f32_16x16x32_bf16(Bt[n][k], At[m][k], acc[ai][bj][m][n], 0, 0, 0); __builtin_amdgcn_s_setprio(0); } while (0)
; #define PG8_WAIT_V(n) asm volatile("s_waitcnt vmcnt(" #n ")" ::: "memory")
; #define PG8_WAIT_L(n) asm volatile("s_waitcnt lgkmcnt(" #n ")" ::: "memory")
; #define PG8_BAR __builtin_amdgcn_s_barrier()
; #define PG8_SCHED __builtin_amdgcn_sched_barrier(0)
; template <class Epi, class Sched>
; __device__ __forceinline__ void gemm_phase(LAS unsigned char* lds, const Gemm g, const Sched& S, const Epi& E, const int tid) {
;     ...
;             PG8_WAIT_V(8); PG8_WAIT_L(0); PG8_BAR; PG8_MMA(0, 0, At, B0); PG8_MMA(0, 1, At, B1); PG8_BAR; PG8_SCHED;
;             PG8_LDA(At, 0, 1); PG8_STAGE(PG8_SB(0, 0), b2, voffB); PG8_STAGE(PG8_SB(0, 1), b2 + hstepB, voffB); PG8_STAGE(PG8_SA(0, 0), a2, voffA);
;             PG8_WAIT_V(8); PG8_WAIT_L(0); PG8_BAR; PG8_MMA(1, 0, At, B0); PG8_MMA(1, 1, At, B1); PG8_BAR; PG8_SCHED;
;             PG8_LDB(B0, 1, 0); PG8_LDB(B1, 1, 1); PG8_SCHED; PG8_LDA(At, 1, 0); PG8_STAGE(PG8_SA(0, 1), a2 + hstepA, voffA);
;             PG8_WAIT_V(8); PG8_WAIT_L(0); PG8_BAR; PG8_MMA(0, 0, At, B0); PG8_MMA(0, 1, At, B1); PG8_BAR; PG8_SCHED;
	v_mfma_f32_16x16x32_bf16 v[64:67], v[146:149], v[190:193], v[64:67]
	v_mfma_f32_16x16x32_bf16 v[60:63], v[154:157], v[190:193], v[60:63]
	v_mfma_f32_16x16x32_bf16 v[56:59], v[146:149], v[198:201], v[56:59]
	v_mfma_f32_16x16x32_bf16 v[52:55], v[154:157], v[198:201], v[52:55]
	v_mfma_f32_16x16x32_bf16 v[40:43], v[146:149], v[210:213], v[40:43]
	v_mfma_f32_16x16x32_bf16 v[36:39], v[154:157], v[210:213], v[36:39]
	v_mfma_f32_16x16x32_bf16 v[24:27], v[146:149], v[234:237], v[24:27]
	v_mfma_f32_16x16x32_bf16 v[20:23], v[154:157], v[234:237], v[20:23]
	v_mfma_f32_16x16x32_bf16 v[64:67], v[150:153], v[194:197], v[64:67]
	v_mfma_f32_16x16x32_bf16 v[60:63], v[158:161], v[194:197], v[60:63]
	v_mfma_f32_16x16x32_bf16 v[56:59], v[150:153], v[202:205], v[56:59]
	v_mfma_f32_16x16x32_bf16 v[52:55], v[158:161], v[202:205], v[52:55]
	v_mfma_f32_16x16x32_bf16 v[40:43], v[150:153], v[220:223], v[40:43]
	v_mfma_f32_16x16x32_bf16 v[36:39], v[158:161], v[220:223], v[36:39]
	v_mfma_f32_16x16x32_bf16 v[24:27], v[150:153], v[238:241], v[24:27]
	v_mfma_f32_16x16x32_bf16 v[20:23], v[158:161], v[238:241], v[20:23]
	v_mfma_f32_16x16x32_bf16 v[48:51], v[174:177], v[190:193], v[48:51]
	v_mfma_f32_16x16x32_bf16 v[44:47], v[182:185], v[190:193], v[44:47]
	v_mfma_f32_16x16x32_bf16 v[32:35], v[174:177], v[198:201], v[32:35]
	v_mfma_f32_16x16x32_bf16 v[28:31], v[182:185], v[198:201], v[28:31]
	v_mfma_f32_16x16x32_bf16 v[16:19], v[174:177], v[210:213], v[16:19]
	v_mfma_f32_16x16x32_bf16 v[12:15], v[182:185], v[210:213], v[12:15]
	v_mfma_f32_16x16x32_bf16 v[8:11], v[174:177], v[234:237], v[8:11]
	v_mfma_f32_16x16x32_bf16 v[4:7], v[182:185], v[234:237], v[4:7]
	v_mfma_f32_16x16x32_bf16 v[48:51], v[178:181], v[194:197], v[48:51]
	v_mfma_f32_16x16x32_bf16 v[44:47], v[186:189], v[194:197], v[44:47]
	v_mfma_f32_16x16x32_bf16 v[32:35], v[178:181], v[202:205], v[32:35]
	v_mfma_f32_16x16x32_bf16 v[28:31], v[186:189], v[202:205], v[28:31]
	v_mfma_f32_16x16x32_bf16 v[16:19], v[178:181], v[220:223], v[16:19]
	v_mfma_f32_16x16x32_bf16 v[12:15], v[186:189], v[220:223], v[12:15]
	v_mfma_f32_16x16x32_bf16 v[8:11], v[178:181], v[238:241], v[8:11]
	v_mfma_f32_16x16x32_bf16 v[4:7], v[186:189], v[238:241], v[4:7]
	s_barrier
	s_add_i32 s74, 0, 0x18000
	s_add_i32 s96, 0, 0x1c000
	v_add_u32_e32 v158, s74, v143
	v_add_u32_e32 v171, s96, v143
	ds_read_b128 v[146:149], v158
	ds_read_b128 v[150:153], v158 offset:1024
	ds_read_b128 v[154:157], v158 offset:2048
	ds_read_b128 v[158:161], v158 offset:3072
	ds_read_b128 v[174:177], v171
	ds_read_b128 v[178:181], v171 offset:1024
	ds_read_b128 v[182:185], v171 offset:2048
	ds_read_b128 v[186:189], v171 offset:3072
	s_add_u32 s12, s88, 0x80000
	s_addc_u32 s13, s89, 0
	s_mov_b32 m0, s79
	v_lshl_add_u64 v[242:243], s[12:13], 0, v[136:137]
	ds_read_b128 v[190:193], v145 offset:32768
	ds_read_b128 v[194:197], v145 offset:33792
	ds_read_b128 v[198:201], v145 offset:34816
	ds_read_b128 v[202:205], v145 offset:35840
	ds_read_b128 v[210:213], v145 offset:36864
	ds_read_b128 v[220:223], v145 offset:37888
	ds_read_b128 v[234:237], v145 offset:38912
	ds_read_b128 v[238:241], v145 offset:39936
	global_load_lds_dwordx4 v[242:243], off
	v_lshl_add_u64 v[242:243], s[12:13], 0, v[134:135]
	s_mov_b32 m0, s84
	s_nop 0
	global_load_lds_dwordx4 v[242:243], off
	s_waitcnt vmcnt(8)
	s_waitcnt lgkmcnt(0)
	s_barrier
	v_mfma_f32_16x16x32_bf16 v[128:131], v[146:149], v[190:193], v[128:131]
	v_mfma_f32_16x16x32_bf16 v[124:127], v[154:157], v[190:193], v[124:127]
	v_mfma_f32_16x16x32_bf16 v[120:123], v[146:149], v[198:201], v[120:123]
	v_mfma_f32_16x16x32_bf16 v[116:119], v[154:157], v[198:201], v[116:119]
	v_mfma_f32_16x16x32_bf16 v[104:107], v[146:149], v[210:213], v[104:107]
	v_mfma_f32_16x16x32_bf16 v[100:103], v[154:157], v[210:213], v[100:103]
	v_mfma_f32_16x16x32_bf16 v[88:91], v[146:149], v[234:237], v[88:91]
	v_mfma_f32_16x16x32_bf16 v[84:87], v[154:157], v[234:237], v[84:87]
	v_mfma_f32_16x16x32_bf16 v[128:131], v[150:153], v[194:197], v[128:131]
	v_mfma_f32_16x16x32_bf16 v[124:127], v[158:161], v[194:197], v[124:127]
	v_mfma_f32_16x16x32_bf16 v[120:123], v[150:153], v[202:205], v[120:123]
	v_mfma_f32_16x16x32_bf16 v[116:119], v[158:161], v[202:205], v[116:119]
	v_mfma_f32_16x16x32_bf16 v[104:107], v[150:153], v[220:223], v[104:107]
	v_mfma_f32_16x16x32_bf16 v[100:103], v[158:161], v[220:223], v[100:103]
	v_mfma_f32_16x16x32_bf16 v[88:91], v[150:153], v[238:241], v[88:91]
	v_mfma_f32_16x16x32_bf16 v[84:87], v[158:161], v[238:241], v[84:87]
	v_mfma_f32_16x16x32_bf16 v[112:115], v[174:177], v[190:193], v[112:115]
	v_mfma_f32_16x16x32_bf16 v[108:111], v[182:185], v[190:193], v[108:111]
	v_mfma_f32_16x16x32_bf16 v[96:99], v[174:177], v[198:201], v[96:99]
	v_mfma_f32_16x16x32_bf16 v[92:95], v[182:185], v[198:201], v[92:95]
	v_mfma_f32_16x16x32_bf16 v[80:83], v[174:177], v[210:213], v[80:83]
	v_mfma_f32_16x16x32_bf16 v[76:79], v[182:185], v[210:213], v[76:79]
	v_mfma_f32_16x16x32_bf16 v[72:75], v[174:177], v[234:237], v[72:75]
	v_mfma_f32_16x16x32_bf16 v[68:71], v[182:185], v[234:237], v[68:71]
	v_mfma_f32_16x16x32_bf16 v[112:115], v[178:181], v[194:197], v[112:115]
	v_mfma_f32_16x16x32_bf16 v[108:111], v[186:189], v[194:197], v[108:111]
	v_mfma_f32_16x16x32_bf16 v[96:99], v[178:181], v[202:205], v[96:99]
	v_mfma_f32_16x16x32_bf16 v[92:95], v[186:189], v[202:205], v[92:95]
	v_mfma_f32_16x16x32_bf16 v[80:83], v[178:181], v[220:223], v[80:83]
	v_mfma_f32_16x16x32_bf16 v[76:79], v[186:189], v[220:223], v[76:79]
	v_mfma_f32_16x16x32_bf16 v[72:75], v[178:181], v[238:241], v[72:75]
	v_mfma_f32_16x16x32_bf16 v[68:71], v[186:189], v[238:241], v[68:71]
	s_barrier
; #define PG8_STAGE(bufoff, gbase, voff) do { _Pragma("unroll") for (int _i = 0; _i < 2; ++_i) \
;         __builtin_amdgcn_global_load_lds((const unsigned*)((const char*)(gbase) + (voff)[_i]), (LAS unsigned*)(lds + (bufoff) + ldsw + _i * 8192), 16, 0, 0); } while (0)
; #define PG8_LDA(dst, b, h) do { _Pragma("unroll") for (int m = 0; m < 4; ++m) _Pragma("unroll") for (int k = 0; k < 2; ++k) dst[m][k] = *(const LAS bf16x8*)(lds + PG8_SA(b, h) + aoff + m * 2048 + k * 1024); } while (0)
; #define PG8_MMA(ai, bj, At, Bt) do { __builtin_amdgcn_s_setprio(1); _Pragma("unroll") for (int m = 0; m < 4; ++m) _Pragma("unroll") for (int n = 0; n < 2; ++n) _Pragma("unroll") for (int k = 0; k < 2; ++k) \
;         acc[ai][bj][m][n] = __builtin_amdgcn_mfma_f32_16x16x32_bf16(Bt[n][k], At[m][k], acc[ai][bj][m][n], 0, 0, 0); __builtin_amdgcn_s_setprio(0); } while (0)
; #define PG8_WAIT_V(n) asm volatile("s_waitcnt vmcnt(" #n ")" ::: "memory")
; #define PG8_WAIT_L(n) asm volatile("s_waitcnt lgkmcnt(" #n ")" ::: "memory")
; #define PG8_BAR __builtin_amdgcn_s_barrier()
; #define PG8_SCHED __builtin_amdgcn_sched_barrier(0)
; template <class Epi, class Sched>
; __device__ __forceinline__ void gemm_phase(LAS unsigned char* lds, const Gemm g, const Sched& S, const Epi& E, const int tid) {
;     ...
;             PG8_LDA(At, 1, 1); PG8_STAGE(PG8_SB(1, 0), b3, voffB); PG8_STAGE(PG8_SB(1, 1), b3 + hstepB, voffB); PG8_STAGE(PG8_SA(1, 0), a3, voffA);
;             PG8_WAIT_V(8); PG8_WAIT_L(0); PG8_BAR; PG8_MMA(1, 0, At, B0); PG8_MMA(1, 1, At, B1); PG8_BAR; PG8_SCHED;
;         }
;         if (wr == 0) PG8_BAR;
	s_add_i32 s12, s74, s57
	v_lshl_add_u64 v[162:163], v[162:163], 0, s[28:29]
	s_mov_b32 m0, s12
	ds_read_b128 v[190:193], v145 offset:49152
	ds_read_b128 v[194:197], v145 offset:50176
	ds_read_b128 v[198:201], v145 offset:51200
	ds_read_b128 v[202:205], v145 offset:52224
	ds_read_b128 v[210:213], v145 offset:53248
	ds_read_b128 v[220:223], v145 offset:54272
	ds_read_b128 v[234:237], v145 offset:55296
	ds_read_b128 v[238:241], v145 offset:56320
	global_load_lds_dwordx4 v[162:163], off
	s_add_i32 m0, s12, 0x2000
	s_add_u32 s12, s86, 0x80080
	v_lshl_add_u64 v[162:163], v[206:207], 0, s[28:29]
	s_addc_u32 s13, s87, 0
	s_add_i32 s74, s96, s57
	global_load_lds_dwordx4 v[162:163], off
	v_lshl_add_u64 v[162:163], s[12:13], 0, v[164:165]
	s_mov_b32 m0, s74
	s_nop 0
	global_load_lds_dwordx4 v[162:163], off
	v_lshl_add_u64 v[162:163], s[12:13], 0, v[132:133]
	s_add_i32 m0, s74, 0x2000
	s_nop 0
	global_load_lds_dwordx4 v[162:163], off
	v_lshl_add_u64 v[162:163], v[224:225], 0, s[28:29]
	s_mov_b32 m0, s85
	s_nop 0
	global_load_lds_dwordx4 v[162:163], off
	v_lshl_add_u64 v[162:163], v[226:227], 0, s[28:29]
	s_mov_b32 m0, s90
	s_nop 0
	global_load_lds_dwordx4 v[162:163], off
	s_waitcnt vmcnt(8)
	s_waitcnt lgkmcnt(0)
	s_barrier
	v_mfma_f32_16x16x32_bf16 v[64:67], v[146:149], v[190:193], v[64:67]
	v_mfma_f32_16x16x32_bf16 v[60:63], v[154:157], v[190:193], v[60:63]
	v_mfma_f32_16x16x32_bf16 v[56:59], v[146:149], v[198:201], v[56:59]
	v_mfma_f32_16x16x32_bf16 v[52:55], v[154:157], v[198:201], v[52:55]
	v_mfma_f32_16x16x32_bf16 v[40:43], v[146:149], v[210:213], v[40:43]
	v_mfma_f32_16x16x32_bf16 v[36:39], v[154:157], v[210:213], v[36:39]
	v_mfma_f32_16x16x32_bf16 v[24:27], v[146:149], v[234:237], v[24:27]
	v_mfma_f32_16x16x32_bf16 v[20:23], v[154:157], v[234:237], v[20:23]
	v_mfma_f32_16x16x32_bf16 v[64:67], v[150:153], v[194:197], v[64:67]
	v_mfma_f32_16x16x32_bf16 v[60:63], v[158:161], v[194:197], v[60:63]
	v_mfma_f32_16x16x32_bf16 v[56:59], v[150:153], v[202:205], v[56:59]
	v_mfma_f32_16x16x32_bf16 v[52:55], v[158:161], v[202:205], v[52:55]
	v_mfma_f32_16x16x32_bf16 v[40:43], v[150:153], v[220:223], v[40:43]
	v_mfma_f32_16x16x32_bf16 v[36:39], v[158:161], v[220:223], v[36:39]
	v_mfma_f32_16x16x32_bf16 v[24:27], v[150:153], v[238:241], v[24:27]
	v_mfma_f32_16x16x32_bf16 v[20:23], v[158:161], v[238:241], v[20:23]
	v_mfma_f32_16x16x32_bf16 v[48:51], v[174:177], v[190:193], v[48:51]
	v_mfma_f32_16x16x32_bf16 v[44:47], v[182:185], v[190:193], v[44:47]
	v_mfma_f32_16x16x32_bf16 v[32:35], v[174:177], v[198:201], v[32:35]
	v_mfma_f32_16x16x32_bf16 v[28:31], v[182:185], v[198:201], v[28:31]
	v_mfma_f32_16x16x32_bf16 v[16:19], v[174:177], v[210:213], v[16:19]
	v_mfma_f32_16x16x32_bf16 v[12:15], v[182:185], v[210:213], v[12:15]
	v_mfma_f32_16x16x32_bf16 v[8:11], v[174:177], v[234:237], v[8:11]
	v_mfma_f32_16x16x32_bf16 v[4:7], v[182:185], v[234:237], v[4:7]
	v_mfma_f32_16x16x32_bf16 v[48:51], v[178:181], v[194:197], v[48:51]
	v_mfma_f32_16x16x32_bf16 v[44:47], v[186:189], v[194:197], v[44:47]
	v_mfma_f32_16x16x32_bf16 v[32:35], v[178:181], v[202:205], v[32:35]
	v_mfma_f32_16x16x32_bf16 v[28:31], v[186:189], v[202:205], v[28:31]
	v_mfma_f32_16x16x32_bf16 v[16:19], v[178:181], v[220:223], v[16:19]
	v_mfma_f32_16x16x32_bf16 v[12:15], v[186:189], v[220:223], v[12:15]
	v_mfma_f32_16x16x32_bf16 v[8:11], v[178:181], v[238:241], v[8:11]
	v_mfma_f32_16x16x32_bf16 v[4:7], v[186:189], v[238:241], v[4:7]
	s_barrier
	s_add_i32 s95, s95, 2
	s_add_u32 s54, s54, 0x100
	s_addc_u32 s55, s55, 0
	s_add_u32 s93, s93, 0x100
	s_addc_u32 s94, s94, 0
	s_cmp_gt_u32 s95, 29
	s_cbranch_scc0 .LBB0_208
	s_and_b64 vcc, exec, s[30:31]
	s_cbranch_vccz .LBB0_211
	s_barrier

; #define PG8_STAGE(bufoff, gbase, voff) do { _Pragma("unroll") for (int _i = 0; _i < 2; ++_i) \
;         __builtin_amdgcn_global_load_lds((const unsigned*)((const char*)(gbase) + (voff)[_i]), (LAS unsigned*)(lds + (bufoff) + ldsw + _i * 8192), 16, 0, 0); } while (0)
; #define PG8_LDA(dst, b, h) do { _Pragma("unroll") for (int m = 0; m < 4; ++m) _Pragma("unroll") for (int k = 0; k < 2; ++k) dst[m][k] = *(const LAS bf16x8*)(lds + PG8_SA(b, h) + aoff + m * 2048 + k * 1024); } while (0)
; #define PG8_LDB(dst, b, h) do { _Pragma("unroll") for (int n = 0; n < 2; ++n) _Pragma("unroll") for (int k = 0; k < 2; ++k) dst[n][k] = *(const LAS bf16x8*)(lds + PG8_SB(b, h) + boff + n * 2048 + k * 1024); } while (0)
; #define PG8_MMA(ai, bj, At, Bt) do { __builtin_amdgcn_s_setprio(1); _Pragma("unroll") for (int m = 0; m < 4; ++m) _Pragma("unroll") for (int n = 0; n < 2; ++n) _Pragma("unroll") for (int k = 0; k < 2; ++k) \
;         acc[ai][bj][m][n] = __builtin_amdgcn_mfma_f32_16x16x32_bf16(Bt[n][k], At[m][k], acc[ai][bj][m][n], 0, 0, 0); __builtin_amdgcn_s_setprio(0); } while (0)
; #define PG8_WAIT_V(n) asm volatile("s_waitcnt vmcnt(" #n ")" ::: "memory")
; #define PG8_WAIT_L(n) asm volatile("s_waitcnt lgkmcnt(" #n ")" ::: "memory")
; #define PG8_BAR __builtin_amdgcn_s_barrier()
; #define PG8_SCHED __builtin_amdgcn_sched_barrier(0)
; template <class Epi, class Sched>
; __device__ __forceinline__ void gemm_phase(LAS unsigned char* lds, const Gemm g, const Sched& S, const Epi& E, const int tid) {
;     ...
;         for (int t = 0; t < nt; t += 2) {
;             const bool last = (t == nt - 2);
;             const char* a1 = cA + (size_t)(t + 1) * kstep;
;             const char* a2 = last ? nA : cA + (size_t)(t + 2) * kstep; const char* b2 = last ? nB : cB + (size_t)(t + 2) * kstep;
;             const char* a3 = a2 + kstep; const char* b3 = b2 + kstep;
;             PG8_LDB(B0, 0, 0); PG8_LDB(B1, 0, 1); PG8_SCHED; PG8_LDA(At, 0, 0); PG8_STAGE(PG8_SA(1, 1), a1 + hstepA, voffA);
;             PG8_WAIT_V(8); PG8_WAIT_L(0); PG8_BAR; PG8_MMA(0, 0, At, B0); PG8_MMA(0, 1, At, B1); PG8_BAR; PG8_SCHED;
;             PG8_LDA(At, 0, 1); PG8_STAGE(PG8_SB(0, 0), b2, voffB); PG8_STAGE(PG8_SB(0, 1), b2 + hstepB, voffB); PG8_STAGE(PG8_SA(0, 0), a2, voffA);
;             PG8_WAIT_V(8); PG8_WAIT_L(0); PG8_BAR; PG8_MMA(1, 0, At, B0); PG8_MMA(1, 1, At, B1); PG8_BAR; PG8_SCHED;
.LBB0_251:
	s_add_u32 s8, s86, 0x100
	s_addc_u32 s9, s87, 0
	s_add_i32 s13, 0, 0x10000
	s_cmp_eq_u32 s12, 28
	s_cselect_b32 s91, s47, s9
	s_cselect_b32 s90, s46, s8
	s_cselect_b32 s89, s17, vcc_hi
	s_cselect_b32 s88, s45, vcc_lo
	s_add_i32 s74, 0, 0x14000
	v_add_u32_e32 v154, s13, v233
	v_add_u32_e32 v162, s74, v233
	ds_read_b128 v[142:145], v154
	ds_read_b128 v[146:149], v154 offset:1024
	ds_read_b128 v[150:153], v154 offset:2048
	ds_read_b128 v[154:157], v154 offset:3072
	ds_read_b128 v[158:161], v162
	ds_read_b128 v[174:177], v162 offset:1024
	ds_read_b128 v[178:181], v162 offset:2048
	ds_read_b128 v[182:185], v162 offset:3072
	v_lshl_add_u64 v[162:163], s[86:87], 0, v[138:139]
	s_add_i32 m0, s79, 0xc000
	ds_read_b128 v[186:189], v235
	ds_read_b128 v[190:193], v235 offset:1024
	ds_read_b128 v[194:197], v235 offset:2048
	ds_read_b128 v[198:201], v235 offset:3072
	ds_read_b128 v[202:205], v235 offset:4096
	ds_read_b128 v[210:213], v235 offset:5120
	ds_read_b128 v[220:223], v235 offset:6144
	ds_read_b128 v[236:239], v235 offset:7168
	global_load_lds_dwordx4 v[162:163], off
	v_lshl_add_u64 v[162:163], s[86:87], 0, v[140:141]
	s_add_i32 m0, s79, 0xe000
	s_nop 0
	global_load_lds_dwordx4 v[162:163], off
	s_waitcnt vmcnt(8)
	s_waitcnt lgkmcnt(0)
	s_barrier
	v_mfma_f32_16x16x32_bf16 v[128:131], v[142:145], v[186:189], v[128:131]
	v_mfma_f32_16x16x32_bf16 v[96:99], v[150:153], v[186:189], v[96:99]
	v_mfma_f32_16x16x32_bf16 v[124:127], v[142:145], v[194:197], v[124:127]
	v_mfma_f32_16x16x32_bf16 v[92:95], v[150:153], v[194:197], v[92:95]
	v_mfma_f32_16x16x32_bf16 v[120:123], v[142:145], v[202:205], v[120:123]
	v_mfma_f32_16x16x32_bf16 v[88:91], v[150:153], v[202:205], v[88:91]
	v_mfma_f32_16x16x32_bf16 v[116:119], v[142:145], v[220:223], v[116:119]
	v_mfma_f32_16x16x32_bf16 v[84:87], v[150:153], v[220:223], v[84:87]
	v_mfma_f32_16x16x32_bf16 v[128:131], v[146:149], v[190:193], v[128:131]
	v_mfma_f32_16x16x32_bf16 v[96:99], v[154:157], v[190:193], v[96:99]
	v_mfma_f32_16x16x32_bf16 v[124:127], v[146:149], v[198:201], v[124:127]
	v_mfma_f32_16x16x32_bf16 v[92:95], v[154:157], v[198:201], v[92:95]
	v_mfma_f32_16x16x32_bf16 v[120:123], v[146:149], v[210:213], v[120:123]
	v_mfma_f32_16x16x32_bf16 v[88:91], v[154:157], v[210:213], v[88:91]
	v_mfma_f32_16x16x32_bf16 v[116:119], v[146:149], v[236:239], v[116:119]
	v_mfma_f32_16x16x32_bf16 v[84:87], v[154:157], v[236:239], v[84:87]
	v_mfma_f32_16x16x32_bf16 v[64:67], v[158:161], v[186:189], v[64:67]
	v_mfma_f32_16x16x32_bf16 v[32:35], v[178:181], v[186:189], v[32:35]
	v_mfma_f32_16x16x32_bf16 v[60:63], v[158:161], v[194:197], v[60:63]
	v_mfma_f32_16x16x32_bf16 v[28:31], v[178:181], v[194:197], v[28:31]
	v_mfma_f32_16x16x32_bf16 v[56:59], v[158:161], v[202:205], v[56:59]
	v_mfma_f32_16x16x32_bf16 v[24:27], v[178:181], v[202:205], v[24:27]
	v_mfma_f32_16x16x32_bf16 v[52:55], v[158:161], v[220:223], v[52:55]
	v_mfma_f32_16x16x32_bf16 v[20:23], v[178:181], v[220:223], v[20:23]
	v_mfma_f32_16x16x32_bf16 v[64:67], v[174:177], v[190:193], v[64:67]
	v_mfma_f32_16x16x32_bf16 v[32:35], v[182:185], v[190:193], v[32:35]
	v_mfma_f32_16x16x32_bf16 v[60:63], v[174:177], v[198:201], v[60:63]
	v_mfma_f32_16x16x32_bf16 v[28:31], v[182:185], v[198:201], v[28:31]
	v_mfma_f32_16x16x32_bf16 v[56:59], v[174:177], v[210:213], v[56:59]
	v_mfma_f32_16x16x32_bf16 v[24:27], v[182:185], v[210:213], v[24:27]
	v_mfma_f32_16x16x32_bf16 v[52:55], v[174:177], v[236:239], v[52:55]
	v_mfma_f32_16x16x32_bf16 v[20:23], v[182:185], v[236:239], v[20:23]
	s_barrier
	s_add_i32 s13, s13, s59
	v_lshl_add_u64 v[162:163], s[88:89], 0, v[164:165]
	s_mov_b32 m0, s13
	ds_read_b128 v[186:189], v235 offset:16384
	ds_read_b128 v[190:193], v235 offset:17408
	ds_read_b128 v[194:197], v235 offset:18432
	ds_read_b128 v[198:201], v235 offset:19456
	ds_read_b128 v[202:205], v235 offset:20480
	ds_read_b128 v[210:213], v235 offset:21504
	ds_read_b128 v[220:223], v235 offset:22528
	ds_read_b128 v[236:239], v235 offset:23552
	global_load_lds_dwordx4 v[162:163], off
	s_add_i32 m0, s13, 0x2000
	s_add_u32 s86, s88, 0x80000
	v_lshl_add_u64 v[206:207], s[88:89], 0, v[136:137]
	s_addc_u32 s87, s89, 0
	s_add_i32 s13, s74, s59
	global_load_lds_dwordx4 v[206:207], off
	v_lshl_add_u64 v[224:225], s[86:87], 0, v[164:165]
	s_mov_b32 m0, s13
	v_lshl_add_u64 v[226:227], s[90:91], 0, v[134:135]
	global_load_lds_dwordx4 v[224:225], off
	v_lshl_add_u64 v[224:225], s[86:87], 0, v[136:137]
	s_add_i32 m0, s13, 0x2000
	s_nop 0
	global_load_lds_dwordx4 v[224:225], off
	v_lshl_add_u64 v[224:225], s[90:91], 0, v[132:133]
	s_mov_b32 m0, s79
	s_nop 0
	global_load_lds_dwordx4 v[224:225], off
	s_mov_b32 m0, s84
	s_nop 0
	global_load_lds_dwordx4 v[226:227], off
	s_waitcnt vmcnt(8)
	s_waitcnt lgkmcnt(0)
	s_barrier
; #define PG8_STAGE(bufoff, gbase, voff) do { _Pragma("unroll") for (int _i = 0; _i < 2; ++_i) \
;         __builtin_amdgcn_global_load_lds((const unsigned*)((const char*)(gbase) + (voff)[_i]), (LAS unsigned*)(lds + (bufoff) + ldsw + _i * 8192), 16, 0, 0); } while (0)
; #define PG8_LDA(dst, b, h) do { _Pragma("unroll") for (int m = 0; m < 4; ++m) _Pragma("unroll") for (int k = 0; k < 2; ++k) dst[m][k] = *(const LAS bf16x8*)(lds + PG8_SA(b, h) + aoff + m * 2048 + k * 1024); } while (0)
; #define PG8_LDB(dst, b, h) do { _Pragma("unroll") for (int n = 0; n < 2; ++n) _Pragma("unroll") for (int k = 0; k < 2; ++k) dst[n][k] = *(const LAS bf16x8*)(lds + PG8_SB(b, h) + boff + n * 2048 + k * 1024); } while (0)
; #define PG8_MMA(ai, bj, At, Bt) do { __builtin_amdgcn_s_setprio(1); _Pragma("unroll") for (int m = 0; m < 4; ++m) _Pragma("unroll") for (int n = 0; n < 2; ++n) _Pragma("unroll") for (int k = 0; k < 2; ++k) \
;         acc[ai][bj][m][n] = __builtin_amdgcn_mfma_f32_16x16x32_bf16(Bt[n][k], At[m][k], acc[ai][bj][m][n], 0, 0, 0); __builtin_amdgcn_s_setprio(0); } while (0)
; #define PG8_WAIT_V(n) asm volatile("s_waitcnt vmcnt(" #n ")" ::: "memory")
; #define PG8_WAIT_L(n) asm volatile("s_waitcnt lgkmcnt(" #n ")" ::: "memory")
; #define PG8_BAR __builtin_amdgcn_s_barrier()
; #define PG8_SCHED __builtin_amdgcn_sched_barrier(0)
; template <class Epi, class Sched>
; __device__ __forceinline__ void gemm_phase(LAS unsigned char* lds, const Gemm g, const Sched& S, const Epi& E, const int tid) {
;     ...
;             PG8_WAIT_V(8); PG8_WAIT_L(0); PG8_BAR; PG8_MMA(0, 0, At, B0); PG8_MMA(0, 1, At, B1); PG8_BAR; PG8_SCHED;
;             PG8_LDA(At, 0, 1); PG8_STAGE(PG8_SB(0, 0), b2, voffB); PG8_STAGE(PG8_SB(0, 1), b2 + hstepB, voffB); PG8_STAGE(PG8_SA(0, 0), a2, voffA);
;             PG8_WAIT_V(8); PG8_WAIT_L(0); PG8_BAR; PG8_MMA(1, 0, At, B0); PG8_MMA(1, 1, At, B1); PG8_BAR; PG8_SCHED;
;             PG8_LDB(B0, 1, 0); PG8_LDB(B1, 1, 1); PG8_SCHED; PG8_LDA(At, 1, 0); PG8_STAGE(PG8_SA(0, 1), a2 + hstepA, voffA);
;             PG8_WAIT_V(8); PG8_WAIT_L(0); PG8_BAR; PG8_MMA(0, 0, At, B0); PG8_MMA(0, 1, At, B1); PG8_BAR; PG8_SCHED;
	v_mfma_f32_16x16x32_bf16 v[112:115], v[142:145], v[186:189], v[112:115]
	v_mfma_f32_16x16x32_bf16 v[80:83], v[150:153], v[186:189], v[80:83]
	v_mfma_f32_16x16x32_bf16 v[108:111], v[142:145], v[194:197], v[108:111]
	v_mfma_f32_16x16x32_bf16 v[76:79], v[150:153], v[194:197], v[76:79]
	v_mfma_f32_16x16x32_bf16 v[104:107], v[142:145], v[202:205], v[104:107]
	v_mfma_f32_16x16x32_bf16 v[72:75], v[150:153], v[202:205], v[72:75]
	v_mfma_f32_16x16x32_bf16 v[100:103], v[142:145], v[220:223], v[100:103]
	v_mfma_f32_16x16x32_bf16 v[68:71], v[150:153], v[220:223], v[68:71]
	v_mfma_f32_16x16x32_bf16 v[112:115], v[146:149], v[190:193], v[112:115]
	v_mfma_f32_16x16x32_bf16 v[80:83], v[154:157], v[190:193], v[80:83]
	v_mfma_f32_16x16x32_bf16 v[108:111], v[146:149], v[198:201], v[108:111]
	v_mfma_f32_16x16x32_bf16 v[76:79], v[154:157], v[198:201], v[76:79]
	v_mfma_f32_16x16x32_bf16 v[104:107], v[146:149], v[210:213], v[104:107]
	v_mfma_f32_16x16x32_bf16 v[72:75], v[154:157], v[210:213], v[72:75]
	v_mfma_f32_16x16x32_bf16 v[100:103], v[146:149], v[236:239], v[100:103]
	v_mfma_f32_16x16x32_bf16 v[68:71], v[154:157], v[236:239], v[68:71]
	v_mfma_f32_16x16x32_bf16 v[48:51], v[158:161], v[186:189], v[48:51]
	v_mfma_f32_16x16x32_bf16 v[16:19], v[178:181], v[186:189], v[16:19]
	v_mfma_f32_16x16x32_bf16 v[44:47], v[158:161], v[194:197], v[44:47]
	v_mfma_f32_16x16x32_bf16 v[12:15], v[178:181], v[194:197], v[12:15]
	v_mfma_f32_16x16x32_bf16 v[40:43], v[158:161], v[202:205], v[40:43]
	v_mfma_f32_16x16x32_bf16 v[8:11], v[178:181], v[202:205], v[8:11]
	v_mfma_f32_16x16x32_bf16 v[36:39], v[158:161], v[220:223], v[36:39]
	v_mfma_f32_16x16x32_bf16 v[4:7], v[178:181], v[220:223], v[4:7]
	v_mfma_f32_16x16x32_bf16 v[48:51], v[174:177], v[190:193], v[48:51]
	v_mfma_f32_16x16x32_bf16 v[16:19], v[182:185], v[190:193], v[16:19]
	v_mfma_f32_16x16x32_bf16 v[44:47], v[174:177], v[198:201], v[44:47]
	v_mfma_f32_16x16x32_bf16 v[12:15], v[182:185], v[198:201], v[12:15]
	v_mfma_f32_16x16x32_bf16 v[40:43], v[174:177], v[210:213], v[40:43]
	v_mfma_f32_16x16x32_bf16 v[8:11], v[182:185], v[210:213], v[8:11]
	v_mfma_f32_16x16x32_bf16 v[36:39], v[174:177], v[236:239], v[36:39]
	v_mfma_f32_16x16x32_bf16 v[4:7], v[182:185], v[236:239], v[4:7]
	s_barrier
	s_add_i32 s13, 0, 0x18000
	s_add_i32 s74, 0, 0x1c000
	v_add_u32_e32 v154, s13, v233
	v_add_u32_e32 v182, s74, v233
	ds_read_b128 v[142:145], v154
	ds_read_b128 v[146:149], v154 offset:1024
	ds_read_b128 v[150:153], v154 offset:2048
	ds_read_b128 v[154:157], v154 offset:3072
	ds_read_b128 v[158:161], v182
	ds_read_b128 v[174:177], v182 offset:1024
	ds_read_b128 v[178:181], v182 offset:2048
	ds_read_b128 v[182:185], v182 offset:3072
	s_add_u32 s86, s90, 0x242000
	s_addc_u32 s87, s91, 0
	s_mov_b32 m0, s85
	v_lshl_add_u64 v[240:241], s[86:87], 0, v[132:133]
	ds_read_b128 v[186:189], v235 offset:32768
	ds_read_b128 v[190:193], v235 offset:33792
	ds_read_b128 v[194:197], v235 offset:34816
	ds_read_b128 v[198:201], v235 offset:35840
	ds_read_b128 v[202:205], v235 offset:36864
	ds_read_b128 v[210:213], v235 offset:37888
	ds_read_b128 v[220:223], v235 offset:38912
	ds_read_b128 v[236:239], v235 offset:39936
	global_load_lds_dwordx4 v[240:241], off
	v_lshl_add_u64 v[240:241], s[86:87], 0, v[134:135]
	s_mov_b32 m0, s92
	s_nop 0
	global_load_lds_dwordx4 v[240:241], off
	s_waitcnt vmcnt(8)
	s_waitcnt lgkmcnt(0)
	s_barrier
	v_mfma_f32_16x16x32_bf16 v[128:131], v[142:145], v[186:189], v[128:131]
	v_mfma_f32_16x16x32_bf16 v[96:99], v[150:153], v[186:189], v[96:99]
	v_mfma_f32_16x16x32_bf16 v[124:127], v[142:145], v[194:197], v[124:127]
	v_mfma_f32_16x16x32_bf16 v[92:95], v[150:153], v[194:197], v[92:95]
	v_mfma_f32_16x16x32_bf16 v[120:123], v[142:145], v[202:205], v[120:123]
	v_mfma_f32_16x16x32_bf16 v[88:91], v[150:153], v[202:205], v[88:91]
	v_mfma_f32_16x16x32_bf16 v[116:119], v[142:145], v[220:223], v[116:119]
	v_mfma_f32_16x16x32_bf16 v[84:87], v[150:153], v[220:223], v[84:87]
	v_mfma_f32_16x16x32_bf16 v[128:131], v[146:149], v[190:193], v[128:131]
	v_mfma_f32_16x16x32_bf16 v[96:99], v[154:157], v[190:193], v[96:99]
	v_mfma_f32_16x16x32_bf16 v[124:127], v[146:149], v[198:201], v[124:127]
	v_mfma_f32_16x16x32_bf16 v[92:95], v[154:157], v[198:201], v[92:95]
	v_mfma_f32_16x16x32_bf16 v[120:123], v[146:149], v[210:213], v[120:123]
	v_mfma_f32_16x16x32_bf16 v[88:91], v[154:157], v[210:213], v[88:91]
	v_mfma_f32_16x16x32_bf16 v[116:119], v[146:149], v[236:239], v[116:119]
	v_mfma_f32_16x16x32_bf16 v[84:87], v[154:157], v[236:239], v[84:87]
	v_mfma_f32_16x16x32_bf16 v[64:67], v[158:161], v[186:189], v[64:67]
	v_mfma_f32_16x16x32_bf16 v[32:35], v[178:181], v[186:189], v[32:35]
	v_mfma_f32_16x16x32_bf16 v[60:63], v[158:161], v[194:197], v[60:63]
	v_mfma_f32_16x16x32_bf16 v[28:31], v[178:181], v[194:197], v[28:31]
	v_mfma_f32_16x16x32_bf16 v[56:59], v[158:161], v[202:205], v[56:59]
	v_mfma_f32_16x16x32_bf16 v[24:27], v[178:181], v[202:205], v[24:27]
	v_mfma_f32_16x16x32_bf16 v[52:55], v[158:161], v[220:223], v[52:55]
	v_mfma_f32_16x16x32_bf16 v[20:23], v[178:181], v[220:223], v[20:23]
	v_mfma_f32_16x16x32_bf16 v[64:67], v[174:177], v[190:193], v[64:67]
	v_mfma_f32_16x16x32_bf16 v[32:35], v[182:185], v[190:193], v[32:35]
	v_mfma_f32_16x16x32_bf16 v[60:63], v[174:177], v[198:201], v[60:63]
	v_mfma_f32_16x16x32_bf16 v[28:31], v[182:185], v[198:201], v[28:31]
	v_mfma_f32_16x16x32_bf16 v[56:59], v[174:177], v[210:213], v[56:59]
	v_mfma_f32_16x16x32_bf16 v[24:27], v[182:185], v[210:213], v[24:27]
	v_mfma_f32_16x16x32_bf16 v[52:55], v[174:177], v[236:239], v[52:55]
	v_mfma_f32_16x16x32_bf16 v[20:23], v[182:185], v[236:239], v[20:23]
	s_barrier
; #define PG8_STAGE(bufoff, gbase, voff) do { _Pragma("unroll") for (int _i = 0; _i < 2; ++_i) \
;         __builtin_amdgcn_global_load_lds((const unsigned*)((const char*)(gbase) + (voff)[_i]), (LAS unsigned*)(lds + (bufoff) + ldsw + _i * 8192), 16, 0, 0); } while (0)
; #define PG8_LDA(dst, b, h) do { _Pragma("unroll") for (int m = 0; m < 4; ++m) _Pragma("unroll") for (int k = 0; k < 2; ++k) dst[m][k] = *(const LAS bf16x8*)(lds + PG8_SA(b, h) + aoff + m * 2048 + k * 1024); } while (0)
; #define PG8_MMA(ai, bj, At, Bt) do { __builtin_amdgcn_s_setprio(1); _Pragma("unroll") for (int m = 0; m < 4; ++m) _Pragma("unroll") for (int n = 0; n < 2; ++n) _Pragma("unroll") for (int k = 0; k < 2; ++k) \
;         acc[ai][bj][m][n] = __builtin_amdgcn_mfma_f32_16x16x32_bf16(Bt[n][k], At[m][k], acc[ai][bj][m][n], 0, 0, 0); __builtin_amdgcn_s_setprio(0); } while (0)
; #define PG8_WAIT_V(n) asm volatile("s_waitcnt vmcnt(" #n ")" ::: "memory")
; #define PG8_WAIT_L(n) asm volatile("s_waitcnt lgkmcnt(" #n ")" ::: "memory")
; #define PG8_BAR __builtin_amdgcn_s_barrier()
; #define PG8_SCHED __builtin_amdgcn_sched_barrier(0)
; template <class Epi, class Sched>
; __device__ __forceinline__ void gemm_phase(LAS unsigned char* lds, const Gemm g, const Sched& S, const Epi& E, const int tid) {
;     ...
;             PG8_LDA(At, 1, 1); PG8_STAGE(PG8_SB(1, 0), b3, voffB); PG8_STAGE(PG8_SB(1, 1), b3 + hstepB, voffB); PG8_STAGE(PG8_SA(1, 0), a3, voffA);
;             PG8_WAIT_V(8); PG8_WAIT_L(0); PG8_BAR; PG8_MMA(1, 0, At, B0); PG8_MMA(1, 1, At, B1); PG8_BAR; PG8_SCHED;
;         }
;         if (wr == 0) PG8_BAR;
	s_add_i32 s13, s13, s59
	v_lshl_add_u64 v[162:163], v[162:163], 0, s[28:29]
	s_mov_b32 m0, s13
	ds_read_b128 v[186:189], v235 offset:49152
	ds_read_b128 v[190:193], v235 offset:50176
	ds_read_b128 v[194:197], v235 offset:51200
	ds_read_b128 v[198:201], v235 offset:52224
	ds_read_b128 v[202:205], v235 offset:53248
	ds_read_b128 v[210:213], v235 offset:54272
	ds_read_b128 v[220:223], v235 offset:55296
	ds_read_b128 v[236:239], v235 offset:56320
	global_load_lds_dwordx4 v[162:163], off
	s_add_i32 m0, s13, 0x2000
	s_add_u32 s86, s88, 0x80080
	v_lshl_add_u64 v[162:163], v[206:207], 0, s[28:29]
	s_addc_u32 s87, s89, 0
	s_add_i32 s13, s74, s59
	global_load_lds_dwordx4 v[162:163], off
	v_lshl_add_u64 v[162:163], s[86:87], 0, v[164:165]
	s_mov_b32 m0, s13
	s_nop 0
	global_load_lds_dwordx4 v[162:163], off
	v_lshl_add_u64 v[162:163], s[86:87], 0, v[136:137]
	s_add_i32 m0, s13, 0x2000
	s_nop 0
	global_load_lds_dwordx4 v[162:163], off
	v_lshl_add_u64 v[162:163], v[224:225], 0, s[28:29]
	s_mov_b32 m0, s93
	s_nop 0
	global_load_lds_dwordx4 v[162:163], off
	v_lshl_add_u64 v[162:163], v[226:227], 0, s[28:29]
	s_mov_b32 m0, s94
	s_nop 0
	global_load_lds_dwordx4 v[162:163], off
	s_waitcnt vmcnt(8)
	s_waitcnt lgkmcnt(0)
	s_barrier
	v_mfma_f32_16x16x32_bf16 v[112:115], v[142:145], v[186:189], v[112:115]
	v_mfma_f32_16x16x32_bf16 v[80:83], v[150:153], v[186:189], v[80:83]
	v_mfma_f32_16x16x32_bf16 v[108:111], v[142:145], v[194:197], v[108:111]
	v_mfma_f32_16x16x32_bf16 v[76:79], v[150:153], v[194:197], v[76:79]
	v_mfma_f32_16x16x32_bf16 v[104:107], v[142:145], v[202:205], v[104:107]
	v_mfma_f32_16x16x32_bf16 v[72:75], v[150:153], v[202:205], v[72:75]
	v_mfma_f32_16x16x32_bf16 v[100:103], v[142:145], v[220:223], v[100:103]
	v_mfma_f32_16x16x32_bf16 v[68:71], v[150:153], v[220:223], v[68:71]
	v_mfma_f32_16x16x32_bf16 v[112:115], v[146:149], v[190:193], v[112:115]
	v_mfma_f32_16x16x32_bf16 v[80:83], v[154:157], v[190:193], v[80:83]
	v_mfma_f32_16x16x32_bf16 v[108:111], v[146:149], v[198:201], v[108:111]
	v_mfma_f32_16x16x32_bf16 v[76:79], v[154:157], v[198:201], v[76:79]
	v_mfma_f32_16x16x32_bf16 v[104:107], v[146:149], v[210:213], v[104:107]
	v_mfma_f32_16x16x32_bf16 v[72:75], v[154:157], v[210:213], v[72:75]
	v_mfma_f32_16x16x32_bf16 v[100:103], v[146:149], v[236:239], v[100:103]
	v_mfma_f32_16x16x32_bf16 v[68:71], v[154:157], v[236:239], v[68:71]
	v_mfma_f32_16x16x32_bf16 v[48:51], v[158:161], v[186:189], v[48:51]
	v_mfma_f32_16x16x32_bf16 v[16:19], v[178:181], v[186:189], v[16:19]
	v_mfma_f32_16x16x32_bf16 v[44:47], v[158:161], v[194:197], v[44:47]
	v_mfma_f32_16x16x32_bf16 v[12:15], v[178:181], v[194:197], v[12:15]
	v_mfma_f32_16x16x32_bf16 v[40:43], v[158:161], v[202:205], v[40:43]
	v_mfma_f32_16x16x32_bf16 v[8:11], v[178:181], v[202:205], v[8:11]
	v_mfma_f32_16x16x32_bf16 v[36:39], v[158:161], v[220:223], v[36:39]
	v_mfma_f32_16x16x32_bf16 v[4:7], v[178:181], v[220:223], v[4:7]
	v_mfma_f32_16x16x32_bf16 v[48:51], v[174:177], v[190:193], v[48:51]
	v_mfma_f32_16x16x32_bf16 v[16:19], v[182:185], v[190:193], v[16:19]
	v_mfma_f32_16x16x32_bf16 v[44:47], v[174:177], v[198:201], v[44:47]
	v_mfma_f32_16x16x32_bf16 v[12:15], v[182:185], v[198:201], v[12:15]
	v_mfma_f32_16x16x32_bf16 v[40:43], v[174:177], v[210:213], v[40:43]
	v_mfma_f32_16x16x32_bf16 v[8:11], v[182:185], v[210:213], v[8:11]
	v_mfma_f32_16x16x32_bf16 v[36:39], v[174:177], v[236:239], v[36:39]
	v_mfma_f32_16x16x32_bf16 v[4:7], v[182:185], v[236:239], v[4:7]
	s_barrier
	s_add_i32 s12, s12, 2
	s_add_u32 vcc_lo, vcc_lo, 0x100
	s_addc_u32 vcc_hi, vcc_hi, 0
	s_cmp_gt_u32 s12, 29
	s_mov_b64 s[86:87], s[8:9]
	s_cbranch_scc0 .LBB0_251
	s_and_b64 vcc, exec, s[42:43]
	s_cbranch_vccz .LBB0_254
	s_barrier

; #define PG8_STAGE(bufoff, gbase, voff) do { _Pragma("unroll") for (int _i = 0; _i < 2; ++_i) \
;         __builtin_amdgcn_global_load_lds((const unsigned*)((const char*)(gbase) + (voff)[_i]), (LAS unsigned*)(lds + (bufoff) + ldsw + _i * 8192), 16, 0, 0); } while (0)
; #define PG8_LDA(dst, b, h) do { _Pragma("unroll") for (int m = 0; m < 4; ++m) _Pragma("unroll") for (int k = 0; k < 2; ++k) dst[m][k] = *(const LAS bf16x8*)(lds + PG8_SA(b, h) + aoff + m * 2048 + k * 1024); } while (0)
; #define PG8_LDB(dst, b, h) do { _Pragma("unroll") for (int n = 0; n < 2; ++n) _Pragma("unroll") for (int k = 0; k < 2; ++k) dst[n][k] = *(const LAS bf16x8*)(lds + PG8_SB(b, h) + boff + n * 2048 + k * 1024); } while (0)
; #define PG8_MMA(ai, bj, At, Bt) do { __builtin_amdgcn_s_setprio(1); _Pragma("unroll") for (int m = 0; m < 4; ++m) _Pragma("unroll") for (int n = 0; n < 2; ++n) _Pragma("unroll") for (int k = 0; k < 2; ++k) \
;         acc[ai][bj][m][n] = __builtin_amdgcn_mfma_f32_16x16x32_bf16(Bt[n][k], At[m][k], acc[ai][bj][m][n], 0, 0, 0); __builtin_amdgcn_s_setprio(0); } while (0)
; #define PG8_WAIT_V(n) asm volatile("s_waitcnt vmcnt(" #n ")" ::: "memory")
; #define PG8_WAIT_L(n) asm volatile("s_waitcnt lgkmcnt(" #n ")" ::: "memory")
; #define PG8_BAR __builtin_amdgcn_s_barrier()
; #define PG8_SCHED __builtin_amdgcn_sched_barrier(0)
; template <class Epi, class Sched>
; __device__ __forceinline__ void gemm_phase(LAS unsigned char* lds, const Gemm g, const Sched& S, const Epi& E, const int tid) {
;     ...
;         for (int t = 0; t < nt; t += 2) {
;             const bool last = (t == nt - 2);
;             const char* a1 = cA + (size_t)(t + 1) * kstep;
;             const char* a2 = last ? nA : cA + (size_t)(t + 2) * kstep; const char* b2 = last ? nB : cB + (size_t)(t + 2) * kstep;
;             const char* a3 = a2 + kstep; const char* b3 = b2 + kstep;
;             PG8_LDB(B0, 0, 0); PG8_LDB(B1, 0, 1); PG8_SCHED; PG8_LDA(At, 0, 0); PG8_STAGE(PG8_SA(1, 1), a1 + hstepA, voffA);
;             PG8_WAIT_V(8); PG8_WAIT_L(0); PG8_BAR; PG8_MMA(0, 0, At, B0); PG8_MMA(0, 1, At, B1); PG8_BAR; PG8_SCHED;
;             PG8_LDA(At, 0, 1); PG8_STAGE(PG8_SB(0, 0), b2, voffB); PG8_STAGE(PG8_SB(0, 1), b2 + hstepB, voffB); PG8_STAGE(PG8_SA(0, 0), a2, voffA);
;             PG8_WAIT_V(8); PG8_WAIT_L(0); PG8_BAR; PG8_MMA(1, 0, At, B0); PG8_MMA(1, 1, At, B1); PG8_BAR; PG8_SCHED;
.LBB0_279:
	s_add_u32 s8, s44, 0x100
	s_addc_u32 s9, s45, 0
	s_add_i32 s12, 0, 0x10000
	s_cmp_eq_u32 s94, 28
	s_cselect_b32 s55, s39, s9
	s_cselect_b32 s54, s38, s8
	s_cselect_b32 s47, s16, s93
	s_cselect_b32 s46, s17, s31
	s_add_i32 s95, 0, 0x14000
	v_add_u32_e32 v158, s12, v155
	v_add_u32_e32 v162, s95, v155
	ds_read_b128 v[142:145], v158
	ds_read_b128 v[146:149], v158 offset:1024
	ds_read_b128 v[150:153], v158 offset:2048
	ds_read_b128 v[158:161], v158 offset:3072
	ds_read_b128 v[174:177], v162
	ds_read_b128 v[178:181], v162 offset:1024
	ds_read_b128 v[182:185], v162 offset:2048
	ds_read_b128 v[186:189], v162 offset:3072
	v_lshl_add_u64 v[162:163], s[44:45], 0, v[138:139]
	s_add_i32 m0, s79, 0xc000
	ds_read_b128 v[190:193], v157
	ds_read_b128 v[194:197], v157 offset:1024
	ds_read_b128 v[198:201], v157 offset:2048
	ds_read_b128 v[202:205], v157 offset:3072
	ds_read_b128 v[210:213], v157 offset:4096
	ds_read_b128 v[220:223], v157 offset:5120
	ds_read_b128 v[234:237], v157 offset:6144
	ds_read_b128 v[238:241], v157 offset:7168
	global_load_lds_dwordx4 v[162:163], off
	v_lshl_add_u64 v[162:163], s[44:45], 0, v[140:141]
	s_add_i32 m0, s79, 0xe000
	s_nop 0
	global_load_lds_dwordx4 v[162:163], off
	s_waitcnt vmcnt(8)
	s_waitcnt lgkmcnt(0)
	s_barrier
	v_mfma_f32_16x16x32_bf16 v[128:131], v[142:145], v[190:193], v[128:131]
	v_mfma_f32_16x16x32_bf16 v[96:99], v[150:153], v[190:193], v[96:99]
	v_mfma_f32_16x16x32_bf16 v[124:127], v[142:145], v[198:201], v[124:127]
	v_mfma_f32_16x16x32_bf16 v[92:95], v[150:153], v[198:201], v[92:95]
	v_mfma_f32_16x16x32_bf16 v[120:123], v[142:145], v[210:213], v[120:123]
	v_mfma_f32_16x16x32_bf16 v[88:91], v[150:153], v[210:213], v[88:91]
	v_mfma_f32_16x16x32_bf16 v[116:119], v[142:145], v[234:237], v[116:119]
	v_mfma_f32_16x16x32_bf16 v[84:87], v[150:153], v[234:237], v[84:87]
	v_mfma_f32_16x16x32_bf16 v[128:131], v[146:149], v[194:197], v[128:131]
	v_mfma_f32_16x16x32_bf16 v[96:99], v[158:161], v[194:197], v[96:99]
	v_mfma_f32_16x16x32_bf16 v[124:127], v[146:149], v[202:205], v[124:127]
	v_mfma_f32_16x16x32_bf16 v[92:95], v[158:161], v[202:205], v[92:95]
	v_mfma_f32_16x16x32_bf16 v[120:123], v[146:149], v[220:223], v[120:123]
	v_mfma_f32_16x16x32_bf16 v[88:91], v[158:161], v[220:223], v[88:91]
	v_mfma_f32_16x16x32_bf16 v[116:119], v[146:149], v[238:241], v[116:119]
	v_mfma_f32_16x16x32_bf16 v[84:87], v[158:161], v[238:241], v[84:87]
	v_mfma_f32_16x16x32_bf16 v[64:67], v[174:177], v[190:193], v[64:67]
	v_mfma_f32_16x16x32_bf16 v[32:35], v[182:185], v[190:193], v[32:35]
	v_mfma_f32_16x16x32_bf16 v[60:63], v[174:177], v[198:201], v[60:63]
	v_mfma_f32_16x16x32_bf16 v[28:31], v[182:185], v[198:201], v[28:31]
	v_mfma_f32_16x16x32_bf16 v[56:59], v[174:177], v[210:213], v[56:59]
	v_mfma_f32_16x16x32_bf16 v[24:27], v[182:185], v[210:213], v[24:27]
	v_mfma_f32_16x16x32_bf16 v[52:55], v[174:177], v[234:237], v[52:55]
	v_mfma_f32_16x16x32_bf16 v[20:23], v[182:185], v[234:237], v[20:23]
	v_mfma_f32_16x16x32_bf16 v[64:67], v[178:181], v[194:197], v[64:67]
	v_mfma_f32_16x16x32_bf16 v[32:35], v[186:189], v[194:197], v[32:35]
	v_mfma_f32_16x16x32_bf16 v[60:63], v[178:181], v[202:205], v[60:63]
	v_mfma_f32_16x16x32_bf16 v[28:31], v[186:189], v[202:205], v[28:31]
	v_mfma_f32_16x16x32_bf16 v[56:59], v[178:181], v[220:223], v[56:59]
	v_mfma_f32_16x16x32_bf16 v[24:27], v[186:189], v[220:223], v[24:27]
	v_mfma_f32_16x16x32_bf16 v[52:55], v[178:181], v[238:241], v[52:55]
	v_mfma_f32_16x16x32_bf16 v[20:23], v[186:189], v[238:241], v[20:23]
	s_barrier
	s_add_i32 s12, s12, s59
	v_lshl_add_u64 v[162:163], s[46:47], 0, v[164:165]
	s_mov_b32 m0, s12
	ds_read_b128 v[190:193], v157 offset:16384
	ds_read_b128 v[194:197], v157 offset:17408
	ds_read_b128 v[198:201], v157 offset:18432
	ds_read_b128 v[202:205], v157 offset:19456
	ds_read_b128 v[210:213], v157 offset:20480
	ds_read_b128 v[220:223], v157 offset:21504
	ds_read_b128 v[234:237], v157 offset:22528
	ds_read_b128 v[238:241], v157 offset:23552
	global_load_lds_dwordx4 v[162:163], off
	s_add_i32 m0, s12, 0x2000
	s_add_u32 s12, s46, 0x80000
	v_lshl_add_u64 v[206:207], s[46:47], 0, v[136:137]
	s_addc_u32 s13, s47, 0
	s_add_i32 s44, s95, s59
	global_load_lds_dwordx4 v[206:207], off
	v_lshl_add_u64 v[224:225], s[12:13], 0, v[164:165]
	s_mov_b32 m0, s44
	v_lshl_add_u64 v[226:227], s[54:55], 0, v[134:135]
	global_load_lds_dwordx4 v[224:225], off
	v_lshl_add_u64 v[224:225], s[12:13], 0, v[136:137]
	s_add_i32 m0, s44, 0x2000
	s_nop 0
	global_load_lds_dwordx4 v[224:225], off
	v_lshl_add_u64 v[224:225], s[54:55], 0, v[132:133]
	s_mov_b32 m0, s79
	s_nop 0
	global_load_lds_dwordx4 v[224:225], off
	s_mov_b32 m0, s84
	s_nop 0
	global_load_lds_dwordx4 v[226:227], off
	s_waitcnt vmcnt(8)
	s_waitcnt lgkmcnt(0)
	s_barrier
; #define PG8_STAGE(bufoff, gbase, voff) do { _Pragma("unroll") for (int _i = 0; _i < 2; ++_i) \
;         __builtin_amdgcn_global_load_lds((const unsigned*)((const char*)(gbase) + (voff)[_i]), (LAS unsigned*)(lds + (bufoff) + ldsw + _i * 8192), 16, 0, 0); } while (0)
; #define PG8_LDA(dst, b, h) do { _Pragma("unroll") for (int m = 0; m < 4; ++m) _Pragma("unroll") for (int k = 0; k < 2; ++k) dst[m][k] = *(const LAS bf16x8*)(lds + PG8_SA(b, h) + aoff + m * 2048 + k * 1024); } while (0)
; #define PG8_LDB(dst, b, h) do { _Pragma("unroll") for (int n = 0; n < 2; ++n) _Pragma("unroll") for (int k = 0; k < 2; ++k) dst[n][k] = *(const LAS bf16x8*)(lds + PG8_SB(b, h) + boff + n * 2048 + k * 1024); } while (0)
; #define PG8_MMA(ai, bj, At, Bt) do { __builtin_amdgcn_s_setprio(1); _Pragma("unroll") for (int m = 0; m < 4; ++m) _Pragma("unroll") for (int n = 0; n < 2; ++n) _Pragma("unroll") for (int k = 0; k < 2; ++k) \
;         acc[ai][bj][m][n] = __builtin_amdgcn_mfma_f32_16x16x32_bf16(Bt[n][k], At[m][k], acc[ai][bj][m][n], 0, 0, 0); __builtin_amdgcn_s_setprio(0); } while (0)
; #define PG8_WAIT_V(n) asm volatile("s_waitcnt vmcnt(" #n ")" ::: "memory")
; #define PG8_WAIT_L(n) asm volatile("s_waitcnt lgkmcnt(" #n ")" ::: "memory")
; #define PG8_BAR __builtin_amdgcn_s_barrier()
; #define PG8_SCHED __builtin_amdgcn_sched_barrier(0)
; template <class Epi, class Sched>
; __device__ __forceinline__ void gemm_phase(LAS unsigned char* lds, const Gemm g, const Sched& S, const Epi& E, const int tid) {
;     ...
;             PG8_WAIT_V(8); PG8_WAIT_L(0); PG8_BAR; PG8_MMA(0, 0, At, B0); PG8_MMA(0, 1, At, B1); PG8_BAR; PG8_SCHED;
;             PG8_LDA(At, 0, 1); PG8_STAGE(PG8_SB(0, 0), b2, voffB); PG8_STAGE(PG8_SB(0, 1), b2 + hstepB, voffB); PG8_STAGE(PG8_SA(0, 0), a2, voffA);
;             PG8_WAIT_V(8); PG8_WAIT_L(0); PG8_BAR; PG8_MMA(1, 0, At, B0); PG8_MMA(1, 1, At, B1); PG8_BAR; PG8_SCHED;
;             PG8_LDB(B0, 1, 0); PG8_LDB(B1, 1, 1); PG8_SCHED; PG8_LDA(At, 1, 0); PG8_STAGE(PG8_SA(0, 1), a2 + hstepA, voffA);
;             PG8_WAIT_V(8); PG8_WAIT_L(0); PG8_BAR; PG8_MMA(0, 0, At, B0); PG8_MMA(0, 1, At, B1); PG8_BAR; PG8_SCHED;
	v_mfma_f32_16x16x32_bf16 v[112:115], v[142:145], v[190:193], v[112:115]
	v_mfma_f32_16x16x32_bf16 v[80:83], v[150:153], v[190:193], v[80:83]
	v_mfma_f32_16x16x32_bf16 v[108:111], v[142:145], v[198:201], v[108:111]
	v_mfma_f32_16x16x32_bf16 v[76:79], v[150:153], v[198:201], v[76:79]
	v_mfma_f32_16x16x32_bf16 v[104:107], v[142:145], v[210:213], v[104:107]
	v_mfma_f32_16x16x32_bf16 v[72:75], v[150:153], v[210:213], v[72:75]
	v_mfma_f32_16x16x32_bf16 v[100:103], v[142:145], v[234:237], v[100:103]
	v_mfma_f32_16x16x32_bf16 v[68:71], v[150:153], v[234:237], v[68:71]
	v_mfma_f32_16x16x32_bf16 v[112:115], v[146:149], v[194:197], v[112:115]
	v_mfma_f32_16x16x32_bf16 v[80:83], v[158:161], v[194:197], v[80:83]
	v_mfma_f32_16x16x32_bf16 v[108:111], v[146:149], v[202:205], v[108:111]
	v_mfma_f32_16x16x32_bf16 v[76:79], v[158:161], v[202:205], v[76:79]
	v_mfma_f32_16x16x32_bf16 v[104:107], v[146:149], v[220:223], v[104:107]
	v_mfma_f32_16x16x32_bf16 v[72:75], v[158:161], v[220:223], v[72:75]
	v_mfma_f32_16x16x32_bf16 v[100:103], v[146:149], v[238:241], v[100:103]
	v_mfma_f32_16x16x32_bf16 v[68:71], v[158:161], v[238:241], v[68:71]
	v_mfma_f32_16x16x32_bf16 v[48:51], v[174:177], v[190:193], v[48:51]
	v_mfma_f32_16x16x32_bf16 v[16:19], v[182:185], v[190:193], v[16:19]
	v_mfma_f32_16x16x32_bf16 v[44:47], v[174:177], v[198:201], v[44:47]
	v_mfma_f32_16x16x32_bf16 v[12:15], v[182:185], v[198:201], v[12:15]
	v_mfma_f32_16x16x32_bf16 v[40:43], v[174:177], v[210:213], v[40:43]
	v_mfma_f32_16x16x32_bf16 v[8:11], v[182:185], v[210:213], v[8:11]
	v_mfma_f32_16x16x32_bf16 v[36:39], v[174:177], v[234:237], v[36:39]
	v_mfma_f32_16x16x32_bf16 v[4:7], v[182:185], v[234:237], v[4:7]
	v_mfma_f32_16x16x32_bf16 v[48:51], v[178:181], v[194:197], v[48:51]
	v_mfma_f32_16x16x32_bf16 v[16:19], v[186:189], v[194:197], v[16:19]
	v_mfma_f32_16x16x32_bf16 v[44:47], v[178:181], v[202:205], v[44:47]
	v_mfma_f32_16x16x32_bf16 v[12:15], v[186:189], v[202:205], v[12:15]
	v_mfma_f32_16x16x32_bf16 v[40:43], v[178:181], v[220:223], v[40:43]
	v_mfma_f32_16x16x32_bf16 v[8:11], v[186:189], v[220:223], v[8:11]
	v_mfma_f32_16x16x32_bf16 v[36:39], v[178:181], v[238:241], v[36:39]
	v_mfma_f32_16x16x32_bf16 v[4:7], v[186:189], v[238:241], v[4:7]
	s_barrier
	s_add_i32 s44, 0, 0x18000
	s_add_i32 s45, 0, 0x1c000
	v_add_u32_e32 v158, s44, v155
	v_add_u32_e32 v171, s45, v155
	ds_read_b128 v[142:145], v158
	ds_read_b128 v[146:149], v158 offset:1024
	ds_read_b128 v[150:153], v158 offset:2048
	ds_read_b128 v[158:161], v158 offset:3072
	ds_read_b128 v[174:177], v171
	ds_read_b128 v[178:181], v171 offset:1024
	ds_read_b128 v[182:185], v171 offset:2048
	ds_read_b128 v[186:189], v171 offset:3072
	s_add_u32 s12, s54, 0x242000
	s_addc_u32 s13, s55, 0
	s_mov_b32 m0, s85
	v_lshl_add_u64 v[242:243], s[12:13], 0, v[132:133]
	ds_read_b128 v[190:193], v157 offset:32768
	ds_read_b128 v[194:197], v157 offset:33792
	ds_read_b128 v[198:201], v157 offset:34816
	ds_read_b128 v[202:205], v157 offset:35840
	ds_read_b128 v[210:213], v157 offset:36864
	ds_read_b128 v[220:223], v157 offset:37888
	ds_read_b128 v[234:237], v157 offset:38912
	ds_read_b128 v[238:241], v157 offset:39936
	global_load_lds_dwordx4 v[242:243], off
	v_lshl_add_u64 v[242:243], s[12:13], 0, v[134:135]
	s_mov_b32 m0, s86
	s_nop 0
	global_load_lds_dwordx4 v[242:243], off
	s_waitcnt vmcnt(8)
	s_waitcnt lgkmcnt(0)
	s_barrier
	v_mfma_f32_16x16x32_bf16 v[128:131], v[142:145], v[190:193], v[128:131]
	v_mfma_f32_16x16x32_bf16 v[96:99], v[150:153], v[190:193], v[96:99]
	v_mfma_f32_16x16x32_bf16 v[124:127], v[142:145], v[198:201], v[124:127]
	v_mfma_f32_16x16x32_bf16 v[92:95], v[150:153], v[198:201], v[92:95]
	v_mfma_f32_16x16x32_bf16 v[120:123], v[142:145], v[210:213], v[120:123]
	v_mfma_f32_16x16x32_bf16 v[88:91], v[150:153], v[210:213], v[88:91]
	v_mfma_f32_16x16x32_bf16 v[116:119], v[142:145], v[234:237], v[116:119]
	v_mfma_f32_16x16x32_bf16 v[84:87], v[150:153], v[234:237], v[84:87]
	v_mfma_f32_16x16x32_bf16 v[128:131], v[146:149], v[194:197], v[128:131]
	v_mfma_f32_16x16x32_bf16 v[96:99], v[158:161], v[194:197], v[96:99]
	v_mfma_f32_16x16x32_bf16 v[124:127], v[146:149], v[202:205], v[124:127]
	v_mfma_f32_16x16x32_bf16 v[92:95], v[158:161], v[202:205], v[92:95]
	v_mfma_f32_16x16x32_bf16 v[120:123], v[146:149], v[220:223], v[120:123]
	v_mfma_f32_16x16x32_bf16 v[88:91], v[158:161], v[220:223], v[88:91]
	v_mfma_f32_16x16x32_bf16 v[116:119], v[146:149], v[238:241], v[116:119]
	v_mfma_f32_16x16x32_bf16 v[84:87], v[158:161], v[238:241], v[84:87]
	v_mfma_f32_16x16x32_bf16 v[64:67], v[174:177], v[190:193], v[64:67]
	v_mfma_f32_16x16x32_bf16 v[32:35], v[182:185], v[190:193], v[32:35]
	v_mfma_f32_16x16x32_bf16 v[60:63], v[174:177], v[198:201], v[60:63]
	v_mfma_f32_16x16x32_bf16 v[28:31], v[182:185], v[198:201], v[28:31]
	v_mfma_f32_16x16x32_bf16 v[56:59], v[174:177], v[210:213], v[56:59]
	v_mfma_f32_16x16x32_bf16 v[24:27], v[182:185], v[210:213], v[24:27]
	v_mfma_f32_16x16x32_bf16 v[52:55], v[174:177], v[234:237], v[52:55]
	v_mfma_f32_16x16x32_bf16 v[20:23], v[182:185], v[234:237], v[20:23]
	v_mfma_f32_16x16x32_bf16 v[64:67], v[178:181], v[194:197], v[64:67]
	v_mfma_f32_16x16x32_bf16 v[32:35], v[186:189], v[194:197], v[32:35]
	v_mfma_f32_16x16x32_bf16 v[60:63], v[178:181], v[202:205], v[60:63]
	v_mfma_f32_16x16x32_bf16 v[28:31], v[186:189], v[202:205], v[28:31]
	v_mfma_f32_16x16x32_bf16 v[56:59], v[178:181], v[220:223], v[56:59]
	v_mfma_f32_16x16x32_bf16 v[24:27], v[186:189], v[220:223], v[24:27]
	v_mfma_f32_16x16x32_bf16 v[52:55], v[178:181], v[238:241], v[52:55]
	v_mfma_f32_16x16x32_bf16 v[20:23], v[186:189], v[238:241], v[20:23]
	s_barrier
; #define PG8_STAGE(bufoff, gbase, voff) do { _Pragma("unroll") for (int _i = 0; _i < 2; ++_i) \
;         __builtin_amdgcn_global_load_lds((const unsigned*)((const char*)(gbase) + (voff)[_i]), (LAS unsigned*)(lds + (bufoff) + ldsw + _i * 8192), 16, 0, 0); } while (0)
; #define PG8_LDA(dst, b, h) do { _Pragma("unroll") for (int m = 0; m < 4; ++m) _Pragma("unroll") for (int k = 0; k < 2; ++k) dst[m][k] = *(const LAS bf16x8*)(lds + PG8_SA(b, h) + aoff + m * 2048 + k * 1024); } while (0)
; #define PG8_MMA(ai, bj, At, Bt) do { __builtin_amdgcn_s_setprio(1); _Pragma("unroll") for (int m = 0; m < 4; ++m) _Pragma("unroll") for (int n = 0; n < 2; ++n) _Pragma("unroll") for (int k = 0; k < 2; ++k) \
;         acc[ai][bj][m][n] = __builtin_amdgcn_mfma_f32_16x16x32_bf16(Bt[n][k], At[m][k], acc[ai][bj][m][n], 0, 0, 0); __builtin_amdgcn_s_setprio(0); } while (0)
; #define PG8_WAIT_V(n) asm volatile("s_waitcnt vmcnt(" #n ")" ::: "memory")
; #define PG8_WAIT_L(n) asm volatile("s_waitcnt lgkmcnt(" #n ")" ::: "memory")
; #define PG8_BAR __builtin_amdgcn_s_barrier()
; #define PG8_SCHED __builtin_amdgcn_sched_barrier(0)
; template <class Epi, class Sched>
; __device__ __forceinline__ void gemm_phase(LAS unsigned char* lds, const Gemm g, const Sched& S, const Epi& E, const int tid) {
;     ...
;             PG8_LDA(At, 1, 1); PG8_STAGE(PG8_SB(1, 0), b3, voffB); PG8_STAGE(PG8_SB(1, 1), b3 + hstepB, voffB); PG8_STAGE(PG8_SA(1, 0), a3, voffA);
;             PG8_WAIT_V(8); PG8_WAIT_L(0); PG8_BAR; PG8_MMA(1, 0, At, B0); PG8_MMA(1, 1, At, B1); PG8_BAR; PG8_SCHED;
;         }
;         if (wr == 0) PG8_BAR;
	s_add_i32 s12, s44, s59
	v_lshl_add_u64 v[162:163], v[162:163], 0, s[28:29]
	s_mov_b32 m0, s12
	ds_read_b128 v[190:193], v157 offset:49152
	ds_read_b128 v[194:197], v157 offset:50176
	ds_read_b128 v[198:201], v157 offset:51200
	ds_read_b128 v[202:205], v157 offset:52224
	ds_read_b128 v[210:213], v157 offset:53248
	ds_read_b128 v[220:223], v157 offset:54272
	ds_read_b128 v[234:237], v157 offset:55296
	ds_read_b128 v[238:241], v157 offset:56320
	global_load_lds_dwordx4 v[162:163], off
	s_add_i32 m0, s12, 0x2000
	s_add_u32 s12, s46, 0x80080
	v_lshl_add_u64 v[162:163], v[206:207], 0, s[28:29]
	s_addc_u32 s13, s47, 0
	s_add_i32 s44, s45, s59
	global_load_lds_dwordx4 v[162:163], off
	v_lshl_add_u64 v[162:163], s[12:13], 0, v[164:165]
	s_mov_b32 m0, s44
	s_nop 0
	global_load_lds_dwordx4 v[162:163], off
	v_lshl_add_u64 v[162:163], s[12:13], 0, v[136:137]
	s_add_i32 m0, s44, 0x2000
	s_nop 0
	global_load_lds_dwordx4 v[162:163], off
	v_lshl_add_u64 v[162:163], v[224:225], 0, s[28:29]
	s_mov_b32 m0, s87
	s_nop 0
	global_load_lds_dwordx4 v[162:163], off
	v_lshl_add_u64 v[162:163], v[226:227], 0, s[28:29]
	s_mov_b32 m0, s88
	s_nop 0
	global_load_lds_dwordx4 v[162:163], off
	s_waitcnt vmcnt(8)
	s_waitcnt lgkmcnt(0)
	s_barrier
	v_mfma_f32_16x16x32_bf16 v[112:115], v[142:145], v[190:193], v[112:115]
	v_mfma_f32_16x16x32_bf16 v[80:83], v[150:153], v[190:193], v[80:83]
	v_mfma_f32_16x16x32_bf16 v[108:111], v[142:145], v[198:201], v[108:111]
	v_mfma_f32_16x16x32_bf16 v[76:79], v[150:153], v[198:201], v[76:79]
	v_mfma_f32_16x16x32_bf16 v[104:107], v[142:145], v[210:213], v[104:107]
	v_mfma_f32_16x16x32_bf16 v[72:75], v[150:153], v[210:213], v[72:75]
	v_mfma_f32_16x16x32_bf16 v[100:103], v[142:145], v[234:237], v[100:103]
	v_mfma_f32_16x16x32_bf16 v[68:71], v[150:153], v[234:237], v[68:71]
	v_mfma_f32_16x16x32_bf16 v[112:115], v[146:149], v[194:197], v[112:115]
	v_mfma_f32_16x16x32_bf16 v[80:83], v[158:161], v[194:197], v[80:83]
	v_mfma_f32_16x16x32_bf16 v[108:111], v[146:149], v[202:205], v[108:111]
	v_mfma_f32_16x16x32_bf16 v[76:79], v[158:161], v[202:205], v[76:79]
	v_mfma_f32_16x16x32_bf16 v[104:107], v[146:149], v[220:223], v[104:107]
	v_mfma_f32_16x16x32_bf16 v[72:75], v[158:161], v[220:223], v[72:75]
	v_mfma_f32_16x16x32_bf16 v[100:103], v[146:149], v[238:241], v[100:103]
	v_mfma_f32_16x16x32_bf16 v[68:71], v[158:161], v[238:241], v[68:71]
	v_mfma_f32_16x16x32_bf16 v[48:51], v[174:177], v[190:193], v[48:51]
	v_mfma_f32_16x16x32_bf16 v[16:19], v[182:185], v[190:193], v[16:19]
	v_mfma_f32_16x16x32_bf16 v[44:47], v[174:177], v[198:201], v[44:47]
	v_mfma_f32_16x16x32_bf16 v[12:15], v[182:185], v[198:201], v[12:15]
	v_mfma_f32_16x16x32_bf16 v[40:43], v[174:177], v[210:213], v[40:43]
	v_mfma_f32_16x16x32_bf16 v[8:11], v[182:185], v[210:213], v[8:11]
	v_mfma_f32_16x16x32_bf16 v[36:39], v[174:177], v[234:237], v[36:39]
	v_mfma_f32_16x16x32_bf16 v[4:7], v[182:185], v[234:237], v[4:7]
	v_mfma_f32_16x16x32_bf16 v[48:51], v[178:181], v[194:197], v[48:51]
	v_mfma_f32_16x16x32_bf16 v[16:19], v[186:189], v[194:197], v[16:19]
	v_mfma_f32_16x16x32_bf16 v[44:47], v[178:181], v[202:205], v[44:47]
	v_mfma_f32_16x16x32_bf16 v[12:15], v[186:189], v[202:205], v[12:15]
	v_mfma_f32_16x16x32_bf16 v[40:43], v[178:181], v[220:223], v[40:43]
	v_mfma_f32_16x16x32_bf16 v[8:11], v[186:189], v[220:223], v[8:11]
	v_mfma_f32_16x16x32_bf16 v[36:39], v[178:181], v[238:241], v[36:39]
	v_mfma_f32_16x16x32_bf16 v[4:7], v[186:189], v[238:241], v[4:7]
	s_barrier
	s_add_i32 s94, s94, 2
	s_add_u32 s31, s31, 0x100
	s_addc_u32 s93, s93, 0
	s_cmp_gt_u32 s94, 29
	s_mov_b64 s[44:45], s[8:9]
	s_cbranch_scc0 .LBB0_279
	s_and_b64 vcc, exec, s[20:21]
	s_cbranch_vccz .LBB0_282
	s_barrier

; #define PG8_STAGE(bufoff, gbase, voff) do { _Pragma("unroll") for (int _i = 0; _i < 2; ++_i) \
;         __builtin_amdgcn_global_load_lds((const unsigned*)((const char*)(gbase) + (voff)[_i]), (LAS unsigned*)(lds + (bufoff) + ldsw + _i * 8192), 16, 0, 0); } while (0)
; #define PG8_LDA(dst, b, h) do { _Pragma("unroll") for (int m = 0; m < 4; ++m) _Pragma("unroll") for (int k = 0; k < 2; ++k) dst[m][k] = *(const LAS bf16x8*)(lds + PG8_SA(b, h) + aoff + m * 2048 + k * 1024); } while (0)
; #define PG8_LDB(dst, b, h) do { _Pragma("unroll") for (int n = 0; n < 2; ++n) _Pragma("unroll") for (int k = 0; k < 2; ++k) dst[n][k] = *(const LAS bf16x8*)(lds + PG8_SB(b, h) + boff + n * 2048 + k * 1024); } while (0)
; #define PG8_MMA(ai, bj, At, Bt) do { __builtin_amdgcn_s_setprio(1); _Pragma("unroll") for (int m = 0; m < 4; ++m) _Pragma("unroll") for (int n = 0; n < 2; ++n) _Pragma("unroll") for (int k = 0; k < 2; ++k) \
;         acc[ai][bj][m][n] = __builtin_amdgcn_mfma_f32_16x16x32_bf16(Bt[n][k], At[m][k], acc[ai][bj][m][n], 0, 0, 0); __builtin_amdgcn_s_setprio(0); } while (0)
; #define PG8_WAIT_V(n) asm volatile("s_waitcnt vmcnt(" #n ")" ::: "memory")
; #define PG8_WAIT_L(n) asm volatile("s_waitcnt lgkmcnt(" #n ")" ::: "memory")
; #define PG8_BAR __builtin_amdgcn_s_barrier()
; #define PG8_SCHED __builtin_amdgcn_sched_barrier(0)
; template <class Epi, class Sched>
; __device__ __forceinline__ void gemm_phase(LAS unsigned char* lds, const Gemm g, const Sched& S, const Epi& E, const int tid) {
;     ...
;         for (int t = 0; t < nt; t += 2) {
;             const bool last = (t == nt - 2);
;             const char* a1 = cA + (size_t)(t + 1) * kstep;
;             const char* a2 = last ? nA : cA + (size_t)(t + 2) * kstep; const char* b2 = last ? nB : cB + (size_t)(t + 2) * kstep;
;             const char* a3 = a2 + kstep; const char* b3 = b2 + kstep;
;             PG8_LDB(B0, 0, 0); PG8_LDB(B1, 0, 1); PG8_SCHED; PG8_LDA(At, 0, 0); PG8_STAGE(PG8_SA(1, 1), a1 + hstepA, voffA);
;             PG8_WAIT_V(8); PG8_WAIT_L(0); PG8_BAR; PG8_MMA(0, 0, At, B0); PG8_MMA(0, 1, At, B1); PG8_BAR; PG8_SCHED;
;             PG8_LDA(At, 0, 1); PG8_STAGE(PG8_SB(0, 0), b2, voffB); PG8_STAGE(PG8_SB(0, 1), b2 + hstepB, voffB); PG8_STAGE(PG8_SA(0, 0), a2, voffA);
;             PG8_WAIT_V(8); PG8_WAIT_L(0); PG8_BAR; PG8_MMA(1, 0, At, B0); PG8_MMA(1, 1, At, B1); PG8_BAR; PG8_SCHED;
.LBB0_308:
	s_add_u32 s12, s54, 0xfffc0080
	s_addc_u32 s13, s55, -1
	s_add_i32 vcc_lo, 0, 0x10000
	s_cmp_eq_u32 s97, 12
	s_cselect_b32 s93, s16, s13
	s_cselect_b32 s92, s17, s12
	v_add_u32_e32 v154, vcc_lo, v151
	s_cselect_b32 s91, s31, s96
	s_cselect_b32 s90, s39, s47
	s_add_i32 vcc_hi, 0, 0x14000
	ds_read_b128 v[136:139], v154
	ds_read_b128 v[174:177], v154 offset:1024
	ds_read_b128 v[178:181], v154 offset:2048
	ds_read_b128 v[182:185], v154 offset:3072
	v_add_u32_e32 v154, vcc_hi, v151
	ds_read_b128 v[186:189], v154
	ds_read_b128 v[190:193], v154 offset:1024
	ds_read_b128 v[194:197], v154 offset:2048
	ds_read_b128 v[198:201], v154 offset:3072
	v_lshl_add_u64 v[154:155], s[54:55], 0, v[132:133]
	s_add_i32 m0, s79, 0xc000
	ds_read_b128 v[202:205], v153
	ds_read_b128 v[220:223], v153 offset:1024
	ds_read_b128 v[234:237], v153 offset:2048
	ds_read_b128 v[238:241], v153 offset:3072
	ds_read_b128 v[242:245], v153 offset:4096
	ds_read_b128 v[246:249], v153 offset:5120
	ds_read_b128 v[250:253], v153 offset:6144
	ds_read_b128 v[210:213], v153 offset:7168
	global_load_lds_dwordx4 v[154:155], off
	v_lshl_add_u64 v[154:155], s[54:55], 0, v[134:135]
	s_add_i32 m0, s79, 0xe000
	s_nop 0
	global_load_lds_dwordx4 v[154:155], off
	s_waitcnt vmcnt(8)
	s_waitcnt lgkmcnt(0)
	s_barrier
	v_mfma_f32_16x16x32_bf16 v[128:131], v[136:139], v[202:205], v[128:131]
	v_mfma_f32_16x16x32_bf16 v[124:127], v[178:181], v[202:205], v[124:127]
	v_mfma_f32_16x16x32_bf16 v[120:123], v[136:139], v[234:237], v[120:123]
	v_mfma_f32_16x16x32_bf16 v[112:115], v[178:181], v[234:237], v[112:115]
	v_mfma_f32_16x16x32_bf16 v[96:99], v[136:139], v[242:245], v[96:99]
	v_mfma_f32_16x16x32_bf16 v[92:95], v[178:181], v[242:245], v[92:95]
	v_mfma_f32_16x16x32_bf16 v[88:91], v[136:139], v[250:253], v[88:91]
	v_mfma_f32_16x16x32_bf16 v[80:83], v[178:181], v[250:253], v[80:83]
	v_mfma_f32_16x16x32_bf16 v[128:131], v[174:177], v[220:223], v[128:131]
	v_mfma_f32_16x16x32_bf16 v[124:127], v[182:185], v[220:223], v[124:127]
	v_mfma_f32_16x16x32_bf16 v[120:123], v[174:177], v[238:241], v[120:123]
	v_mfma_f32_16x16x32_bf16 v[112:115], v[182:185], v[238:241], v[112:115]
	v_mfma_f32_16x16x32_bf16 v[96:99], v[174:177], v[246:249], v[96:99]
	v_mfma_f32_16x16x32_bf16 v[92:95], v[182:185], v[246:249], v[92:95]
	v_mfma_f32_16x16x32_bf16 v[88:91], v[174:177], v[210:213], v[88:91]
	v_mfma_f32_16x16x32_bf16 v[80:83], v[182:185], v[210:213], v[80:83]
	v_mfma_f32_16x16x32_bf16 v[116:119], v[186:189], v[202:205], v[116:119]
	v_mfma_f32_16x16x32_bf16 v[108:111], v[194:197], v[202:205], v[108:111]
	v_mfma_f32_16x16x32_bf16 v[104:107], v[186:189], v[234:237], v[104:107]
	v_mfma_f32_16x16x32_bf16 v[100:103], v[194:197], v[234:237], v[100:103]
	v_mfma_f32_16x16x32_bf16 v[84:87], v[186:189], v[242:245], v[84:87]
	v_mfma_f32_16x16x32_bf16 v[76:79], v[194:197], v[242:245], v[76:79]
	v_mfma_f32_16x16x32_bf16 v[72:75], v[186:189], v[250:253], v[72:75]
	v_mfma_f32_16x16x32_bf16 v[68:71], v[194:197], v[250:253], v[68:71]
	v_mfma_f32_16x16x32_bf16 v[116:119], v[190:193], v[220:223], v[116:119]
	v_mfma_f32_16x16x32_bf16 v[108:111], v[198:201], v[220:223], v[108:111]
	v_mfma_f32_16x16x32_bf16 v[104:107], v[190:193], v[238:241], v[104:107]
	v_mfma_f32_16x16x32_bf16 v[100:103], v[198:201], v[238:241], v[100:103]
	v_mfma_f32_16x16x32_bf16 v[84:87], v[190:193], v[246:249], v[84:87]
	v_mfma_f32_16x16x32_bf16 v[76:79], v[198:201], v[246:249], v[76:79]
	v_mfma_f32_16x16x32_bf16 v[72:75], v[190:193], v[210:213], v[72:75]
	v_mfma_f32_16x16x32_bf16 v[68:71], v[198:201], v[210:213], v[68:71]
	s_barrier
	s_add_i32 s12, vcc_lo, s59
	v_lshl_add_u64 v[154:155], s[90:91], 0, v[164:165]
	s_mov_b32 m0, s12
	ds_read_b128 v[202:205], v153 offset:16384
	ds_read_b128 v[210:213], v153 offset:17408
	ds_read_b128 v[220:223], v153 offset:18432
	ds_read_b128 v[234:237], v153 offset:19456
	ds_read_b128 v[238:241], v153 offset:20480
	ds_read_b128 v[242:245], v153 offset:21504
	ds_read_b128 v[246:249], v153 offset:22528
	ds_read_b128 v[250:253], v153 offset:23552
	global_load_lds_dwordx4 v[154:155], off
	s_add_i32 m0, s12, 0x2000
	s_add_u32 s12, s90, 0x40000
	v_lshl_add_u64 v[162:163], s[90:91], 0, v[160:161]
	s_addc_u32 s13, s91, 0
	s_add_i32 vcc_lo, vcc_hi, s59
	global_load_lds_dwordx4 v[162:163], off
	v_lshl_add_u64 v[206:207], s[12:13], 0, v[164:165]
	s_mov_b32 m0, vcc_lo
	v_lshl_add_u64 v[224:225], s[92:93], 0, v[158:159]
	global_load_lds_dwordx4 v[206:207], off
	v_lshl_add_u64 v[206:207], s[12:13], 0, v[160:161]
	s_add_i32 m0, vcc_lo, 0x2000
	s_nop 0
	global_load_lds_dwordx4 v[206:207], off
	v_lshl_add_u64 v[206:207], s[92:93], 0, v[156:157]
	s_mov_b32 m0, s79
	s_nop 0
	global_load_lds_dwordx4 v[206:207], off
	s_mov_b32 m0, s85
	s_nop 0
	global_load_lds_dwordx4 v[224:225], off
	s_waitcnt vmcnt(8)
	s_waitcnt lgkmcnt(0)
	s_barrier
; #define PG8_STAGE(bufoff, gbase, voff) do { _Pragma("unroll") for (int _i = 0; _i < 2; ++_i) \
;         __builtin_amdgcn_global_load_lds((const unsigned*)((const char*)(gbase) + (voff)[_i]), (LAS unsigned*)(lds + (bufoff) + ldsw + _i * 8192), 16, 0, 0); } while (0)
; #define PG8_LDA(dst, b, h) do { _Pragma("unroll") for (int m = 0; m < 4; ++m) _Pragma("unroll") for (int k = 0; k < 2; ++k) dst[m][k] = *(const LAS bf16x8*)(lds + PG8_SA(b, h) + aoff + m * 2048 + k * 1024); } while (0)
; #define PG8_LDB(dst, b, h) do { _Pragma("unroll") for (int n = 0; n < 2; ++n) _Pragma("unroll") for (int k = 0; k < 2; ++k) dst[n][k] = *(const LAS bf16x8*)(lds + PG8_SB(b, h) + boff + n * 2048 + k * 1024); } while (0)
; #define PG8_MMA(ai, bj, At, Bt) do { __builtin_amdgcn_s_setprio(1); _Pragma("unroll") for (int m = 0; m < 4; ++m) _Pragma("unroll") for (int n = 0; n < 2; ++n) _Pragma("unroll") for (int k = 0; k < 2; ++k) \
;         acc[ai][bj][m][n] = __builtin_amdgcn_mfma_f32_16x16x32_bf16(Bt[n][k], At[m][k], acc[ai][bj][m][n], 0, 0, 0); __builtin_amdgcn_s_setprio(0); } while (0)
; #define PG8_WAIT_V(n) asm volatile("s_waitcnt vmcnt(" #n ")" ::: "memory")
; #define PG8_WAIT_L(n) asm volatile("s_waitcnt lgkmcnt(" #n ")" ::: "memory")
; #define PG8_BAR __builtin_amdgcn_s_barrier()
; #define PG8_SCHED __builtin_amdgcn_sched_barrier(0)
; template <class Epi, class Sched>
; __device__ __forceinline__ void gemm_phase(LAS unsigned char* lds, const Gemm g, const Sched& S, const Epi& E, const int tid) {
;     ...
;             PG8_WAIT_V(8); PG8_WAIT_L(0); PG8_BAR; PG8_MMA(0, 0, At, B0); PG8_MMA(0, 1, At, B1); PG8_BAR; PG8_SCHED;
;             PG8_LDA(At, 0, 1); PG8_STAGE(PG8_SB(0, 0), b2, voffB); PG8_STAGE(PG8_SB(0, 1), b2 + hstepB, voffB); PG8_STAGE(PG8_SA(0, 0), a2, voffA);
;             PG8_WAIT_V(8); PG8_WAIT_L(0); PG8_BAR; PG8_MMA(1, 0, At, B0); PG8_MMA(1, 1, At, B1); PG8_BAR; PG8_SCHED;
;             PG8_LDB(B0, 1, 0); PG8_LDB(B1, 1, 1); PG8_SCHED; PG8_LDA(At, 1, 0); PG8_STAGE(PG8_SA(0, 1), a2 + hstepA, voffA);
;             PG8_WAIT_V(8); PG8_WAIT_L(0); PG8_BAR; PG8_MMA(0, 0, At, B0); PG8_MMA(0, 1, At, B1); PG8_BAR; PG8_SCHED;
	v_mfma_f32_16x16x32_bf16 v[64:67], v[136:139], v[202:205], v[64:67]
	v_mfma_f32_16x16x32_bf16 v[60:63], v[178:181], v[202:205], v[60:63]
	v_mfma_f32_16x16x32_bf16 v[56:59], v[136:139], v[220:223], v[56:59]
	v_mfma_f32_16x16x32_bf16 v[48:51], v[178:181], v[220:223], v[48:51]
	v_mfma_f32_16x16x32_bf16 v[32:35], v[136:139], v[238:241], v[32:35]
	v_mfma_f32_16x16x32_bf16 v[28:31], v[178:181], v[238:241], v[28:31]
	v_mfma_f32_16x16x32_bf16 v[20:23], v[136:139], v[246:249], v[20:23]
	v_mfma_f32_16x16x32_bf16 v[12:15], v[178:181], v[246:249], v[12:15]
	v_mfma_f32_16x16x32_bf16 v[64:67], v[174:177], v[210:213], v[64:67]
	v_mfma_f32_16x16x32_bf16 v[60:63], v[182:185], v[210:213], v[60:63]
	v_mfma_f32_16x16x32_bf16 v[56:59], v[174:177], v[234:237], v[56:59]
	v_mfma_f32_16x16x32_bf16 v[48:51], v[182:185], v[234:237], v[48:51]
	v_mfma_f32_16x16x32_bf16 v[32:35], v[174:177], v[242:245], v[32:35]
	v_mfma_f32_16x16x32_bf16 v[28:31], v[182:185], v[242:245], v[28:31]
	v_mfma_f32_16x16x32_bf16 v[20:23], v[174:177], v[250:253], v[20:23]
	v_mfma_f32_16x16x32_bf16 v[12:15], v[182:185], v[250:253], v[12:15]
	v_mfma_f32_16x16x32_bf16 v[52:55], v[186:189], v[202:205], v[52:55]
	v_mfma_f32_16x16x32_bf16 v[44:47], v[194:197], v[202:205], v[44:47]
	v_mfma_f32_16x16x32_bf16 v[40:43], v[186:189], v[220:223], v[40:43]
	v_mfma_f32_16x16x32_bf16 v[36:39], v[194:197], v[220:223], v[36:39]
	v_mfma_f32_16x16x32_bf16 v[24:27], v[186:189], v[238:241], v[24:27]
	v_mfma_f32_16x16x32_bf16 v[16:19], v[194:197], v[238:241], v[16:19]
	v_mfma_f32_16x16x32_bf16 v[8:11], v[186:189], v[246:249], v[8:11]
	v_mfma_f32_16x16x32_bf16 v[4:7], v[194:197], v[246:249], v[4:7]
	v_mfma_f32_16x16x32_bf16 v[52:55], v[190:193], v[210:213], v[52:55]
	v_mfma_f32_16x16x32_bf16 v[44:47], v[198:201], v[210:213], v[44:47]
	v_mfma_f32_16x16x32_bf16 v[40:43], v[190:193], v[234:237], v[40:43]
	v_mfma_f32_16x16x32_bf16 v[36:39], v[198:201], v[234:237], v[36:39]
	v_mfma_f32_16x16x32_bf16 v[24:27], v[190:193], v[242:245], v[24:27]
	v_mfma_f32_16x16x32_bf16 v[16:19], v[198:201], v[242:245], v[16:19]
	v_mfma_f32_16x16x32_bf16 v[8:11], v[190:193], v[250:253], v[8:11]
	v_mfma_f32_16x16x32_bf16 v[4:7], v[198:201], v[250:253], v[4:7]
	s_barrier
	s_add_i32 vcc_lo, 0, 0x18000
	v_add_u32_e32 v171, vcc_lo, v151
	s_add_i32 vcc_hi, 0, 0x1c000
	ds_read_b128 v[136:139], v171
	ds_read_b128 v[174:177], v171 offset:1024
	ds_read_b128 v[178:181], v171 offset:2048
	ds_read_b128 v[182:185], v171 offset:3072
	v_add_u32_e32 v171, vcc_hi, v151
	ds_read_b128 v[186:189], v171
	ds_read_b128 v[190:193], v171 offset:1024
	ds_read_b128 v[194:197], v171 offset:2048
	ds_read_b128 v[198:201], v171 offset:3072
	s_add_u32 s12, s92, 0x40000
	s_addc_u32 s13, s93, 0
	s_mov_b32 m0, s86
	v_lshl_add_u64 v[226:227], s[12:13], 0, v[156:157]
	ds_read_b128 v[202:205], v153 offset:32768
	ds_read_b128 v[210:213], v153 offset:33792
	ds_read_b128 v[220:223], v153 offset:34816
	ds_read_b128 v[234:237], v153 offset:35840
	ds_read_b128 v[238:241], v153 offset:36864
	ds_read_b128 v[242:245], v153 offset:37888
	ds_read_b128 v[246:249], v153 offset:38912
	ds_read_b128 v[250:253], v153 offset:39936
	global_load_lds_dwordx4 v[226:227], off
	v_lshl_add_u64 v[226:227], s[12:13], 0, v[158:159]
	s_mov_b32 m0, s87
	s_nop 0
	global_load_lds_dwordx4 v[226:227], off
	s_waitcnt vmcnt(8)
	s_waitcnt lgkmcnt(0)
	s_barrier
	v_mfma_f32_16x16x32_bf16 v[128:131], v[136:139], v[202:205], v[128:131]
	v_mfma_f32_16x16x32_bf16 v[124:127], v[178:181], v[202:205], v[124:127]
	v_mfma_f32_16x16x32_bf16 v[120:123], v[136:139], v[220:223], v[120:123]
	v_mfma_f32_16x16x32_bf16 v[112:115], v[178:181], v[220:223], v[112:115]
	v_mfma_f32_16x16x32_bf16 v[96:99], v[136:139], v[238:241], v[96:99]
	v_mfma_f32_16x16x32_bf16 v[92:95], v[178:181], v[238:241], v[92:95]
	v_mfma_f32_16x16x32_bf16 v[88:91], v[136:139], v[246:249], v[88:91]
	v_mfma_f32_16x16x32_bf16 v[80:83], v[178:181], v[246:249], v[80:83]
	v_mfma_f32_16x16x32_bf16 v[128:131], v[174:177], v[210:213], v[128:131]
	v_mfma_f32_16x16x32_bf16 v[124:127], v[182:185], v[210:213], v[124:127]
	v_mfma_f32_16x16x32_bf16 v[120:123], v[174:177], v[234:237], v[120:123]
	v_mfma_f32_16x16x32_bf16 v[112:115], v[182:185], v[234:237], v[112:115]
	v_mfma_f32_16x16x32_bf16 v[96:99], v[174:177], v[242:245], v[96:99]
	v_mfma_f32_16x16x32_bf16 v[92:95], v[182:185], v[242:245], v[92:95]
	v_mfma_f32_16x16x32_bf16 v[88:91], v[174:177], v[250:253], v[88:91]
	v_mfma_f32_16x16x32_bf16 v[80:83], v[182:185], v[250:253], v[80:83]
	v_mfma_f32_16x16x32_bf16 v[116:119], v[186:189], v[202:205], v[116:119]
	v_mfma_f32_16x16x32_bf16 v[108:111], v[194:197], v[202:205], v[108:111]
	v_mfma_f32_16x16x32_bf16 v[104:107], v[186:189], v[220:223], v[104:107]
	v_mfma_f32_16x16x32_bf16 v[100:103], v[194:197], v[220:223], v[100:103]
	v_mfma_f32_16x16x32_bf16 v[84:87], v[186:189], v[238:241], v[84:87]
	v_mfma_f32_16x16x32_bf16 v[76:79], v[194:197], v[238:241], v[76:79]
	v_mfma_f32_16x16x32_bf16 v[72:75], v[186:189], v[246:249], v[72:75]
	v_mfma_f32_16x16x32_bf16 v[68:71], v[194:197], v[246:249], v[68:71]
	v_mfma_f32_16x16x32_bf16 v[116:119], v[190:193], v[210:213], v[116:119]
	v_mfma_f32_16x16x32_bf16 v[108:111], v[198:201], v[210:213], v[108:111]
	v_mfma_f32_16x16x32_bf16 v[104:107], v[190:193], v[234:237], v[104:107]
	v_mfma_f32_16x16x32_bf16 v[100:103], v[198:201], v[234:237], v[100:103]
	v_mfma_f32_16x16x32_bf16 v[84:87], v[190:193], v[242:245], v[84:87]
	v_mfma_f32_16x16x32_bf16 v[76:79], v[198:201], v[242:245], v[76:79]
	v_mfma_f32_16x16x32_bf16 v[72:75], v[190:193], v[250:253], v[72:75]
	v_mfma_f32_16x16x32_bf16 v[68:71], v[198:201], v[250:253], v[68:71]
	s_barrier
; #define PG8_STAGE(bufoff, gbase, voff) do { _Pragma("unroll") for (int _i = 0; _i < 2; ++_i) \
;         __builtin_amdgcn_global_load_lds((const unsigned*)((const char*)(gbase) + (voff)[_i]), (LAS unsigned*)(lds + (bufoff) + ldsw + _i * 8192), 16, 0, 0); } while (0)
; #define PG8_LDA(dst, b, h) do { _Pragma("unroll") for (int m = 0; m < 4; ++m) _Pragma("unroll") for (int k = 0; k < 2; ++k) dst[m][k] = *(const LAS bf16x8*)(lds + PG8_SA(b, h) + aoff + m * 2048 + k * 1024); } while (0)
; #define PG8_MMA(ai, bj, At, Bt) do { __builtin_amdgcn_s_setprio(1); _Pragma("unroll") for (int m = 0; m < 4; ++m) _Pragma("unroll") for (int n = 0; n < 2; ++n) _Pragma("unroll") for (int k = 0; k < 2; ++k) \
;         acc[ai][bj][m][n] = __builtin_amdgcn_mfma_f32_16x16x32_bf16(Bt[n][k], At[m][k], acc[ai][bj][m][n], 0, 0, 0); __builtin_amdgcn_s_setprio(0); } while (0)
; #define PG8_WAIT_V(n) asm volatile("s_waitcnt vmcnt(" #n ")" ::: "memory")
; #define PG8_WAIT_L(n) asm volatile("s_waitcnt lgkmcnt(" #n ")" ::: "memory")
; #define PG8_BAR __builtin_amdgcn_s_barrier()
; #define PG8_SCHED __builtin_amdgcn_sched_barrier(0)
; template <class Epi, class Sched>
; __device__ __forceinline__ void gemm_phase(LAS unsigned char* lds, const Gemm g, const Sched& S, const Epi& E, const int tid) {
;     ...
;             PG8_LDA(At, 1, 1); PG8_STAGE(PG8_SB(1, 0), b3, voffB); PG8_STAGE(PG8_SB(1, 1), b3 + hstepB, voffB); PG8_STAGE(PG8_SA(1, 0), a3, voffA);
;             PG8_WAIT_V(8); PG8_WAIT_L(0); PG8_BAR; PG8_MMA(1, 0, At, B0); PG8_MMA(1, 1, At, B1); PG8_BAR; PG8_SCHED;
;         }
;         if (wr == 0) PG8_BAR;
	s_add_i32 s12, vcc_lo, s59
	v_lshl_add_u64 v[154:155], v[154:155], 0, s[28:29]
	s_mov_b32 m0, s12
	ds_read_b128 v[202:205], v153 offset:49152
	ds_read_b128 v[210:213], v153 offset:50176
	ds_read_b128 v[220:223], v153 offset:51200
	ds_read_b128 v[234:237], v153 offset:52224
	ds_read_b128 v[238:241], v153 offset:53248
	ds_read_b128 v[242:245], v153 offset:54272
	ds_read_b128 v[246:249], v153 offset:55296
	ds_read_b128 v[250:253], v153 offset:56320
	global_load_lds_dwordx4 v[154:155], off
	s_add_i32 m0, s12, 0x2000
	s_add_u32 s12, s90, 0x40080
	v_lshl_add_u64 v[154:155], v[162:163], 0, s[28:29]
	s_addc_u32 s13, s91, 0
	s_add_i32 s90, vcc_hi, s59
	global_load_lds_dwordx4 v[154:155], off
	v_lshl_add_u64 v[154:155], s[12:13], 0, v[164:165]
	s_mov_b32 m0, s90
	s_nop 0
	global_load_lds_dwordx4 v[154:155], off
	v_lshl_add_u64 v[154:155], s[12:13], 0, v[160:161]
	s_add_i32 m0, s90, 0x2000
	s_nop 0
	global_load_lds_dwordx4 v[154:155], off
	v_lshl_add_u64 v[154:155], v[206:207], 0, s[28:29]
	s_mov_b32 m0, s88
	s_nop 0
	global_load_lds_dwordx4 v[154:155], off
	v_lshl_add_u64 v[154:155], v[224:225], 0, s[28:29]
	s_mov_b32 m0, s89
	s_nop 0
	global_load_lds_dwordx4 v[154:155], off
	s_waitcnt vmcnt(8)
	s_waitcnt lgkmcnt(0)
	s_barrier
	v_mfma_f32_16x16x32_bf16 v[64:67], v[136:139], v[202:205], v[64:67]
	v_mfma_f32_16x16x32_bf16 v[60:63], v[178:181], v[202:205], v[60:63]
	v_mfma_f32_16x16x32_bf16 v[56:59], v[136:139], v[220:223], v[56:59]
	v_mfma_f32_16x16x32_bf16 v[48:51], v[178:181], v[220:223], v[48:51]
	v_mfma_f32_16x16x32_bf16 v[32:35], v[136:139], v[238:241], v[32:35]
	v_mfma_f32_16x16x32_bf16 v[28:31], v[178:181], v[238:241], v[28:31]
	v_mfma_f32_16x16x32_bf16 v[20:23], v[136:139], v[246:249], v[20:23]
	v_mfma_f32_16x16x32_bf16 v[12:15], v[178:181], v[246:249], v[12:15]
	v_mfma_f32_16x16x32_bf16 v[64:67], v[174:177], v[210:213], v[64:67]
	v_mfma_f32_16x16x32_bf16 v[60:63], v[182:185], v[210:213], v[60:63]
	v_mfma_f32_16x16x32_bf16 v[56:59], v[174:177], v[234:237], v[56:59]
	v_mfma_f32_16x16x32_bf16 v[48:51], v[182:185], v[234:237], v[48:51]
	v_mfma_f32_16x16x32_bf16 v[32:35], v[174:177], v[242:245], v[32:35]
	v_mfma_f32_16x16x32_bf16 v[28:31], v[182:185], v[242:245], v[28:31]
	v_mfma_f32_16x16x32_bf16 v[20:23], v[174:177], v[250:253], v[20:23]
	v_mfma_f32_16x16x32_bf16 v[12:15], v[182:185], v[250:253], v[12:15]
	v_mfma_f32_16x16x32_bf16 v[52:55], v[186:189], v[202:205], v[52:55]
	v_mfma_f32_16x16x32_bf16 v[44:47], v[194:197], v[202:205], v[44:47]
	v_mfma_f32_16x16x32_bf16 v[40:43], v[186:189], v[220:223], v[40:43]
	v_mfma_f32_16x16x32_bf16 v[36:39], v[194:197], v[220:223], v[36:39]
	v_mfma_f32_16x16x32_bf16 v[24:27], v[186:189], v[238:241], v[24:27]
	v_mfma_f32_16x16x32_bf16 v[16:19], v[194:197], v[238:241], v[16:19]
	v_mfma_f32_16x16x32_bf16 v[8:11], v[186:189], v[246:249], v[8:11]
	v_mfma_f32_16x16x32_bf16 v[4:7], v[194:197], v[246:249], v[4:7]
	v_mfma_f32_16x16x32_bf16 v[52:55], v[190:193], v[210:213], v[52:55]
	v_mfma_f32_16x16x32_bf16 v[44:47], v[198:201], v[210:213], v[44:47]
	v_mfma_f32_16x16x32_bf16 v[40:43], v[190:193], v[234:237], v[40:43]
	v_mfma_f32_16x16x32_bf16 v[36:39], v[198:201], v[234:237], v[36:39]
	v_mfma_f32_16x16x32_bf16 v[24:27], v[190:193], v[242:245], v[24:27]
	v_mfma_f32_16x16x32_bf16 v[16:19], v[198:201], v[242:245], v[16:19]
	v_mfma_f32_16x16x32_bf16 v[8:11], v[190:193], v[250:253], v[8:11]
	v_mfma_f32_16x16x32_bf16 v[4:7], v[198:201], v[250:253], v[4:7]
	s_barrier
	s_add_i32 s97, s97, 2
	s_add_u32 s54, s54, 0x100
	s_addc_u32 s55, s55, 0
	s_add_u32 s47, s47, 0x100
	s_addc_u32 s96, s96, 0
	s_cmp_gt_u32 s97, 13
	s_cbranch_scc0 .LBB0_308
	s_and_b64 vcc, exec, s[20:21]
	s_cbranch_vccz .LBB0_311
	s_barrier

; #define PG8_STAGE(bufoff, gbase, voff) do { _Pragma("unroll") for (int _i = 0; _i < 2; ++_i) \
;         __builtin_amdgcn_global_load_lds((const unsigned*)((const char*)(gbase) + (voff)[_i]), (LAS unsigned*)(lds + (bufoff) + ldsw + _i * 8192), 16, 0, 0); } while (0)
; #define PG8_LDA(dst, b, h) do { _Pragma("unroll") for (int m = 0; m < 4; ++m) _Pragma("unroll") for (int k = 0; k < 2; ++k) dst[m][k] = *(const LAS bf16x8*)(lds + PG8_SA(b, h) + aoff + m * 2048 + k * 1024); } while (0)
; #define PG8_LDB(dst, b, h) do { _Pragma("unroll") for (int n = 0; n < 2; ++n) _Pragma("unroll") for (int k = 0; k < 2; ++k) dst[n][k] = *(const LAS bf16x8*)(lds + PG8_SB(b, h) + boff + n * 2048 + k * 1024); } while (0)
; #define PG8_MMA(ai, bj, At, Bt) do { __builtin_amdgcn_s_setprio(1); _Pragma("unroll") for (int m = 0; m < 4; ++m) _Pragma("unroll") for (int n = 0; n < 2; ++n) _Pragma("unroll") for (int k = 0; k < 2; ++k) \
;         acc[ai][bj][m][n] = __builtin_amdgcn_mfma_f32_16x16x32_bf16(Bt[n][k], At[m][k], acc[ai][bj][m][n], 0, 0, 0); __builtin_amdgcn_s_setprio(0); } while (0)
; #define PG8_WAIT_V(n) asm volatile("s_waitcnt vmcnt(" #n ")" ::: "memory")
; #define PG8_WAIT_L(n) asm volatile("s_waitcnt lgkmcnt(" #n ")" ::: "memory")
; #define PG8_BAR __builtin_amdgcn_s_barrier()
; #define PG8_SCHED __builtin_amdgcn_sched_barrier(0)
; template <class Epi, class Sched>
; __device__ __forceinline__ void gemm_phase(LAS unsigned char* lds, const Gemm g, const Sched& S, const Epi& E, const int tid) {
;     ...
;         for (int t = 0; t < nt; t += 2) {
;             const bool last = (t == nt - 2);
;             const char* a1 = cA + (size_t)(t + 1) * kstep;
;             const char* a2 = last ? nA : cA + (size_t)(t + 2) * kstep; const char* b2 = last ? nB : cB + (size_t)(t + 2) * kstep;
;             const char* a3 = a2 + kstep; const char* b3 = b2 + kstep;
;             PG8_LDB(B0, 0, 0); PG8_LDB(B1, 0, 1); PG8_SCHED; PG8_LDA(At, 0, 0); PG8_STAGE(PG8_SA(1, 1), a1 + hstepA, voffA);
;             PG8_WAIT_V(8); PG8_WAIT_L(0); PG8_BAR; PG8_MMA(0, 0, At, B0); PG8_MMA(0, 1, At, B1); PG8_BAR; PG8_SCHED;
;             PG8_LDA(At, 0, 1); PG8_STAGE(PG8_SB(0, 0), b2, voffB); PG8_STAGE(PG8_SB(0, 1), b2 + hstepB, voffB); PG8_STAGE(PG8_SA(0, 0), a2, voffA);
;             PG8_WAIT_V(8); PG8_WAIT_L(0); PG8_BAR; PG8_MMA(1, 0, At, B0); PG8_MMA(1, 1, At, B1); PG8_BAR; PG8_SCHED;
.LBB0_332:
	s_add_u32 s12, s54, 0xfffc0080
	s_addc_u32 s13, s55, -1
	s_add_i32 vcc_lo, 0, 0x10000
	s_cmp_eq_u32 s97, 12
	s_cselect_b32 s93, s16, s13
	s_cselect_b32 s92, s17, s12
	s_cselect_b32 s91, s31, s96
	s_cselect_b32 s90, s39, s47
	s_add_i32 vcc_hi, 0, 0x14000
	v_add_u32_e32 v144, vcc_lo, v178
	v_add_u32_e32 v176, vcc_hi, v178
	ds_read_b128 v[132:135], v144
	ds_read_b128 v[136:139], v144 offset:1024
	ds_read_b128 v[140:143], v144 offset:2048
	ds_read_b128 v[144:147], v144 offset:3072
	ds_read_b128 v[148:151], v176
	ds_read_b128 v[152:155], v176 offset:1024
	ds_read_b128 v[182:185], v176 offset:2048
	ds_read_b128 v[186:189], v176 offset:3072
	v_lshl_add_u64 v[176:177], s[54:55], 0, v[162:163]
	s_add_i32 m0, s79, 0xc000
	ds_read_b128 v[190:193], v180
	ds_read_b128 v[194:197], v180 offset:1024
	ds_read_b128 v[198:201], v180 offset:2048
	ds_read_b128 v[202:205], v180 offset:3072
	ds_read_b128 v[210:213], v180 offset:4096
	ds_read_b128 v[220:223], v180 offset:5120
	ds_read_b128 v[234:237], v180 offset:6144
	ds_read_b128 v[238:241], v180 offset:7168
	global_load_lds_dwordx4 v[176:177], off
	v_lshl_add_u64 v[176:177], s[54:55], 0, v[174:175]
	s_add_i32 m0, s79, 0xe000
	s_nop 0
	global_load_lds_dwordx4 v[176:177], off
	s_waitcnt vmcnt(8)
	s_waitcnt lgkmcnt(0)
	s_barrier
	v_mfma_f32_16x16x32_bf16 v[128:131], v[132:135], v[190:193], v[128:131]
	v_mfma_f32_16x16x32_bf16 v[124:127], v[140:143], v[190:193], v[124:127]
	v_mfma_f32_16x16x32_bf16 v[112:115], v[132:135], v[198:201], v[112:115]
	v_mfma_f32_16x16x32_bf16 v[108:111], v[140:143], v[198:201], v[108:111]
	v_mfma_f32_16x16x32_bf16 v[96:99], v[132:135], v[210:213], v[96:99]
	v_mfma_f32_16x16x32_bf16 v[92:95], v[140:143], v[210:213], v[92:95]
	v_mfma_f32_16x16x32_bf16 v[80:83], v[132:135], v[234:237], v[80:83]
	v_mfma_f32_16x16x32_bf16 v[76:79], v[140:143], v[234:237], v[76:79]
	v_mfma_f32_16x16x32_bf16 v[128:131], v[136:139], v[194:197], v[128:131]
	v_mfma_f32_16x16x32_bf16 v[124:127], v[144:147], v[194:197], v[124:127]
	v_mfma_f32_16x16x32_bf16 v[112:115], v[136:139], v[202:205], v[112:115]
	v_mfma_f32_16x16x32_bf16 v[108:111], v[144:147], v[202:205], v[108:111]
	v_mfma_f32_16x16x32_bf16 v[96:99], v[136:139], v[220:223], v[96:99]
	v_mfma_f32_16x16x32_bf16 v[92:95], v[144:147], v[220:223], v[92:95]
	v_mfma_f32_16x16x32_bf16 v[80:83], v[136:139], v[238:241], v[80:83]
	v_mfma_f32_16x16x32_bf16 v[76:79], v[144:147], v[238:241], v[76:79]
	v_mfma_f32_16x16x32_bf16 v[120:123], v[148:151], v[190:193], v[120:123]
	v_mfma_f32_16x16x32_bf16 v[116:119], v[182:185], v[190:193], v[116:119]
	v_mfma_f32_16x16x32_bf16 v[104:107], v[148:151], v[198:201], v[104:107]
	v_mfma_f32_16x16x32_bf16 v[100:103], v[182:185], v[198:201], v[100:103]
	v_mfma_f32_16x16x32_bf16 v[88:91], v[148:151], v[210:213], v[88:91]
	v_mfma_f32_16x16x32_bf16 v[84:87], v[182:185], v[210:213], v[84:87]
	v_mfma_f32_16x16x32_bf16 v[72:75], v[148:151], v[234:237], v[72:75]
	v_mfma_f32_16x16x32_bf16 v[68:71], v[182:185], v[234:237], v[68:71]
	v_mfma_f32_16x16x32_bf16 v[120:123], v[152:155], v[194:197], v[120:123]
	v_mfma_f32_16x16x32_bf16 v[116:119], v[186:189], v[194:197], v[116:119]
	v_mfma_f32_16x16x32_bf16 v[104:107], v[152:155], v[202:205], v[104:107]
	v_mfma_f32_16x16x32_bf16 v[100:103], v[186:189], v[202:205], v[100:103]
	v_mfma_f32_16x16x32_bf16 v[88:91], v[152:155], v[220:223], v[88:91]
	v_mfma_f32_16x16x32_bf16 v[84:87], v[186:189], v[220:223], v[84:87]
	v_mfma_f32_16x16x32_bf16 v[72:75], v[152:155], v[238:241], v[72:75]
	v_mfma_f32_16x16x32_bf16 v[68:71], v[186:189], v[238:241], v[68:71]
	s_barrier
	s_add_i32 s12, vcc_lo, s59
	v_lshl_add_u64 v[176:177], s[90:91], 0, v[164:165]
	s_mov_b32 m0, s12
	ds_read_b128 v[190:193], v180 offset:16384
	ds_read_b128 v[194:197], v180 offset:17408
	ds_read_b128 v[198:201], v180 offset:18432
	ds_read_b128 v[202:205], v180 offset:19456
	ds_read_b128 v[210:213], v180 offset:20480
	ds_read_b128 v[220:223], v180 offset:21504
	ds_read_b128 v[234:237], v180 offset:22528
	ds_read_b128 v[238:241], v180 offset:23552
	global_load_lds_dwordx4 v[176:177], off
	s_add_i32 m0, s12, 0x2000
	s_add_u32 s12, s90, 0x40000
	v_lshl_add_u64 v[206:207], s[90:91], 0, v[160:161]
	s_addc_u32 s13, s91, 0
	s_add_i32 vcc_lo, vcc_hi, s59
	global_load_lds_dwordx4 v[206:207], off
	v_lshl_add_u64 v[224:225], s[12:13], 0, v[164:165]
	s_mov_b32 m0, vcc_lo
	v_lshl_add_u64 v[226:227], s[92:93], 0, v[158:159]
	global_load_lds_dwordx4 v[224:225], off
	v_lshl_add_u64 v[224:225], s[12:13], 0, v[160:161]
	s_add_i32 m0, vcc_lo, 0x2000
	s_nop 0
	global_load_lds_dwordx4 v[224:225], off
	v_lshl_add_u64 v[224:225], s[92:93], 0, v[156:157]
	s_mov_b32 m0, s79
	s_nop 0
	global_load_lds_dwordx4 v[224:225], off
	s_mov_b32 m0, s85
	s_nop 0
	global_load_lds_dwordx4 v[226:227], off
	s_waitcnt vmcnt(8)
	s_waitcnt lgkmcnt(0)
	s_barrier
; #define PG8_STAGE(bufoff, gbase, voff) do { _Pragma("unroll") for (int _i = 0; _i < 2; ++_i) \
;         __builtin_amdgcn_global_load_lds((const unsigned*)((const char*)(gbase) + (voff)[_i]), (LAS unsigned*)(lds + (bufoff) + ldsw + _i * 8192), 16, 0, 0); } while (0)
; #define PG8_LDA(dst, b, h) do { _Pragma("unroll") for (int m = 0; m < 4; ++m) _Pragma("unroll") for (int k = 0; k < 2; ++k) dst[m][k] = *(const LAS bf16x8*)(lds + PG8_SA(b, h) + aoff + m * 2048 + k * 1024); } while (0)
; #define PG8_LDB(dst, b, h) do { _Pragma("unroll") for (int n = 0; n < 2; ++n) _Pragma("unroll") for (int k = 0; k < 2; ++k) dst[n][k] = *(const LAS bf16x8*)(lds + PG8_SB(b, h) + boff + n * 2048 + k * 1024); } while (0)
; #define PG8_MMA(ai, bj, At, Bt) do { __builtin_amdgcn_s_setprio(1); _Pragma("unroll") for (int m = 0; m < 4; ++m) _Pragma("unroll") for (int n = 0; n < 2; ++n) _Pragma("unroll") for (int k = 0; k < 2; ++k) \
;         acc[ai][bj][m][n] = __builtin_amdgcn_mfma_f32_16x16x32_bf16(Bt[n][k], At[m][k], acc[ai][bj][m][n], 0, 0, 0); __builtin_amdgcn_s_setprio(0); } while (0)
; #define PG8_WAIT_V(n) asm volatile("s_waitcnt vmcnt(" #n ")" ::: "memory")
; #define PG8_WAIT_L(n) asm volatile("s_waitcnt lgkmcnt(" #n ")" ::: "memory")
; #define PG8_BAR __builtin_amdgcn_s_barrier()
; #define PG8_SCHED __builtin_amdgcn_sched_barrier(0)
; template <class Epi, class Sched>
; __device__ __forceinline__ void gemm_phase(LAS unsigned char* lds, const Gemm g, const Sched& S, const Epi& E, const int tid) {
;     ...
;             PG8_WAIT_V(8); PG8_WAIT_L(0); PG8_BAR; PG8_MMA(0, 0, At, B0); PG8_MMA(0, 1, At, B1); PG8_BAR; PG8_SCHED;
;             PG8_LDA(At, 0, 1); PG8_STAGE(PG8_SB(0, 0), b2, voffB); PG8_STAGE(PG8_SB(0, 1), b2 + hstepB, voffB); PG8_STAGE(PG8_SA(0, 0), a2, voffA);
;             PG8_WAIT_V(8); PG8_WAIT_L(0); PG8_BAR; PG8_MMA(1, 0, At, B0); PG8_MMA(1, 1, At, B1); PG8_BAR; PG8_SCHED;
;             PG8_LDB(B0, 1, 0); PG8_LDB(B1, 1, 1); PG8_SCHED; PG8_LDA(At, 1, 0); PG8_STAGE(PG8_SA(0, 1), a2 + hstepA, voffA);
;             PG8_WAIT_V(8); PG8_WAIT_L(0); PG8_BAR; PG8_MMA(0, 0, At, B0); PG8_MMA(0, 1, At, B1); PG8_BAR; PG8_SCHED;
	v_mfma_f32_16x16x32_bf16 v[64:67], v[132:135], v[190:193], v[64:67]
	v_mfma_f32_16x16x32_bf16 v[60:63], v[140:143], v[190:193], v[60:63]
	v_mfma_f32_16x16x32_bf16 v[48:51], v[132:135], v[198:201], v[48:51]
	v_mfma_f32_16x16x32_bf16 v[44:47], v[140:143], v[198:201], v[44:47]
	v_mfma_f32_16x16x32_bf16 v[32:35], v[132:135], v[210:213], v[32:35]
	v_mfma_f32_16x16x32_bf16 v[28:31], v[140:143], v[210:213], v[28:31]
	v_mfma_f32_16x16x32_bf16 v[16:19], v[132:135], v[234:237], v[16:19]
	v_mfma_f32_16x16x32_bf16 v[12:15], v[140:143], v[234:237], v[12:15]
	v_mfma_f32_16x16x32_bf16 v[64:67], v[136:139], v[194:197], v[64:67]
	v_mfma_f32_16x16x32_bf16 v[60:63], v[144:147], v[194:197], v[60:63]
	v_mfma_f32_16x16x32_bf16 v[48:51], v[136:139], v[202:205], v[48:51]
	v_mfma_f32_16x16x32_bf16 v[44:47], v[144:147], v[202:205], v[44:47]
	v_mfma_f32_16x16x32_bf16 v[32:35], v[136:139], v[220:223], v[32:35]
	v_mfma_f32_16x16x32_bf16 v[28:31], v[144:147], v[220:223], v[28:31]
	v_mfma_f32_16x16x32_bf16 v[16:19], v[136:139], v[238:241], v[16:19]
	v_mfma_f32_16x16x32_bf16 v[12:15], v[144:147], v[238:241], v[12:15]
	v_mfma_f32_16x16x32_bf16 v[56:59], v[148:151], v[190:193], v[56:59]
	v_mfma_f32_16x16x32_bf16 v[52:55], v[182:185], v[190:193], v[52:55]
	v_mfma_f32_16x16x32_bf16 v[40:43], v[148:151], v[198:201], v[40:43]
	v_mfma_f32_16x16x32_bf16 v[36:39], v[182:185], v[198:201], v[36:39]
	v_mfma_f32_16x16x32_bf16 v[24:27], v[148:151], v[210:213], v[24:27]
	v_mfma_f32_16x16x32_bf16 v[20:23], v[182:185], v[210:213], v[20:23]
	v_mfma_f32_16x16x32_bf16 v[8:11], v[148:151], v[234:237], v[8:11]
	v_mfma_f32_16x16x32_bf16 v[4:7], v[182:185], v[234:237], v[4:7]
	v_mfma_f32_16x16x32_bf16 v[56:59], v[152:155], v[194:197], v[56:59]
	v_mfma_f32_16x16x32_bf16 v[52:55], v[186:189], v[194:197], v[52:55]
	v_mfma_f32_16x16x32_bf16 v[40:43], v[152:155], v[202:205], v[40:43]
	v_mfma_f32_16x16x32_bf16 v[36:39], v[186:189], v[202:205], v[36:39]
	v_mfma_f32_16x16x32_bf16 v[24:27], v[152:155], v[220:223], v[24:27]
	v_mfma_f32_16x16x32_bf16 v[20:23], v[186:189], v[220:223], v[20:23]
	v_mfma_f32_16x16x32_bf16 v[8:11], v[152:155], v[238:241], v[8:11]
	v_mfma_f32_16x16x32_bf16 v[4:7], v[186:189], v[238:241], v[4:7]
	s_barrier
	s_add_i32 vcc_lo, 0, 0x18000
	s_add_i32 vcc_hi, 0, 0x1c000
	v_add_u32_e32 v144, vcc_lo, v178
	v_add_u32_e32 v181, vcc_hi, v178
	ds_read_b128 v[132:135], v144
	ds_read_b128 v[136:139], v144 offset:1024
	ds_read_b128 v[140:143], v144 offset:2048
	ds_read_b128 v[144:147], v144 offset:3072
	ds_read_b128 v[148:151], v181
	ds_read_b128 v[152:155], v181 offset:1024
	ds_read_b128 v[182:185], v181 offset:2048
	ds_read_b128 v[186:189], v181 offset:3072
	s_add_u32 s12, s92, 0x40000
	s_addc_u32 s13, s93, 0
	s_mov_b32 m0, s86
	v_lshl_add_u64 v[242:243], s[12:13], 0, v[156:157]
	ds_read_b128 v[190:193], v180 offset:32768
	ds_read_b128 v[194:197], v180 offset:33792
	ds_read_b128 v[198:201], v180 offset:34816
	ds_read_b128 v[202:205], v180 offset:35840
	ds_read_b128 v[210:213], v180 offset:36864
	ds_read_b128 v[220:223], v180 offset:37888
	ds_read_b128 v[234:237], v180 offset:38912
	ds_read_b128 v[238:241], v180 offset:39936
	global_load_lds_dwordx4 v[242:243], off
	v_lshl_add_u64 v[242:243], s[12:13], 0, v[158:159]
	s_mov_b32 m0, s87
	s_nop 0
	global_load_lds_dwordx4 v[242:243], off
	s_waitcnt vmcnt(8)
	s_waitcnt lgkmcnt(0)
	s_barrier
	v_mfma_f32_16x16x32_bf16 v[128:131], v[132:135], v[190:193], v[128:131]
	v_mfma_f32_16x16x32_bf16 v[124:127], v[140:143], v[190:193], v[124:127]
	v_mfma_f32_16x16x32_bf16 v[112:115], v[132:135], v[198:201], v[112:115]
	v_mfma_f32_16x16x32_bf16 v[108:111], v[140:143], v[198:201], v[108:111]
	v_mfma_f32_16x16x32_bf16 v[96:99], v[132:135], v[210:213], v[96:99]
	v_mfma_f32_16x16x32_bf16 v[92:95], v[140:143], v[210:213], v[92:95]
	v_mfma_f32_16x16x32_bf16 v[80:83], v[132:135], v[234:237], v[80:83]
	v_mfma_f32_16x16x32_bf16 v[76:79], v[140:143], v[234:237], v[76:79]
	v_mfma_f32_16x16x32_bf16 v[128:131], v[136:139], v[194:197], v[128:131]
	v_mfma_f32_16x16x32_bf16 v[124:127], v[144:147], v[194:197], v[124:127]
	v_mfma_f32_16x16x32_bf16 v[112:115], v[136:139], v[202:205], v[112:115]
	v_mfma_f32_16x16x32_bf16 v[108:111], v[144:147], v[202:205], v[108:111]
	v_mfma_f32_16x16x32_bf16 v[96:99], v[136:139], v[220:223], v[96:99]
	v_mfma_f32_16x16x32_bf16 v[92:95], v[144:147], v[220:223], v[92:95]
	v_mfma_f32_16x16x32_bf16 v[80:83], v[136:139], v[238:241], v[80:83]
	v_mfma_f32_16x16x32_bf16 v[76:79], v[144:147], v[238:241], v[76:79]
	v_mfma_f32_16x16x32_bf16 v[120:123], v[148:151], v[190:193], v[120:123]
	v_mfma_f32_16x16x32_bf16 v[116:119], v[182:185], v[190:193], v[116:119]
	v_mfma_f32_16x16x32_bf16 v[104:107], v[148:151], v[198:201], v[104:107]
	v_mfma_f32_16x16x32_bf16 v[100:103], v[182:185], v[198:201], v[100:103]
	v_mfma_f32_16x16x32_bf16 v[88:91], v[148:151], v[210:213], v[88:91]
	v_mfma_f32_16x16x32_bf16 v[84:87], v[182:185], v[210:213], v[84:87]
	v_mfma_f32_16x16x32_bf16 v[72:75], v[148:151], v[234:237], v[72:75]
	v_mfma_f32_16x16x32_bf16 v[68:71], v[182:185], v[234:237], v[68:71]
	v_mfma_f32_16x16x32_bf16 v[120:123], v[152:155], v[194:197], v[120:123]
	v_mfma_f32_16x16x32_bf16 v[116:119], v[186:189], v[194:197], v[116:119]
	v_mfma_f32_16x16x32_bf16 v[104:107], v[152:155], v[202:205], v[104:107]
	v_mfma_f32_16x16x32_bf16 v[100:103], v[186:189], v[202:205], v[100:103]
	v_mfma_f32_16x16x32_bf16 v[88:91], v[152:155], v[220:223], v[88:91]
	v_mfma_f32_16x16x32_bf16 v[84:87], v[186:189], v[220:223], v[84:87]
	v_mfma_f32_16x16x32_bf16 v[72:75], v[152:155], v[238:241], v[72:75]
	v_mfma_f32_16x16x32_bf16 v[68:71], v[186:189], v[238:241], v[68:71]
	s_barrier
; #define PG8_STAGE(bufoff, gbase, voff) do { _Pragma("unroll") for (int _i = 0; _i < 2; ++_i) \
;         __builtin_amdgcn_global_load_lds((const unsigned*)((const char*)(gbase) + (voff)[_i]), (LAS unsigned*)(lds + (bufoff) + ldsw + _i * 8192), 16, 0, 0); } while (0)
; #define PG8_LDA(dst, b, h) do { _Pragma("unroll") for (int m = 0; m < 4; ++m) _Pragma("unroll") for (int k = 0; k < 2; ++k) dst[m][k] = *(const LAS bf16x8*)(lds + PG8_SA(b, h) + aoff + m * 2048 + k * 1024); } while (0)
; #define PG8_MMA(ai, bj, At, Bt) do { __builtin_amdgcn_s_setprio(1); _Pragma("unroll") for (int m = 0; m < 4; ++m) _Pragma("unroll") for (int n = 0; n < 2; ++n) _Pragma("unroll") for (int k = 0; k < 2; ++k) \
;         acc[ai][bj][m][n] = __builtin_amdgcn_mfma_f32_16x16x32_bf16(Bt[n][k], At[m][k], acc[ai][bj][m][n], 0, 0, 0); __builtin_amdgcn_s_setprio(0); } while (0)
; #define PG8_WAIT_V(n) asm volatile("s_waitcnt vmcnt(" #n ")" ::: "memory")
; #define PG8_WAIT_L(n) asm volatile("s_waitcnt lgkmcnt(" #n ")" ::: "memory")
; #define PG8_BAR __builtin_amdgcn_s_barrier()
; #define PG8_SCHED __builtin_amdgcn_sched_barrier(0)
; template <class Epi, class Sched>
; __device__ __forceinline__ void gemm_phase(LAS unsigned char* lds, const Gemm g, const Sched& S, const Epi& E, const int tid) {
;     ...
;             PG8_LDA(At, 1, 1); PG8_STAGE(PG8_SB(1, 0), b3, voffB); PG8_STAGE(PG8_SB(1, 1), b3 + hstepB, voffB); PG8_STAGE(PG8_SA(1, 0), a3, voffA);
;             PG8_WAIT_V(8); PG8_WAIT_L(0); PG8_BAR; PG8_MMA(1, 0, At, B0); PG8_MMA(1, 1, At, B1); PG8_BAR; PG8_SCHED;
;         }
;         if (wr == 0) PG8_BAR;
	s_add_i32 s12, vcc_lo, s59
	v_lshl_add_u64 v[176:177], v[176:177], 0, s[28:29]
	s_mov_b32 m0, s12
	ds_read_b128 v[190:193], v180 offset:49152
	ds_read_b128 v[194:197], v180 offset:50176
	ds_read_b128 v[198:201], v180 offset:51200
	ds_read_b128 v[202:205], v180 offset:52224
	ds_read_b128 v[210:213], v180 offset:53248
	ds_read_b128 v[220:223], v180 offset:54272
	ds_read_b128 v[234:237], v180 offset:55296
	ds_read_b128 v[238:241], v180 offset:56320
	global_load_lds_dwordx4 v[176:177], off
	s_add_i32 m0, s12, 0x2000
	s_add_u32 s12, s90, 0x40080
	v_lshl_add_u64 v[176:177], v[206:207], 0, s[28:29]
	s_addc_u32 s13, s91, 0
	s_add_i32 s90, vcc_hi, s59
	global_load_lds_dwordx4 v[176:177], off
	v_lshl_add_u64 v[176:177], s[12:13], 0, v[164:165]
	s_mov_b32 m0, s90
	s_nop 0
	global_load_lds_dwordx4 v[176:177], off
	v_lshl_add_u64 v[176:177], s[12:13], 0, v[160:161]
	s_add_i32 m0, s90, 0x2000
	s_nop 0
	global_load_lds_dwordx4 v[176:177], off
	v_lshl_add_u64 v[176:177], v[224:225], 0, s[28:29]
	s_mov_b32 m0, s88
	s_nop 0
	global_load_lds_dwordx4 v[176:177], off
	v_lshl_add_u64 v[176:177], v[226:227], 0, s[28:29]
	s_mov_b32 m0, s89
	s_nop 0
	global_load_lds_dwordx4 v[176:177], off
	s_waitcnt vmcnt(8)
	s_waitcnt lgkmcnt(0)
	s_barrier
	v_mfma_f32_16x16x32_bf16 v[64:67], v[132:135], v[190:193], v[64:67]
	v_mfma_f32_16x16x32_bf16 v[60:63], v[140:143], v[190:193], v[60:63]
	v_mfma_f32_16x16x32_bf16 v[48:51], v[132:135], v[198:201], v[48:51]
	v_mfma_f32_16x16x32_bf16 v[44:47], v[140:143], v[198:201], v[44:47]
	v_mfma_f32_16x16x32_bf16 v[32:35], v[132:135], v[210:213], v[32:35]
	v_mfma_f32_16x16x32_bf16 v[28:31], v[140:143], v[210:213], v[28:31]
	v_mfma_f32_16x16x32_bf16 v[16:19], v[132:135], v[234:237], v[16:19]
	v_mfma_f32_16x16x32_bf16 v[12:15], v[140:143], v[234:237], v[12:15]
	v_mfma_f32_16x16x32_bf16 v[64:67], v[136:139], v[194:197], v[64:67]
	v_mfma_f32_16x16x32_bf16 v[60:63], v[144:147], v[194:197], v[60:63]
	v_mfma_f32_16x16x32_bf16 v[48:51], v[136:139], v[202:205], v[48:51]
	v_mfma_f32_16x16x32_bf16 v[44:47], v[144:147], v[202:205], v[44:47]
	v_mfma_f32_16x16x32_bf16 v[32:35], v[136:139], v[220:223], v[32:35]
	v_mfma_f32_16x16x32_bf16 v[28:31], v[144:147], v[220:223], v[28:31]
	v_mfma_f32_16x16x32_bf16 v[16:19], v[136:139], v[238:241], v[16:19]
	v_mfma_f32_16x16x32_bf16 v[12:15], v[144:147], v[238:241], v[12:15]
	v_mfma_f32_16x16x32_bf16 v[56:59], v[148:151], v[190:193], v[56:59]
	v_mfma_f32_16x16x32_bf16 v[52:55], v[182:185], v[190:193], v[52:55]
	v_mfma_f32_16x16x32_bf16 v[40:43], v[148:151], v[198:201], v[40:43]
	v_mfma_f32_16x16x32_bf16 v[36:39], v[182:185], v[198:201], v[36:39]
	v_mfma_f32_16x16x32_bf16 v[24:27], v[148:151], v[210:213], v[24:27]
	v_mfma_f32_16x16x32_bf16 v[20:23], v[182:185], v[210:213], v[20:23]
	v_mfma_f32_16x16x32_bf16 v[8:11], v[148:151], v[234:237], v[8:11]
	v_mfma_f32_16x16x32_bf16 v[4:7], v[182:185], v[234:237], v[4:7]
	v_mfma_f32_16x16x32_bf16 v[56:59], v[152:155], v[194:197], v[56:59]
	v_mfma_f32_16x16x32_bf16 v[52:55], v[186:189], v[194:197], v[52:55]
	v_mfma_f32_16x16x32_bf16 v[40:43], v[152:155], v[202:205], v[40:43]
	v_mfma_f32_16x16x32_bf16 v[36:39], v[186:189], v[202:205], v[36:39]
	v_mfma_f32_16x16x32_bf16 v[24:27], v[152:155], v[220:223], v[24:27]
	v_mfma_f32_16x16x32_bf16 v[20:23], v[186:189], v[220:223], v[20:23]
	v_mfma_f32_16x16x32_bf16 v[8:11], v[152:155], v[238:241], v[8:11]
	v_mfma_f32_16x16x32_bf16 v[4:7], v[186:189], v[238:241], v[4:7]
	s_barrier
	s_add_i32 s97, s97, 2
	s_add_u32 s54, s54, 0x100
	s_addc_u32 s55, s55, 0
	s_add_u32 s47, s47, 0x100
	s_addc_u32 s96, s96, 0
	s_cmp_gt_u32 s97, 13
	s_cbranch_scc0 .LBB0_332
	s_and_b64 vcc, exec, s[20:21]
	s_cbranch_vccz .LBB0_335
	s_barrier

; #define PG8_STAGE(bufoff, gbase, voff) do { _Pragma("unroll") for (int _i = 0; _i < 2; ++_i) \
;         __builtin_amdgcn_global_load_lds((const unsigned*)((const char*)(gbase) + (voff)[_i]), (LAS unsigned*)(lds + (bufoff) + ldsw + _i * 8192), 16, 0, 0); } while (0)
; #define PG8_LDA(dst, b, h) do { _Pragma("unroll") for (int m = 0; m < 4; ++m) _Pragma("unroll") for (int k = 0; k < 2; ++k) dst[m][k] = *(const LAS bf16x8*)(lds + PG8_SA(b, h) + aoff + m * 2048 + k * 1024); } while (0)
; #define PG8_LDB(dst, b, h) do { _Pragma("unroll") for (int n = 0; n < 2; ++n) _Pragma("unroll") for (int k = 0; k < 2; ++k) dst[n][k] = *(const LAS bf16x8*)(lds + PG8_SB(b, h) + boff + n * 2048 + k * 1024); } while (0)
; #define PG8_MMA(ai, bj, At, Bt) do { __builtin_amdgcn_s_setprio(1); _Pragma("unroll") for (int m = 0; m < 4; ++m) _Pragma("unroll") for (int n = 0; n < 2; ++n) _Pragma("unroll") for (int k = 0; k < 2; ++k) \
;         acc[ai][bj][m][n] = __builtin_amdgcn_mfma_f32_16x16x32_bf16(Bt[n][k], At[m][k], acc[ai][bj][m][n], 0, 0, 0); __builtin_amdgcn_s_setprio(0); } while (0)
; #define PG8_WAIT_V(n) asm volatile("s_waitcnt vmcnt(" #n ")" ::: "memory")
; #define PG8_WAIT_L(n) asm volatile("s_waitcnt lgkmcnt(" #n ")" ::: "memory")
; #define PG8_BAR __builtin_amdgcn_s_barrier()
; #define PG8_SCHED __builtin_amdgcn_sched_barrier(0)
; template <class Epi, class Sched>
; __device__ __forceinline__ void gemm_phase(LAS unsigned char* lds, const Gemm g, const Sched& S, const Epi& E, const int tid) {
;     ...
;         for (int t = 0; t < nt; t += 2) {
;             const bool last = (t == nt - 2);
;             const char* a1 = cA + (size_t)(t + 1) * kstep;
;             const char* a2 = last ? nA : cA + (size_t)(t + 2) * kstep; const char* b2 = last ? nB : cB + (size_t)(t + 2) * kstep;
;             const char* a3 = a2 + kstep; const char* b3 = b2 + kstep;
;             PG8_LDB(B0, 0, 0); PG8_LDB(B1, 0, 1); PG8_SCHED; PG8_LDA(At, 0, 0); PG8_STAGE(PG8_SA(1, 1), a1 + hstepA, voffA);
;             PG8_WAIT_V(8); PG8_WAIT_L(0); PG8_BAR; PG8_MMA(0, 0, At, B0); PG8_MMA(0, 1, At, B1); PG8_BAR; PG8_SCHED;
;             PG8_LDA(At, 0, 1); PG8_STAGE(PG8_SB(0, 0), b2, voffB); PG8_STAGE(PG8_SB(0, 1), b2 + hstepB, voffB); PG8_STAGE(PG8_SA(0, 0), a2, voffA);
;             PG8_WAIT_V(8); PG8_WAIT_L(0); PG8_BAR; PG8_MMA(1, 0, At, B0); PG8_MMA(1, 1, At, B1); PG8_BAR; PG8_SCHED;
.LBB0_589:
	s_add_u32 s54, s46, 0xfff80080
	s_addc_u32 s55, s47, -1
	s_add_i32 s88, 0, 0x10000
	s_cmp_eq_u32 s87, 28
	s_cselect_b32 s85, s0, s55
	s_cselect_b32 s84, s9, s54
	s_cselect_b32 s55, s11, s86
	s_cselect_b32 s54, s31, s39
	s_add_i32 s90, 0, 0x14000
	v_add_u32_e32 v154, s88, v163
	v_add_u32_e32 v175, s90, v163
	ds_read_b128 v[100:103], v154
	ds_read_b128 v[104:107], v154 offset:1024
	ds_read_b128 v[150:153], v154 offset:2048
	ds_read_b128 v[154:157], v154 offset:3072
	ds_read_b128 v[158:161], v175
	ds_read_b128 v[176:179], v175 offset:1024
	ds_read_b128 v[180:183], v175 offset:2048
	ds_read_b128 v[184:187], v175 offset:3072
	v_lshl_add_u64 v[210:211], s[46:47], 0, v[146:147]
	s_add_i32 m0, s5, 0xc000
	ds_read_b128 v[188:191], v174
	ds_read_b128 v[192:195], v174 offset:1024
	ds_read_b128 v[196:199], v174 offset:2048
	ds_read_b128 v[200:203], v174 offset:3072
	ds_read_b128 v[204:207], v174 offset:4096
	ds_read_b128 v[234:237], v174 offset:5120
	ds_read_b128 v[238:241], v174 offset:6144
	ds_read_b128 v[242:245], v174 offset:7168
	global_load_lds_dwordx4 v[210:211], off
	v_lshl_add_u64 v[210:211], s[46:47], 0, v[148:149]
	s_add_i32 m0, s5, 0xe000
	s_nop 0
	global_load_lds_dwordx4 v[210:211], off
	s_waitcnt vmcnt(8)
	s_waitcnt lgkmcnt(0)
	s_barrier
	v_mfma_f32_16x16x32_bf16 v[136:139], v[100:103], v[188:191], v[136:139]
	v_mfma_f32_16x16x32_bf16 v[132:135], v[150:153], v[188:191], v[132:135]
	v_mfma_f32_16x16x32_bf16 v[128:131], v[100:103], v[196:199], v[128:131]
	v_mfma_f32_16x16x32_bf16 v[124:127], v[150:153], v[196:199], v[124:127]
	v_mfma_f32_16x16x32_bf16 v[120:123], v[100:103], v[204:207], v[120:123]
	v_mfma_f32_16x16x32_bf16 v[116:119], v[150:153], v[204:207], v[116:119]
	v_mfma_f32_16x16x32_bf16 v[112:115], v[100:103], v[238:241], v[112:115]
	v_mfma_f32_16x16x32_bf16 v[108:111], v[150:153], v[238:241], v[108:111]
	v_mfma_f32_16x16x32_bf16 v[136:139], v[104:107], v[192:195], v[136:139]
	v_mfma_f32_16x16x32_bf16 v[132:135], v[154:157], v[192:195], v[132:135]
	v_mfma_f32_16x16x32_bf16 v[128:131], v[104:107], v[200:203], v[128:131]
	v_mfma_f32_16x16x32_bf16 v[124:127], v[154:157], v[200:203], v[124:127]
	v_mfma_f32_16x16x32_bf16 v[120:123], v[104:107], v[234:237], v[120:123]
	v_mfma_f32_16x16x32_bf16 v[116:119], v[154:157], v[234:237], v[116:119]
	v_mfma_f32_16x16x32_bf16 v[112:115], v[104:107], v[242:245], v[112:115]
	v_mfma_f32_16x16x32_bf16 v[108:111], v[154:157], v[242:245], v[108:111]
	v_mfma_f32_16x16x32_bf16 v[64:67], v[158:161], v[188:191], v[64:67]
	v_mfma_f32_16x16x32_bf16 v[60:63], v[180:183], v[188:191], v[60:63]
	v_mfma_f32_16x16x32_bf16 v[56:59], v[158:161], v[196:199], v[56:59]
	v_mfma_f32_16x16x32_bf16 v[52:55], v[180:183], v[196:199], v[52:55]
	v_mfma_f32_16x16x32_bf16 v[48:51], v[158:161], v[204:207], v[48:51]
	v_mfma_f32_16x16x32_bf16 v[44:47], v[180:183], v[204:207], v[44:47]
	v_mfma_f32_16x16x32_bf16 v[40:43], v[158:161], v[238:241], v[40:43]
	v_mfma_f32_16x16x32_bf16 v[36:39], v[180:183], v[238:241], v[36:39]
	v_mfma_f32_16x16x32_bf16 v[64:67], v[176:179], v[192:195], v[64:67]
	v_mfma_f32_16x16x32_bf16 v[60:63], v[184:187], v[192:195], v[60:63]
	v_mfma_f32_16x16x32_bf16 v[56:59], v[176:179], v[200:203], v[56:59]
	v_mfma_f32_16x16x32_bf16 v[52:55], v[184:187], v[200:203], v[52:55]
	v_mfma_f32_16x16x32_bf16 v[48:51], v[176:179], v[234:237], v[48:51]
	v_mfma_f32_16x16x32_bf16 v[44:47], v[184:187], v[234:237], v[44:47]
	v_mfma_f32_16x16x32_bf16 v[40:43], v[176:179], v[242:245], v[40:43]
	v_mfma_f32_16x16x32_bf16 v[36:39], v[184:187], v[242:245], v[36:39]
	s_barrier
	s_add_i32 s88, s88, s1
	v_lshl_add_u64 v[210:211], s[54:55], 0, v[164:165]
	s_mov_b32 m0, s88
	ds_read_b128 v[188:191], v174 offset:16384
	ds_read_b128 v[192:195], v174 offset:17408
	ds_read_b128 v[196:199], v174 offset:18432
	ds_read_b128 v[200:203], v174 offset:19456
	ds_read_b128 v[204:207], v174 offset:20480
	ds_read_b128 v[234:237], v174 offset:21504
	ds_read_b128 v[238:241], v174 offset:22528
	ds_read_b128 v[242:245], v174 offset:23552
	global_load_lds_dwordx4 v[210:211], off
	s_add_i32 m0, s88, 0x2000
	s_add_u32 s88, s54, 0x80000
	v_lshl_add_u64 v[212:213], s[54:55], 0, v[144:145]
	s_addc_u32 s89, s55, 0
	s_add_i32 s90, s90, s1
	global_load_lds_dwordx4 v[212:213], off
	v_lshl_add_u64 v[220:221], s[88:89], 0, v[164:165]
	s_mov_b32 m0, s90
	v_lshl_add_u64 v[222:223], s[84:85], 0, v[142:143]
	global_load_lds_dwordx4 v[220:221], off
	v_lshl_add_u64 v[220:221], s[88:89], 0, v[144:145]
	s_add_i32 m0, s90, 0x2000
	s_nop 0
	global_load_lds_dwordx4 v[220:221], off
	v_lshl_add_u64 v[220:221], s[84:85], 0, v[140:141]
	s_mov_b32 m0, s5
	s_nop 0
	global_load_lds_dwordx4 v[220:221], off
	s_mov_b32 m0, s26
	s_nop 0
	global_load_lds_dwordx4 v[222:223], off
	s_waitcnt vmcnt(8)
	s_waitcnt lgkmcnt(0)
	s_barrier
; #define PG8_STAGE(bufoff, gbase, voff) do { _Pragma("unroll") for (int _i = 0; _i < 2; ++_i) \
;         __builtin_amdgcn_global_load_lds((const unsigned*)((const char*)(gbase) + (voff)[_i]), (LAS unsigned*)(lds + (bufoff) + ldsw + _i * 8192), 16, 0, 0); } while (0)
; #define PG8_LDA(dst, b, h) do { _Pragma("unroll") for (int m = 0; m < 4; ++m) _Pragma("unroll") for (int k = 0; k < 2; ++k) dst[m][k] = *(const LAS bf16x8*)(lds + PG8_SA(b, h) + aoff + m * 2048 + k * 1024); } while (0)
; #define PG8_LDB(dst, b, h) do { _Pragma("unroll") for (int n = 0; n < 2; ++n) _Pragma("unroll") for (int k = 0; k < 2; ++k) dst[n][k] = *(const LAS bf16x8*)(lds + PG8_SB(b, h) + boff + n * 2048 + k * 1024); } while (0)
; #define PG8_MMA(ai, bj, At, Bt) do { __builtin_amdgcn_s_setprio(1); _Pragma("unroll") for (int m = 0; m < 4; ++m) _Pragma("unroll") for (int n = 0; n < 2; ++n) _Pragma("unroll") for (int k = 0; k < 2; ++k) \
;         acc[ai][bj][m][n] = __builtin_amdgcn_mfma_f32_16x16x32_bf16(Bt[n][k], At[m][k], acc[ai][bj][m][n], 0, 0, 0); __builtin_amdgcn_s_setprio(0); } while (0)
; #define PG8_WAIT_V(n) asm volatile("s_waitcnt vmcnt(" #n ")" ::: "memory")
; #define PG8_WAIT_L(n) asm volatile("s_waitcnt lgkmcnt(" #n ")" ::: "memory")
; #define PG8_BAR __builtin_amdgcn_s_barrier()
; #define PG8_SCHED __builtin_amdgcn_sched_barrier(0)
; template <class Epi, class Sched>
; __device__ __forceinline__ void gemm_phase(LAS unsigned char* lds, const Gemm g, const Sched& S, const Epi& E, const int tid) {
;     ...
;             PG8_WAIT_V(8); PG8_WAIT_L(0); PG8_BAR; PG8_MMA(0, 0, At, B0); PG8_MMA(0, 1, At, B1); PG8_BAR; PG8_SCHED;
;             PG8_LDA(At, 0, 1); PG8_STAGE(PG8_SB(0, 0), b2, voffB); PG8_STAGE(PG8_SB(0, 1), b2 + hstepB, voffB); PG8_STAGE(PG8_SA(0, 0), a2, voffA);
;             PG8_WAIT_V(8); PG8_WAIT_L(0); PG8_BAR; PG8_MMA(1, 0, At, B0); PG8_MMA(1, 1, At, B1); PG8_BAR; PG8_SCHED;
;             PG8_LDB(B0, 1, 0); PG8_LDB(B1, 1, 1); PG8_SCHED; PG8_LDA(At, 1, 0); PG8_STAGE(PG8_SA(0, 1), a2 + hstepA, voffA);
;             PG8_WAIT_V(8); PG8_WAIT_L(0); PG8_BAR; PG8_MMA(0, 0, At, B0); PG8_MMA(0, 1, At, B1); PG8_BAR; PG8_SCHED;
	v_mfma_f32_16x16x32_bf16 v[96:99], v[100:103], v[188:191], v[96:99]
	v_mfma_f32_16x16x32_bf16 v[92:95], v[150:153], v[188:191], v[92:95]
	v_mfma_f32_16x16x32_bf16 v[88:91], v[100:103], v[196:199], v[88:91]
	v_mfma_f32_16x16x32_bf16 v[84:87], v[150:153], v[196:199], v[84:87]
	v_mfma_f32_16x16x32_bf16 v[80:83], v[100:103], v[204:207], v[80:83]
	v_mfma_f32_16x16x32_bf16 v[76:79], v[150:153], v[204:207], v[76:79]
	v_mfma_f32_16x16x32_bf16 v[72:75], v[100:103], v[238:241], v[72:75]
	v_mfma_f32_16x16x32_bf16 v[68:71], v[150:153], v[238:241], v[68:71]
	v_mfma_f32_16x16x32_bf16 v[96:99], v[104:107], v[192:195], v[96:99]
	v_mfma_f32_16x16x32_bf16 v[92:95], v[154:157], v[192:195], v[92:95]
	v_mfma_f32_16x16x32_bf16 v[88:91], v[104:107], v[200:203], v[88:91]
	v_mfma_f32_16x16x32_bf16 v[84:87], v[154:157], v[200:203], v[84:87]
	v_mfma_f32_16x16x32_bf16 v[80:83], v[104:107], v[234:237], v[80:83]
	v_mfma_f32_16x16x32_bf16 v[76:79], v[154:157], v[234:237], v[76:79]
	v_mfma_f32_16x16x32_bf16 v[72:75], v[104:107], v[242:245], v[72:75]
	v_mfma_f32_16x16x32_bf16 v[68:71], v[154:157], v[242:245], v[68:71]
	v_mfma_f32_16x16x32_bf16 v[32:35], v[158:161], v[188:191], v[32:35]
	v_mfma_f32_16x16x32_bf16 v[28:31], v[180:183], v[188:191], v[28:31]
	v_mfma_f32_16x16x32_bf16 v[24:27], v[158:161], v[196:199], v[24:27]
	v_mfma_f32_16x16x32_bf16 v[20:23], v[180:183], v[196:199], v[20:23]
	v_mfma_f32_16x16x32_bf16 v[16:19], v[158:161], v[204:207], v[16:19]
	v_mfma_f32_16x16x32_bf16 v[12:15], v[180:183], v[204:207], v[12:15]
	v_mfma_f32_16x16x32_bf16 v[8:11], v[158:161], v[238:241], v[8:11]
	v_mfma_f32_16x16x32_bf16 v[4:7], v[180:183], v[238:241], v[4:7]
	v_mfma_f32_16x16x32_bf16 v[32:35], v[176:179], v[192:195], v[32:35]
	v_mfma_f32_16x16x32_bf16 v[28:31], v[184:187], v[192:195], v[28:31]
	v_mfma_f32_16x16x32_bf16 v[24:27], v[176:179], v[200:203], v[24:27]
	v_mfma_f32_16x16x32_bf16 v[20:23], v[184:187], v[200:203], v[20:23]
	v_mfma_f32_16x16x32_bf16 v[16:19], v[176:179], v[234:237], v[16:19]
	v_mfma_f32_16x16x32_bf16 v[12:15], v[184:187], v[234:237], v[12:15]
	v_mfma_f32_16x16x32_bf16 v[8:11], v[176:179], v[242:245], v[8:11]
	v_mfma_f32_16x16x32_bf16 v[4:7], v[184:187], v[242:245], v[4:7]
	s_barrier
	s_add_i32 s88, 0, 0x18000
	s_add_i32 s89, 0, 0x1c000
	v_add_u32_e32 v154, s88, v163
	v_add_u32_e32 v175, s89, v163
	ds_read_b128 v[100:103], v154
	ds_read_b128 v[104:107], v154 offset:1024
	ds_read_b128 v[150:153], v154 offset:2048
	ds_read_b128 v[154:157], v154 offset:3072
	ds_read_b128 v[158:161], v175
	ds_read_b128 v[176:179], v175 offset:1024
	ds_read_b128 v[180:183], v175 offset:2048
	ds_read_b128 v[184:187], v175 offset:3072
	s_add_u32 s84, s84, 0x80000
	s_addc_u32 s85, s85, 0
	s_mov_b32 m0, s56
	v_lshl_add_u64 v[246:247], s[84:85], 0, v[140:141]
	ds_read_b128 v[188:191], v174 offset:32768
	ds_read_b128 v[192:195], v174 offset:33792
	ds_read_b128 v[196:199], v174 offset:34816
	ds_read_b128 v[200:203], v174 offset:35840
	ds_read_b128 v[204:207], v174 offset:36864
	ds_read_b128 v[234:237], v174 offset:37888
	ds_read_b128 v[238:241], v174 offset:38912
	ds_read_b128 v[242:245], v174 offset:39936
	global_load_lds_dwordx4 v[246:247], off
	v_lshl_add_u64 v[246:247], s[84:85], 0, v[142:143]
	s_mov_b32 m0, s57
	s_nop 0
	global_load_lds_dwordx4 v[246:247], off
	s_waitcnt vmcnt(8)
	s_waitcnt lgkmcnt(0)
	s_barrier
	v_mfma_f32_16x16x32_bf16 v[136:139], v[100:103], v[188:191], v[136:139]
	v_mfma_f32_16x16x32_bf16 v[132:135], v[150:153], v[188:191], v[132:135]
	v_mfma_f32_16x16x32_bf16 v[128:131], v[100:103], v[196:199], v[128:131]
	v_mfma_f32_16x16x32_bf16 v[124:127], v[150:153], v[196:199], v[124:127]
	v_mfma_f32_16x16x32_bf16 v[120:123], v[100:103], v[204:207], v[120:123]
	v_mfma_f32_16x16x32_bf16 v[116:119], v[150:153], v[204:207], v[116:119]
	v_mfma_f32_16x16x32_bf16 v[112:115], v[100:103], v[238:241], v[112:115]
	v_mfma_f32_16x16x32_bf16 v[108:111], v[150:153], v[238:241], v[108:111]
	v_mfma_f32_16x16x32_bf16 v[136:139], v[104:107], v[192:195], v[136:139]
	v_mfma_f32_16x16x32_bf16 v[132:135], v[154:157], v[192:195], v[132:135]
	v_mfma_f32_16x16x32_bf16 v[128:131], v[104:107], v[200:203], v[128:131]
	v_mfma_f32_16x16x32_bf16 v[124:127], v[154:157], v[200:203], v[124:127]
	v_mfma_f32_16x16x32_bf16 v[120:123], v[104:107], v[234:237], v[120:123]
	v_mfma_f32_16x16x32_bf16 v[116:119], v[154:157], v[234:237], v[116:119]
	v_mfma_f32_16x16x32_bf16 v[112:115], v[104:107], v[242:245], v[112:115]
	v_mfma_f32_16x16x32_bf16 v[108:111], v[154:157], v[242:245], v[108:111]
	v_mfma_f32_16x16x32_bf16 v[64:67], v[158:161], v[188:191], v[64:67]
	v_mfma_f32_16x16x32_bf16 v[60:63], v[180:183], v[188:191], v[60:63]
	v_mfma_f32_16x16x32_bf16 v[56:59], v[158:161], v[196:199], v[56:59]
	v_mfma_f32_16x16x32_bf16 v[52:55], v[180:183], v[196:199], v[52:55]
	v_mfma_f32_16x16x32_bf16 v[48:51], v[158:161], v[204:207], v[48:51]
	v_mfma_f32_16x16x32_bf16 v[44:47], v[180:183], v[204:207], v[44:47]
	v_mfma_f32_16x16x32_bf16 v[40:43], v[158:161], v[238:241], v[40:43]
	v_mfma_f32_16x16x32_bf16 v[36:39], v[180:183], v[238:241], v[36:39]
	v_mfma_f32_16x16x32_bf16 v[64:67], v[176:179], v[192:195], v[64:67]
	v_mfma_f32_16x16x32_bf16 v[60:63], v[184:187], v[192:195], v[60:63]
	v_mfma_f32_16x16x32_bf16 v[56:59], v[176:179], v[200:203], v[56:59]
	v_mfma_f32_16x16x32_bf16 v[52:55], v[184:187], v[200:203], v[52:55]
	v_mfma_f32_16x16x32_bf16 v[48:51], v[176:179], v[234:237], v[48:51]
	v_mfma_f32_16x16x32_bf16 v[44:47], v[184:187], v[234:237], v[44:47]
	v_mfma_f32_16x16x32_bf16 v[40:43], v[176:179], v[242:245], v[40:43]
	v_mfma_f32_16x16x32_bf16 v[36:39], v[184:187], v[242:245], v[36:39]
	s_barrier
; #define PG8_STAGE(bufoff, gbase, voff) do { _Pragma("unroll") for (int _i = 0; _i < 2; ++_i) \
;         __builtin_amdgcn_global_load_lds((const unsigned*)((const char*)(gbase) + (voff)[_i]), (LAS unsigned*)(lds + (bufoff) + ldsw + _i * 8192), 16, 0, 0); } while (0)
; #define PG8_LDA(dst, b, h) do { _Pragma("unroll") for (int m = 0; m < 4; ++m) _Pragma("unroll") for (int k = 0; k < 2; ++k) dst[m][k] = *(const LAS bf16x8*)(lds + PG8_SA(b, h) + aoff + m * 2048 + k * 1024); } while (0)
; #define PG8_MMA(ai, bj, At, Bt) do { __builtin_amdgcn_s_setprio(1); _Pragma("unroll") for (int m = 0; m < 4; ++m) _Pragma("unroll") for (int n = 0; n < 2; ++n) _Pragma("unroll") for (int k = 0; k < 2; ++k) \
;         acc[ai][bj][m][n] = __builtin_amdgcn_mfma_f32_16x16x32_bf16(Bt[n][k], At[m][k], acc[ai][bj][m][n], 0, 0, 0); __builtin_amdgcn_s_setprio(0); } while (0)
; #define PG8_WAIT_V(n) asm volatile("s_waitcnt vmcnt(" #n ")" ::: "memory")
; #define PG8_WAIT_L(n) asm volatile("s_waitcnt lgkmcnt(" #n ")" ::: "memory")
; #define PG8_BAR __builtin_amdgcn_s_barrier()
; #define PG8_SCHED __builtin_amdgcn_sched_barrier(0)
; template <class Epi, class Sched>
; __device__ __forceinline__ void gemm_phase(LAS unsigned char* lds, const Gemm g, const Sched& S, const Epi& E, const int tid) {
;     ...
;             PG8_LDA(At, 1, 1); PG8_STAGE(PG8_SB(1, 0), b3, voffB); PG8_STAGE(PG8_SB(1, 1), b3 + hstepB, voffB); PG8_STAGE(PG8_SA(1, 0), a3, voffA);
;             PG8_WAIT_V(8); PG8_WAIT_L(0); PG8_BAR; PG8_MMA(1, 0, At, B0); PG8_MMA(1, 1, At, B1); PG8_BAR; PG8_SCHED;
;         }
;         if (wr == 0) PG8_BAR;
	s_add_i32 s84, s88, s1
	v_lshl_add_u64 v[210:211], v[210:211], 0, s[28:29]
	s_mov_b32 m0, s84
	ds_read_b128 v[188:191], v174 offset:49152
	ds_read_b128 v[192:195], v174 offset:50176
	ds_read_b128 v[196:199], v174 offset:51200
	ds_read_b128 v[200:203], v174 offset:52224
	ds_read_b128 v[204:207], v174 offset:53248
	ds_read_b128 v[234:237], v174 offset:54272
	ds_read_b128 v[238:241], v174 offset:55296
	ds_read_b128 v[242:245], v174 offset:56320
	global_load_lds_dwordx4 v[210:211], off
	s_add_i32 m0, s84, 0x2000
	s_add_u32 s54, s54, 0x80080
	v_lshl_add_u64 v[210:211], v[212:213], 0, s[28:29]
	s_addc_u32 s55, s55, 0
	s_add_i32 s84, s89, s1
	global_load_lds_dwordx4 v[210:211], off
	v_lshl_add_u64 v[210:211], s[54:55], 0, v[164:165]
	s_mov_b32 m0, s84
	s_nop 0
	global_load_lds_dwordx4 v[210:211], off
	v_lshl_add_u64 v[210:211], s[54:55], 0, v[144:145]
	s_add_i32 m0, s84, 0x2000
	s_nop 0
	global_load_lds_dwordx4 v[210:211], off
	v_lshl_add_u64 v[210:211], v[220:221], 0, s[28:29]
	s_mov_b32 m0, s58
	s_nop 0
	global_load_lds_dwordx4 v[210:211], off
	v_lshl_add_u64 v[210:211], v[222:223], 0, s[28:29]
	s_mov_b32 m0, s59
	s_nop 0
	global_load_lds_dwordx4 v[210:211], off
	s_waitcnt vmcnt(8)
	s_waitcnt lgkmcnt(0)
	s_barrier
	v_mfma_f32_16x16x32_bf16 v[96:99], v[100:103], v[188:191], v[96:99]
	v_mfma_f32_16x16x32_bf16 v[92:95], v[150:153], v[188:191], v[92:95]
	v_mfma_f32_16x16x32_bf16 v[88:91], v[100:103], v[196:199], v[88:91]
	v_mfma_f32_16x16x32_bf16 v[84:87], v[150:153], v[196:199], v[84:87]
	v_mfma_f32_16x16x32_bf16 v[80:83], v[100:103], v[204:207], v[80:83]
	v_mfma_f32_16x16x32_bf16 v[76:79], v[150:153], v[204:207], v[76:79]
	v_mfma_f32_16x16x32_bf16 v[72:75], v[100:103], v[238:241], v[72:75]
	v_mfma_f32_16x16x32_bf16 v[68:71], v[150:153], v[238:241], v[68:71]
	v_mfma_f32_16x16x32_bf16 v[96:99], v[104:107], v[192:195], v[96:99]
	v_mfma_f32_16x16x32_bf16 v[92:95], v[154:157], v[192:195], v[92:95]
	v_mfma_f32_16x16x32_bf16 v[88:91], v[104:107], v[200:203], v[88:91]
	v_mfma_f32_16x16x32_bf16 v[84:87], v[154:157], v[200:203], v[84:87]
	v_mfma_f32_16x16x32_bf16 v[80:83], v[104:107], v[234:237], v[80:83]
	v_mfma_f32_16x16x32_bf16 v[76:79], v[154:157], v[234:237], v[76:79]
	v_mfma_f32_16x16x32_bf16 v[72:75], v[104:107], v[242:245], v[72:75]
	v_mfma_f32_16x16x32_bf16 v[68:71], v[154:157], v[242:245], v[68:71]
	v_mfma_f32_16x16x32_bf16 v[32:35], v[158:161], v[188:191], v[32:35]
	v_mfma_f32_16x16x32_bf16 v[28:31], v[180:183], v[188:191], v[28:31]
	v_mfma_f32_16x16x32_bf16 v[24:27], v[158:161], v[196:199], v[24:27]
	v_mfma_f32_16x16x32_bf16 v[20:23], v[180:183], v[196:199], v[20:23]
	v_mfma_f32_16x16x32_bf16 v[16:19], v[158:161], v[204:207], v[16:19]
	v_mfma_f32_16x16x32_bf16 v[12:15], v[180:183], v[204:207], v[12:15]
	v_mfma_f32_16x16x32_bf16 v[8:11], v[158:161], v[238:241], v[8:11]
	v_mfma_f32_16x16x32_bf16 v[4:7], v[180:183], v[238:241], v[4:7]
	v_mfma_f32_16x16x32_bf16 v[32:35], v[176:179], v[192:195], v[32:35]
	v_mfma_f32_16x16x32_bf16 v[28:31], v[184:187], v[192:195], v[28:31]
	v_mfma_f32_16x16x32_bf16 v[24:27], v[176:179], v[200:203], v[24:27]
	v_mfma_f32_16x16x32_bf16 v[20:23], v[184:187], v[200:203], v[20:23]
	v_mfma_f32_16x16x32_bf16 v[16:19], v[176:179], v[234:237], v[16:19]
	v_mfma_f32_16x16x32_bf16 v[12:15], v[184:187], v[234:237], v[12:15]
	v_mfma_f32_16x16x32_bf16 v[8:11], v[176:179], v[242:245], v[8:11]
	v_mfma_f32_16x16x32_bf16 v[4:7], v[184:187], v[242:245], v[4:7]
	s_barrier
	s_add_i32 s87, s87, 2
	s_add_u32 s46, s46, 0x100
	s_addc_u32 s47, s47, 0
	s_add_u32 s39, s39, 0x100
	s_addc_u32 s86, s86, 0
	s_cmp_gt_u32 s87, 29
	s_cbranch_scc0 .LBB0_589
	s_and_b64 vcc, exec, s[16:17]
	s_cbranch_vccz .LBB0_592
	s_barrier
